# v48_a3_qk16_state_gate_hoists_logtrim
# speedup vs baseline: 1.0402x; 1.0017x over previous
;     ...
; #pragma unroll
;         for (int e = 0; e < 4; ++e) { float s2 = 0.f;
; #pragma unroll
;             for (int nt = 0; nt < 16; ++nt) s2 += acc[nt][e] * acc[nt][e];
;             s2 += __shfl_xor(s2, 1); s2 += __shfl_xor(s2, 2); s2 += __shfl_xor(s2, 4); s2 += __shfl_xor(s2, 8);
;             rs[e] = 1.0f / sqrtf(s2 * (1.0f / 256.0f) + EPS); }
;     ...
;           bf16_t* orow = proj + (size_t)(t0 + i0 + r) * NMAIN + C_GR + h * 256;
;           bf16_t* drow = dry ? proj + (size_t)NT * NMAIN + (size_t)((t0 + i0 + r) & 63) * NMAIN + C_GR + h * 256 : orow;
;           u32x4 gv[8];
; #pragma unroll
;           for (int q = 0; q < 8; ++q) gv[q] = *(const u32x4*)(orow + 8 * (cgp + 4 * q));
.LBB0_477:
	v_add_u32_e32 v80, s44, v197
	v_mov_b64_e32 v[82:83], s[22:23]
	v_mad_i64_i32 v[82:83], s[98:99], v80, s48, v[82:83]
	v_lshl_add_u64 v[82:83], s[36:37], 1, v[82:83]
	v_mov_b32_e32 v80, v110
	v_mov_b32_e32 v81, 0
	v_lshl_add_u64 v[82:83], v[82:83], 0, v[80:81]
	s_mov_b32 s100, s25
	s_mov_b32 s101, 0
	v_lshl_add_u64 v[80:81], v[82:83], 0, s[100:101]
	v_lshl_add_u64 v[82:83], v[82:83], 0, s[14:15]
	global_load_dwordx4 v[210:213], v[80:81], off
	global_load_dwordx4 v[214:217], v[82:83], off offset:64
	global_load_dwordx4 v[218:221], v[82:83], off offset:128
	global_load_dwordx4 v[222:225], v[82:83], off offset:192
	global_load_dwordx4 v[226:229], v[82:83], off offset:256
	global_load_dwordx4 v[230:233], v[82:83], off offset:320
	global_load_dwordx4 v[234:237], v[82:83], off offset:384
	global_load_dwordx4 v[238:241], v[82:83], off offset:448
	v_xor_b32_e32 v0, 1, v187
	v_cmp_lt_i32_e32 vcc, v0, v190
	s_waitcnt lgkmcnt(0)
	v_xor_b32_e32 v68, 2, v187
	v_xor_b32_e32 v69, 4, v187
	v_cndmask_b32_e32 v0, v187, v0, vcc
	v_lshlrev_b32_e32 v2, 2, v0
	v_mul_f32_e32 v0, v64, v64
	v_fmac_f32_e32 v0, v60, v60
	v_fmac_f32_e32 v0, v52, v52
	v_fmac_f32_e32 v0, v48, v48
	v_fmac_f32_e32 v0, v44, v44
	v_fmac_f32_e32 v0, v40, v40
	v_fmac_f32_e32 v0, v36, v36
	v_fmac_f32_e32 v0, v24, v24
	v_fmac_f32_e32 v0, v20, v20
	v_fmac_f32_e32 v0, v16, v16
	v_fmac_f32_e32 v0, v12, v12
	v_fmac_f32_e32 v0, v8, v8
	v_fmac_f32_e32 v0, v4, v4
	v_fmac_f32_e32 v0, v32, v32
	v_fmac_f32_e32 v0, v28, v28
	v_fmac_f32_e32 v0, v56, v56
	ds_bpermute_b32 v3, v2, v0
	v_cmp_lt_i32_e32 vcc, v68, v190
	v_xor_b32_e32 v70, 8, v187
	v_mul_f32_e32 v77, v66, v66
	v_cndmask_b32_e32 v68, v187, v68, vcc
	v_lshlrev_b32_e32 v68, 2, v68
	s_waitcnt lgkmcnt(0)
	v_add_f32_e32 v0, v0, v3
	ds_bpermute_b32 v3, v68, v0
	v_cmp_lt_i32_e32 vcc, v69, v190
	v_fmac_f32_e32 v77, v62, v62
	v_fmac_f32_e32 v77, v54, v54
	v_cndmask_b32_e32 v69, v187, v69, vcc
	v_lshlrev_b32_e32 v69, 2, v69
	s_waitcnt lgkmcnt(0)
	v_add_f32_e32 v0, v0, v3
	ds_bpermute_b32 v3, v69, v0
	v_cmp_lt_i32_e32 vcc, v70, v190
	v_fmac_f32_e32 v77, v50, v50
	v_fmac_f32_e32 v77, v46, v46
	v_cndmask_b32_e32 v70, v187, v70, vcc
	v_lshlrev_b32_e32 v70, 2, v70
	s_waitcnt lgkmcnt(0)
	v_add_f32_e32 v0, v0, v3
	ds_bpermute_b32 v3, v70, v0
	v_fmac_f32_e32 v77, v42, v42
	v_fmac_f32_e32 v77, v38, v38
	v_fmac_f32_e32 v77, v26, v26
	v_fmac_f32_e32 v77, v22, v22
	s_waitcnt lgkmcnt(0)
	v_add_f32_e32 v0, v0, v3
	v_fmamk_f32 v0, v0, 0x3b800000, v206
	v_mul_f32_e32 v3, 0x4f800000, v0
	v_cmp_gt_f32_e32 vcc, s49, v0
	v_fmac_f32_e32 v77, v18, v18
	v_fmac_f32_e32 v77, v14, v14
	v_cndmask_b32_e32 v0, v0, v3, vcc
	v_sqrt_f32_e32 v3, v0
	v_fmac_f32_e32 v77, v10, v10
	v_fmac_f32_e32 v77, v6, v6
	v_fmac_f32_e32 v77, v34, v34
	v_add_u32_e32 v71, -1, v3
	v_fma_f32 v73, -v71, v3, v0
	v_cmp_ge_f32_e64 s[6:7], 0, v73
	v_mul_f32_e32 v73, v65, v65
	v_fmac_f32_e32 v73, v61, v61
	v_fmac_f32_e32 v73, v53, v53
	v_fmac_f32_e32 v73, v49, v49
	v_fmac_f32_e32 v73, v45, v45
	v_fmac_f32_e32 v73, v41, v41
	v_fmac_f32_e32 v73, v37, v37
	v_fmac_f32_e32 v73, v25, v25
	v_fmac_f32_e32 v73, v21, v21
	v_fmac_f32_e32 v73, v17, v17
	v_fmac_f32_e32 v73, v13, v13
	v_fmac_f32_e32 v73, v9, v9
	v_fmac_f32_e32 v73, v5, v5
	v_fmac_f32_e32 v73, v33, v33
	v_fmac_f32_e32 v73, v29, v29
	v_fmac_f32_e32 v73, v57, v57
	v_add_u32_e32 v72, 1, v3
	ds_bpermute_b32 v74, v2, v73
	v_cndmask_b32_e64 v71, v3, v71, s[6:7]
	v_fma_f32 v3, -v72, v3, v0
	v_cmp_lt_f32_e64 s[6:7], 0, v3
	v_fmac_f32_e32 v77, v30, v30
	v_fmac_f32_e32 v77, v58, v58
	v_cndmask_b32_e64 v3, v71, v72, s[6:7]
	v_mul_f32_e32 v71, 0x37800000, v3
	v_cndmask_b32_e32 v3, v3, v71, vcc
	s_waitcnt lgkmcnt(0)
	v_add_f32_e32 v71, v73, v74
	ds_bpermute_b32 v72, v68, v71
	v_cmp_class_f32_e32 vcc, v0, v207
	ds_bpermute_b32 v78, v2, v77
	s_waitcnt lgkmcnt(0)
	v_cndmask_b32_e32 v0, v3, v0, vcc
	v_add_f32_e32 v71, v71, v72
	ds_bpermute_b32 v72, v69, v71
	v_div_scale_f32 v3, s[0:1], v0, v0, 1.0
	v_rcp_f32_e32 v73, v3
	s_barrier
	s_waitcnt lgkmcnt(0)
	v_add_f32_e32 v71, v71, v72
	ds_bpermute_b32 v72, v70, v71
	v_fma_f32 v74, -v3, v73, 1.0
	v_fmac_f32_e32 v73, v74, v73
	v_div_scale_f32 v74, vcc, 1.0, v0, 1.0
	s_waitcnt lgkmcnt(0)
	v_add_f32_e32 v71, v71, v72
	v_fmamk_f32 v71, v71, 0x3b800000, v206
	v_mul_f32_e32 v72, 0x4f800000, v71
	v_cmp_gt_f32_e64 s[6:7], s49, v71
	v_mul_f32_e32 v75, v74, v73
	v_fma_f32 v76, -v3, v75, v74
	v_cndmask_b32_e64 v71, v71, v72, s[6:7]
	v_sqrt_f32_e32 v72, v71
	v_fmac_f32_e32 v75, v76, v73
	v_fma_f32 v3, -v3, v75, v74
	v_div_fmas_f32 v3, v3, v73, v75
	v_add_u32_e32 v74, -1, v72
	v_fma_f32 v76, -v74, v72, v71
	v_cmp_ge_f32_e64 s[8:9], 0, v76
	v_add_u32_e32 v76, 1, v72
	v_div_fixup_f32 v0, v3, v0, 1.0
	v_cndmask_b32_e64 v74, v72, v74, s[8:9]
	v_fma_f32 v72, -v76, v72, v71
	v_cmp_lt_f32_e64 s[8:9], 0, v72
	v_mul_f32_e32 v44, v44, v0
	s_nop 0
	v_cndmask_b32_e64 v72, v74, v76, s[8:9]
	v_mul_f32_e32 v74, 0x37800000, v72
	v_cndmask_b32_e64 v72, v72, v74, s[6:7]
	v_add_f32_e32 v74, v77, v78
	ds_bpermute_b32 v76, v68, v74
	v_mul_f32_e32 v78, v67, v67
	v_fmac_f32_e32 v78, v63, v63
	v_fmac_f32_e32 v78, v55, v55
	v_fmac_f32_e32 v78, v51, v51
	s_waitcnt lgkmcnt(0)
	v_add_f32_e32 v74, v74, v76
	ds_bpermute_b32 v76, v69, v74
	v_fmac_f32_e32 v78, v47, v47
	v_fmac_f32_e32 v78, v43, v43
	v_cmp_class_f32_e64 s[6:7], v71, v207
	v_fmac_f32_e32 v78, v39, v39
	s_waitcnt lgkmcnt(0)
	v_add_f32_e32 v73, v74, v76
	ds_bpermute_b32 v74, v70, v73
	v_cndmask_b32_e64 v71, v72, v71, s[6:7]
	v_fmac_f32_e32 v78, v27, v27
	v_div_scale_f32 v72, s[0:1], v71, v71, 1.0
	v_fmac_f32_e32 v78, v23, v23
	v_rcp_f32_e32 v77, v72
	v_fmac_f32_e32 v78, v19, v19
	s_waitcnt lgkmcnt(0)
; #define LAS __attribute__((address_space(3)))
; __device__ __forceinline__ unsigned f2bf(float f) { return (unsigned)__builtin_bit_cast(unsigned short, (__bf16)f); }
; #define X make_ctx(lds_raw)
;     ...
;         for (int e = 0; e < 4; ++e) { float s2 = 0.f;
; #pragma unroll
;             for (int nt = 0; nt < 16; ++nt) s2 += acc[nt][e] * acc[nt][e];
;             s2 += __shfl_xor(s2, 1); s2 += __shfl_xor(s2, 2); s2 += __shfl_xor(s2, 4); s2 += __shfl_xor(s2, 8);
;             rs[e] = 1.0f / sqrtf(s2 * (1.0f / 256.0f) + EPS); }
;         __syncthreads();
;         { LAS bf16_t* ost = (LAS bf16_t*)(X.lds + w * 8704);
; #pragma unroll
;           for (int nt = 0; nt < 16; ++nt) { const float nw = a->gla_norm_w[16 * nt + fr];
; #pragma unroll
;               for (int e = 0; e < 4; ++e) ost[(4 * fq + e) * 272 + 16 * nt + fr] = (bf16_t)f2bf(acc[nt][e] * rs[e] * nw); }
	v_add_f32_e32 v73, v73, v74
	v_fmac_f32_e32 v78, v15, v15
	v_fmamk_f32 v73, v73, 0x3b800000, v206
	v_fmac_f32_e32 v78, v11, v11
	v_mul_f32_e32 v74, 0x4f800000, v73
	v_cmp_gt_f32_e64 s[6:7], s49, v73
	v_fmac_f32_e32 v78, v7, v7
	v_fma_f32 v3, -v72, v77, 1.0
	v_cndmask_b32_e64 v73, v73, v74, s[6:7]
	v_fmac_f32_e32 v78, v35, v35
	v_fmac_f32_e32 v77, v3, v77
	v_div_scale_f32 v3, vcc, 1.0, v71, 1.0
	v_sqrt_f32_e32 v74, v73
	v_fmac_f32_e32 v78, v31, v31
	v_mul_f32_e32 v75, v3, v77
	v_fmac_f32_e32 v78, v59, v59
	v_fma_f32 v76, -v72, v75, v3
	ds_bpermute_b32 v2, v2, v78
	v_fmac_f32_e32 v75, v76, v77
	v_fma_f32 v3, -v72, v75, v3
	v_add_u32_e32 v72, -1, v74
	v_fma_f32 v76, -v72, v74, v73
	v_cmp_ge_f32_e64 s[8:9], 0, v76
	v_add_u32_e32 v76, 1, v74
	s_waitcnt lgkmcnt(0)
	v_add_f32_e32 v2, v78, v2
	v_cndmask_b32_e64 v72, v74, v72, s[8:9]
	v_fma_f32 v74, -v76, v74, v73
	v_cmp_lt_f32_e64 s[8:9], 0, v74
	ds_bpermute_b32 v68, v68, v2
	s_load_dwordx2 s[0:1], s[10:11], 0x48
	v_cndmask_b32_e64 v72, v72, v76, s[8:9]
	v_mul_f32_e32 v74, 0x37800000, v72
	v_cndmask_b32_e64 v72, v72, v74, s[6:7]
	v_cmp_class_f32_e64 s[6:7], v73, v207
	s_waitcnt lgkmcnt(0)
	v_add_f32_e32 v68, v2, v68
	ds_bpermute_b32 v69, v69, v68
	v_cndmask_b32_e64 v72, v72, v73, s[6:7]
	v_div_scale_f32 v73, s[6:7], v72, v72, 1.0
	v_rcp_f32_e32 v76, v73
	v_div_fmas_f32 v2, v3, v77, v75
	v_div_fixup_f32 v2, v2, v71, 1.0
	global_load_dword v79, v208, s[0:1]
	global_load_dword v74, v208, s[0:1] offset:64
	global_load_dword v77, v208, s[0:1] offset:192
	v_fma_f32 v3, -v73, v76, 1.0
	v_fmac_f32_e32 v76, v3, v76
	s_waitcnt lgkmcnt(0)
	v_add_f32_e32 v3, v68, v69
	ds_bpermute_b32 v68, v70, v3
	v_div_scale_f32 v70, vcc, 1.0, v72, 1.0
	v_mul_f32_e32 v71, v70, v76
	v_fma_f32 v75, -v73, v71, v70
	s_waitcnt lgkmcnt(0)
	v_add_f32_e32 v3, v3, v68
	v_fmamk_f32 v3, v3, 0x3b800000, v206
	v_mul_f32_e32 v68, 0x4f800000, v3
	v_cmp_gt_f32_e64 s[6:7], s49, v3
	v_fmac_f32_e32 v71, v75, v76
	v_fma_f32 v70, -v73, v71, v70
	v_cndmask_b32_e64 v3, v3, v68, s[6:7]
	v_sqrt_f32_e32 v68, v3
	v_div_fmas_f32 v70, v70, v76, v71
	global_load_dword v69, v208, s[0:1] offset:128
	v_div_fixup_f32 v70, v70, v72, 1.0
	v_add_u32_e32 v73, -1, v68
	v_fma_f32 v75, -v73, v68, v3
	v_cmp_ge_f32_e64 s[8:9], 0, v75
	v_add_u32_e32 v75, 1, v68
	global_load_dword v72, v208, s[0:1] offset:256
	v_cndmask_b32_e64 v73, v68, v73, s[8:9]
	v_fma_f32 v68, -v75, v68, v3
	v_cmp_lt_f32_e64 s[8:9], 0, v68
	v_mul_f32_e32 v48, v48, v0
	v_mul_f32_e32 v40, v40, v0
	v_cndmask_b32_e64 v68, v73, v75, s[8:9]
	v_mul_f32_e32 v73, 0x37800000, v68
	v_cndmask_b32_e64 v68, v68, v73, s[6:7]
	v_cmp_class_f32_e64 s[6:7], v3, v207
	v_mul_f32_e32 v36, v36, v0
	v_mul_f32_e32 v24, v24, v0
	v_cndmask_b32_e64 v3, v68, v3, s[6:7]
	v_div_scale_f32 v68, s[6:7], v3, v3, 1.0
	v_rcp_f32_e32 v73, v68
	v_mul_f32_e32 v64, v64, v0
	v_mul_f32_e32 v60, v60, v0
	v_mul_f32_e32 v52, v52, v0
	v_fma_f32 v71, -v68, v73, 1.0
	v_fmac_f32_e32 v73, v71, v73
	v_div_scale_f32 v71, vcc, 1.0, v3, 1.0
	v_mul_f32_e32 v75, v71, v73
	v_fma_f32 v76, -v68, v75, v71
	v_fmac_f32_e32 v75, v76, v73
	v_fma_f32 v68, -v68, v75, v71
	v_div_fmas_f32 v68, v68, v73, v75
	v_div_fixup_f32 v3, v68, v3, 1.0
	global_load_dword v68, v208, s[0:1] offset:320
	global_load_dword v71, v208, s[0:1] offset:384
	global_load_dword v73, v208, s[0:1] offset:448
	v_mul_f32_e32 v4, v4, v0
	v_mul_f32_e32 v20, v20, v0
	v_mul_f32_e32 v16, v16, v0
	v_mul_f32_e32 v12, v12, v0
	v_mul_f32_e32 v8, v8, v0
	s_lshl_b32 s36, s36, 1
	v_mov_b32_e32 v111, v1
	s_add_i32 s42, s42, s84
	s_cmpk_lt_i32 s42, 0x200
	s_waitcnt vmcnt(7)
	v_mul_f32_e32 v64, v64, v79
	s_waitcnt vmcnt(6)
	v_mul_f32_e32 v60, v60, v74
	s_waitcnt vmcnt(5)
	v_mul_f32_e32 v48, v48, v77
	v_cvt_pk_bf16_f32 v48, v48, s0
	ds_write_b16 v196, v48 offset:96
	v_mul_f32_e32 v48, v49, v2
	global_load_dword v49, v208, s[0:1] offset:512
	v_cvt_pk_bf16_f32 v64, v64, s0
	v_cvt_pk_bf16_f32 v60, v60, s0
	ds_write_b16 v196, v64
	v_mul_f32_e32 v64, v65, v2
	ds_write_b16 v196, v60 offset:32
	v_mul_f32_e32 v60, v61, v2
	v_mul_f32_e32 v64, v64, v79
	v_mul_f32_e32 v60, v60, v74
	v_mul_f32_e32 v48, v48, v77
	v_cvt_pk_bf16_f32 v64, v64, s0
	v_cvt_pk_bf16_f32 v60, v60, s0
	v_cvt_pk_bf16_f32 v48, v48, s0
	ds_write_b16 v196, v64 offset:544
	s_waitcnt vmcnt(5)
	v_mul_f32_e32 v52, v52, v69
	v_cvt_pk_bf16_f32 v52, v52, s0
	ds_write_b16 v196, v52 offset:64
	v_mul_f32_e32 v52, v53, v2
	v_mul_f32_e32 v52, v52, v69
	v_cvt_pk_bf16_f32 v52, v52, s0
	s_waitcnt vmcnt(4)
	v_mul_f32_e32 v44, v44, v72
	v_cvt_pk_bf16_f32 v44, v44, s0
	ds_write_b16 v196, v44 offset:128
	v_mul_f32_e32 v44, v45, v2
	v_mul_f32_e32 v44, v44, v72
	v_cvt_pk_bf16_f32 v44, v44, s0
	ds_write_b16 v196, v44 offset:672
	global_load_dword v44, v208, s[0:1] offset:576
	v_mul_f32_e32 v64, v66, v70
	ds_write_b16 v196, v60 offset:576
	v_mul_f32_e32 v60, v62, v70
	ds_write_b16 v196, v52 offset:608
	v_mul_f32_e32 v52, v54, v70
	ds_write_b16 v196, v48 offset:640
	v_mul_f32_e32 v48, v50, v70
	v_mul_f32_e32 v45, v46, v70
	v_mul_f32_e32 v64, v64, v79
	v_mul_f32_e32 v60, v60, v74
	v_mul_f32_e32 v52, v52, v69
	v_mul_f32_e32 v48, v48, v77
	v_mul_f32_e32 v45, v45, v72
	v_cvt_pk_bf16_f32 v64, v64, s0
	v_cvt_pk_bf16_f32 v60, v60, s0
	v_cvt_pk_bf16_f32 v52, v52, s0
	v_cvt_pk_bf16_f32 v48, v48, s0
	v_cvt_pk_bf16_f32 v45, v45, s0
	ds_write_b16 v196, v64 offset:1088
	s_waitcnt vmcnt(4)
	v_mul_f32_e32 v40, v40, v68
	s_waitcnt vmcnt(3)
	v_mul_f32_e32 v36, v36, v71
	s_waitcnt vmcnt(2)
; #define LAS __attribute__((address_space(3)))
; __device__ __forceinline__ unsigned f2bf(float f) { return (unsigned)__builtin_bit_cast(unsigned short, (__bf16)f); }
; #define X make_ctx(lds_raw)
;     ...
;         { LAS bf16_t* ost = (LAS bf16_t*)(X.lds + w * 8704);
; #pragma unroll
;           for (int nt = 0; nt < 16; ++nt) { const float nw = a->gla_norm_w[16 * nt + fr];
; #pragma unroll
;               for (int e = 0; e < 4; ++e) ost[(4 * fq + e) * 272 + 16 * nt + fr] = (bf16_t)f2bf(acc[nt][e] * rs[e] * nw); }
	v_mul_f32_e32 v24, v24, v73
	v_cvt_pk_bf16_f32 v40, v40, s0
	v_cvt_pk_bf16_f32 v36, v36, s0
	v_cvt_pk_bf16_f32 v24, v24, s0
	ds_write_b16 v196, v40 offset:160
	v_mul_f32_e32 v40, v41, v2
	global_load_dword v41, v208, s[0:1] offset:640
	ds_write_b16 v196, v36 offset:192
	v_mul_f32_e32 v36, v37, v2
	global_load_dword v37, v208, s[0:1] offset:704
	ds_write_b16 v196, v24 offset:224
	v_mul_f32_e32 v24, v25, v2
	global_load_dword v25, v208, s[0:1] offset:768
	v_mul_f32_e32 v40, v40, v68
	v_mul_f32_e32 v36, v36, v71
	v_mul_f32_e32 v24, v24, v73
	v_cvt_pk_bf16_f32 v40, v40, s0
	v_cvt_pk_bf16_f32 v36, v36, s0
	v_cvt_pk_bf16_f32 v24, v24, s0
	ds_write_b16 v196, v40 offset:704
	v_mul_f32_e32 v40, v42, v70
	ds_write_b16 v196, v36 offset:736
	v_mul_f32_e32 v36, v38, v70
	ds_write_b16 v196, v24 offset:768
	v_mul_f32_e32 v24, v26, v70
	v_mul_f32_e32 v40, v40, v68
	v_mul_f32_e32 v36, v36, v71
	v_mul_f32_e32 v24, v24, v73
	v_cvt_pk_bf16_f32 v40, v40, s0
	v_cvt_pk_bf16_f32 v36, v36, s0
	v_cvt_pk_bf16_f32 v24, v24, s0
	v_mul_f32_e32 v64, v67, v3
	ds_write_b16 v196, v60 offset:1120
	v_mul_f32_e32 v60, v63, v3
	ds_write_b16 v196, v52 offset:1152
	v_mul_f32_e32 v52, v55, v3
	ds_write_b16 v196, v48 offset:1184
	v_mul_f32_e32 v48, v51, v3
	ds_write_b16 v196, v45 offset:1216
	v_mul_f32_e32 v45, v47, v3
	ds_write_b16 v196, v40 offset:1248
	v_mul_f32_e32 v40, v43, v3
	ds_write_b16 v196, v36 offset:1280
	v_mul_f32_e32 v36, v39, v3
	ds_write_b16 v196, v24 offset:1312
	v_mul_f32_e32 v24, v27, v3
	v_mul_f32_e32 v64, v79, v64
	v_mul_f32_e32 v60, v60, v74
	v_mul_f32_e32 v52, v52, v69
	v_mul_f32_e32 v48, v48, v77
	v_mul_f32_e32 v45, v45, v72
	v_mul_f32_e32 v40, v40, v68
	v_mul_f32_e32 v36, v36, v71
	v_mul_f32_e32 v24, v24, v73
	v_cvt_pk_bf16_f32 v64, v64, s0
	v_cvt_pk_bf16_f32 v60, v60, s0
	v_cvt_pk_bf16_f32 v52, v52, s0
	v_cvt_pk_bf16_f32 v48, v48, s0
	v_cvt_pk_bf16_f32 v45, v45, s0
	v_cvt_pk_bf16_f32 v40, v40, s0
	v_cvt_pk_bf16_f32 v36, v36, s0
	v_cvt_pk_bf16_f32 v24, v24, s0
	ds_write_b16 v196, v64 offset:1632
	ds_write_b16 v196, v60 offset:1664
	ds_write_b16 v196, v52 offset:1696
	ds_write_b16 v196, v48 offset:1728
	ds_write_b16 v196, v45 offset:1760
	ds_write_b16 v196, v40 offset:1792
	ds_write_b16 v196, v36 offset:1824
	ds_write_b16 v196, v24 offset:1856
	global_load_dword v24, v208, s[0:1] offset:832
	global_load_dword v26, v208, s[0:1] offset:896
	global_load_dword v27, v208, s[0:1] offset:960
	s_waitcnt vmcnt(7)
	v_mul_f32_e32 v20, v20, v49
	s_waitcnt vmcnt(6)
	v_mul_f32_e32 v16, v16, v44
	v_cvt_pk_bf16_f32 v20, v20, s0
	v_cvt_pk_bf16_f32 v16, v16, s0
	ds_write_b16 v196, v20 offset:256
	v_mul_f32_e32 v20, v21, v2
	ds_write_b16 v196, v16 offset:288
	v_mul_f32_e32 v16, v17, v2
	v_mul_f32_e32 v20, v20, v49
	v_mul_f32_e32 v16, v16, v44
	v_cvt_pk_bf16_f32 v20, v20, s0
	v_cvt_pk_bf16_f32 v16, v16, s0
	ds_write_b16 v196, v20 offset:800
	v_mul_f32_e32 v20, v22, v70
	ds_write_b16 v196, v16 offset:832
	s_waitcnt vmcnt(5)
	v_mul_f32_e32 v12, v12, v41
	v_cvt_pk_bf16_f32 v12, v12, s0
	ds_write_b16 v196, v12 offset:320
	s_waitcnt vmcnt(4)
	v_mul_f32_e32 v8, v8, v37
	v_cvt_pk_bf16_f32 v8, v8, s0
	v_mul_f32_e32 v12, v13, v2
	s_waitcnt vmcnt(3)
	v_mul_f32_e32 v4, v4, v25
	v_cvt_pk_bf16_f32 v4, v4, s0
	ds_write_b16 v196, v4 offset:384
	v_mul_f32_e32 v4, v5, v2
	v_mul_f32_e32 v4, v4, v25
	v_cvt_pk_bf16_f32 v4, v4, s0
	ds_write_b16 v196, v4 offset:928
	v_mul_f32_e32 v4, v6, v70
	v_mul_f32_e32 v4, v4, v25
	v_cvt_pk_bf16_f32 v4, v4, s0
	ds_write_b16 v196, v4 offset:1472
	v_mul_f32_e32 v4, v7, v3
	v_mul_f32_e32 v4, v4, v25
	v_cvt_pk_bf16_f32 v4, v4, s0
	ds_write_b16 v196, v4 offset:2016
	v_mul_f32_e32 v4, v32, v0
	ds_write_b16 v196, v8 offset:352
	v_mul_f32_e32 v8, v9, v2
	v_mul_f32_e32 v12, v12, v41
	v_mul_f32_e32 v8, v8, v37
	v_cvt_pk_bf16_f32 v12, v12, s0
	v_cvt_pk_bf16_f32 v8, v8, s0
	v_mul_f32_e32 v16, v18, v70
	ds_write_b16 v196, v12 offset:864
	v_mul_f32_e32 v12, v14, v70
	ds_write_b16 v196, v8 offset:896
	v_mul_f32_e32 v8, v10, v70
	v_mul_f32_e32 v20, v20, v49
	v_mul_f32_e32 v16, v16, v44
	v_mul_f32_e32 v12, v12, v41
	v_mul_f32_e32 v8, v8, v37
	v_cvt_pk_bf16_f32 v20, v20, s0
	v_cvt_pk_bf16_f32 v16, v16, s0
	v_cvt_pk_bf16_f32 v12, v12, s0
	v_cvt_pk_bf16_f32 v8, v8, s0
	ds_write_b16 v196, v20 offset:1344
	v_mul_f32_e32 v20, v23, v3
	ds_write_b16 v196, v16 offset:1376
	v_mul_f32_e32 v16, v19, v3
	ds_write_b16 v196, v12 offset:1408
	v_mul_f32_e32 v12, v15, v3
	ds_write_b16 v196, v8 offset:1440
	v_mul_f32_e32 v8, v11, v3
	v_mul_f32_e32 v20, v20, v49
	v_mul_f32_e32 v16, v16, v44
	v_mul_f32_e32 v12, v12, v41
	v_mul_f32_e32 v8, v8, v37
	v_cvt_pk_bf16_f32 v20, v20, s0
	v_cvt_pk_bf16_f32 v16, v16, s0
	v_cvt_pk_bf16_f32 v12, v12, s0
	v_cvt_pk_bf16_f32 v8, v8, s0
	ds_write_b16 v196, v20 offset:1888
	ds_write_b16 v196, v16 offset:1920
	ds_write_b16 v196, v12 offset:1952
	ds_write_b16 v196, v8 offset:1984
	s_waitcnt vmcnt(2)
	v_mul_f32_e32 v4, v4, v24
	v_cvt_pk_bf16_f32 v4, v4, s0
	ds_write_b16 v196, v4 offset:416
	v_mul_f32_e32 v4, v33, v2
	v_mul_f32_e32 v4, v4, v24
	v_cvt_pk_bf16_f32 v4, v4, s0
	ds_write_b16 v196, v4 offset:960
	v_mul_f32_e32 v4, v34, v70
	v_mul_f32_e32 v4, v4, v24
	v_cvt_pk_bf16_f32 v4, v4, s0
	ds_write_b16 v196, v4 offset:1504
	v_mul_f32_e32 v4, v35, v3
	v_mul_f32_e32 v4, v4, v24
	v_cvt_pk_bf16_f32 v4, v4, s0
	ds_write_b16 v196, v4 offset:2048
	v_mul_f32_e32 v4, v28, v0
	v_mul_f32_e32 v0, v56, v0
	s_waitcnt vmcnt(0)
; #define LAS __attribute__((address_space(3)))
; __device__ __forceinline__ unsigned f2bf(float f) { return (unsigned)__builtin_bit_cast(unsigned short, (__bf16)f); }
; __device__ __forceinline__ void unpack8(u32x4 w, float* f) { f[0] = lo16(w.x); f[1] = hi16(w.x); f[2] = lo16(w.y); f[3] = hi16(w.y); f[4] = lo16(w.z); f[5] = hi16(w.z); f[6] = lo16(w.w); f[7] = hi16(w.w); }
; __device__ __forceinline__ u32x4 pack8(const float* f) { u32x4 w; w.x = pk2(f[0], f[1]); w.y = pk2(f[2], f[3]); w.z = pk2(f[4], f[5]); w.w = pk2(f[6], f[7]); return w; }
; __device__ __forceinline__ float sigmoidf_(float x) { return __builtin_amdgcn_rcpf(1.0f + __expf(-x)); }
; #define X make_ctx(lds_raw)
;     ...
;           for (int nt = 0; nt < 16; ++nt) { const float nw = a->gla_norm_w[16 * nt + fr];
; #pragma unroll
;               for (int e = 0; e < 4; ++e) ost[(4 * fq + e) * 272 + 16 * nt + fr] = (bf16_t)f2bf(acc[nt][e] * rs[e] * nw); }
;           asm volatile("s_waitcnt lgkmcnt(0)" ::: "memory");
;           const int r = X.lane >> 2, cgp = X.lane & 3;
;           bf16_t* orow = proj + (size_t)(t0 + i0 + r) * NMAIN + C_GR + h * 256;
;           bf16_t* drow = dry ? proj + (size_t)NT * NMAIN + (size_t)((t0 + i0 + r) & 63) * NMAIN + C_GR + h * 256 : orow;
;           u32x4 gv[8];
; #pragma unroll
;           for (int q = 0; q < 8; ++q) gv[q] = *(const u32x4*)(orow + 8 * (cgp + 4 * q));
; #pragma unroll
;           for (int q = 0; q < 8; ++q) { const int c = cgp + 4 * q; float v[8], gr[8]; unpack8(*(const LAS u32x4*)(ost + r * 272 + 8 * c), v); unpack8(gv[q], gr);
; #pragma unroll
;               for (int e = 0; e < 8; ++e) v[e] *= gr[e] * sigmoidf_(gr[e]);
;               *(u32x4*)(drow + 8 * c) = pack8(v); } }
	v_mul_f32_e32 v0, v0, v27
	v_cvt_pk_bf16_f32 v0, v0, s0
	v_mul_f32_e32 v4, v4, v26
	ds_write_b16 v196, v0 offset:480
	v_mul_f32_e32 v0, v57, v2
	v_cvt_pk_bf16_f32 v4, v4, s0
	v_mul_f32_e32 v0, v0, v27
	ds_write_b16 v196, v4 offset:448
	v_mul_f32_e32 v4, v29, v2
	v_cvt_pk_bf16_f32 v0, v0, s0
	v_mul_f32_e32 v4, v4, v26
	ds_write_b16 v196, v0 offset:1024
	v_mul_f32_e32 v0, v58, v70
	v_cvt_pk_bf16_f32 v4, v4, s0
	v_mul_f32_e32 v0, v0, v27
	ds_write_b16 v196, v4 offset:992
	v_mul_f32_e32 v4, v30, v70
	v_cvt_pk_bf16_f32 v0, v0, s0
	v_mul_f32_e32 v4, v4, v26
	ds_write_b16 v196, v0 offset:1568
	v_mul_f32_e32 v0, v59, v3
	v_cvt_pk_bf16_f32 v4, v4, s0
	v_mul_f32_e32 v0, v0, v27
	ds_write_b16 v196, v4 offset:1536
	v_mul_f32_e32 v4, v31, v3
	v_cvt_pk_bf16_f32 v0, v0, s0
	v_mul_f32_e32 v4, v4, v26
	ds_write_b16 v196, v0 offset:2112
	v_add_u32_e32 v0, s44, v197
	v_mov_b64_e32 v[2:3], s[22:23]
	v_cvt_pk_bf16_f32 v4, v4, s0
	v_mad_i64_i32 v[2:3], s[0:1], v0, s48, v[2:3]
	v_lshl_add_u64 v[2:3], v[2:3], 0, s[36:37]
	v_lshl_add_u64 v[2:3], v[2:3], 0, v[110:111]
	ds_write_b16 v196, v4 offset:2080
	v_add_co_u32_e32 v44, vcc, s25, v2
	s_waitcnt lgkmcnt(0)
	v_lshl_add_u64 v[26:27], v[2:3], 0, s[14:15]
	s_nop 0
	v_addc_co_u32_e32 v45, vcc, 0, v3, vcc
	s_waitcnt vmcnt(0)
	v_mov_b32_e32 v28, v210
	v_mov_b32_e32 v29, v211
	v_mov_b32_e32 v30, v212
	v_mov_b32_e32 v31, v213
	v_mov_b32_e32 v32, v214
	v_mov_b32_e32 v33, v215
	v_mov_b32_e32 v34, v216
	v_mov_b32_e32 v35, v217
	v_mov_b32_e32 v22, v218
	v_mov_b32_e32 v23, v219
	v_mov_b32_e32 v24, v220
	v_mov_b32_e32 v25, v221
	v_mov_b32_e32 v18, v222
	v_mov_b32_e32 v19, v223
	v_mov_b32_e32 v20, v224
	v_mov_b32_e32 v21, v225
	v_mov_b32_e32 v14, v226
	v_mov_b32_e32 v15, v227
	v_mov_b32_e32 v16, v228
	v_mov_b32_e32 v17, v229
	ds_read_b128 v[36:39], v198
	v_mov_b32_e32 v10, v230
	v_mov_b32_e32 v11, v231
	v_mov_b32_e32 v12, v232
	v_mov_b32_e32 v13, v233
	v_mov_b32_e32 v6, v234
	v_mov_b32_e32 v7, v235
	v_mov_b32_e32 v8, v236
	v_mov_b32_e32 v9, v237
	v_mov_b32_e32 v2, v238
	v_mov_b32_e32 v3, v239
	v_mov_b32_e32 v4, v240
	v_mov_b32_e32 v5, v241
	ds_read_b128 v[40:43], v198 offset:64
	s_waitcnt lgkmcnt(1)
	v_lshlrev_b32_e32 v46, 16, v36
	v_and_b32_e32 v47, 0xffff0000, v36
	s_waitcnt vmcnt(7)
	v_lshlrev_b32_e32 v48, 16, v28
	v_and_b32_e32 v49, 0xffff0000, v28
	v_mul_f32_e32 v0, 0xbfb8aa3b, v48
	v_exp_f32_e32 v0, v0
	v_mul_f32_e32 v28, 0xbfb8aa3b, v49
	v_exp_f32_e32 v28, v28
	v_add_f32_e32 v0, 1.0, v0
	v_rcp_f32_e32 v50, v0
	v_add_f32_e32 v0, 1.0, v28
	v_lshlrev_b32_e32 v28, 16, v29
	v_rcp_f32_e32 v51, v0
	v_and_b32_e32 v29, 0xffff0000, v29
	v_mul_f32_e32 v0, 0xbfb8aa3b, v28
	v_exp_f32_e32 v0, v0
	v_mul_f32_e32 v36, 0xbfb8aa3b, v29
	v_exp_f32_e32 v36, v36
	v_pk_mul_f32 v[48:49], v[50:51], v[48:49]
	v_add_f32_e32 v0, 1.0, v0
	v_rcp_f32_e32 v50, v0
	v_add_f32_e32 v0, 1.0, v36
	v_rcp_f32_e32 v51, v0
	v_pk_mul_f32 v[46:47], v[48:49], v[46:47]
	v_lshlrev_b32_e32 v48, 16, v30
	v_lshlrev_b32_e32 v36, 16, v37
	v_and_b32_e32 v37, 0xffff0000, v37
	v_pk_mul_f32 v[28:29], v[50:51], v[28:29]
	v_and_b32_e32 v49, 0xffff0000, v30
	v_mul_f32_e32 v0, 0xbfb8aa3b, v48
	v_pk_mul_f32 v[36:37], v[28:29], v[36:37]
	v_exp_f32_e32 v0, v0
	v_mul_f32_e32 v29, 0xbfb8aa3b, v49
	v_exp_f32_e32 v30, v29
	v_lshlrev_b32_e32 v28, 16, v38
	v_add_f32_e32 v0, 1.0, v0
	v_rcp_f32_e32 v50, v0
	v_add_f32_e32 v0, 1.0, v30
	v_lshlrev_b32_e32 v30, 16, v31
	v_rcp_f32_e32 v51, v0
	v_and_b32_e32 v31, 0xffff0000, v31
	v_mul_f32_e32 v0, 0xbfb8aa3b, v30
	v_and_b32_e32 v29, 0xffff0000, v38
	v_exp_f32_e32 v0, v0
	v_mul_f32_e32 v38, 0xbfb8aa3b, v31
	v_exp_f32_e32 v38, v38
	v_pk_mul_f32 v[48:49], v[50:51], v[48:49]
	v_add_f32_e32 v0, 1.0, v0
	v_rcp_f32_e32 v50, v0
	v_add_f32_e32 v0, 1.0, v38
	v_rcp_f32_e32 v51, v0
	v_pk_mul_f32 v[48:49], v[48:49], v[28:29]
	v_lshlrev_b32_e32 v28, 16, v39
	v_and_b32_e32 v29, 0xffff0000, v39
	v_pk_mul_f32 v[30:31], v[50:51], v[30:31]
	s_nop 0
	v_pk_mul_f32 v[38:39], v[30:31], v[28:29]
	v_cvt_pk_bf16_f32 v28, v46, v47
	v_cvt_pk_bf16_f32 v29, v36, v37
	v_cvt_pk_bf16_f32 v30, v48, v49
	v_cvt_pk_bf16_f32 v31, v38, v39
	global_store_dwordx4 v[44:45], v[28:31], off
	s_waitcnt vmcnt(7)
	s_nop 0
	v_lshlrev_b32_e32 v30, 16, v32
	v_and_b32_e32 v31, 0xffff0000, v32
	v_mul_f32_e32 v0, 0xbfb8aa3b, v30
	v_exp_f32_e32 v0, v0
	v_mul_f32_e32 v29, 0xbfb8aa3b, v31
	v_exp_f32_e32 v32, v29
	s_waitcnt lgkmcnt(0)
	v_lshlrev_b32_e32 v28, 16, v40
	v_add_f32_e32 v0, 1.0, v0
	v_rcp_f32_e32 v36, v0
	v_add_f32_e32 v0, 1.0, v32
	v_lshlrev_b32_e32 v32, 16, v33
	v_rcp_f32_e32 v37, v0
	v_and_b32_e32 v33, 0xffff0000, v33
	v_mul_f32_e32 v0, 0xbfb8aa3b, v32
	v_exp_f32_e32 v0, v0
	v_mul_f32_e32 v38, 0xbfb8aa3b, v33
	v_exp_f32_e32 v38, v38
	v_pk_mul_f32 v[30:31], v[36:37], v[30:31]
	v_add_f32_e32 v0, 1.0, v0
	v_rcp_f32_e32 v36, v0
	v_add_f32_e32 v0, 1.0, v38
	v_rcp_f32_e32 v37, v0
	v_and_b32_e32 v29, 0xffff0000, v40
	v_pk_mul_f32 v[28:29], v[30:31], v[28:29]
	v_lshlrev_b32_e32 v30, 16, v41
	v_pk_mul_f32 v[32:33], v[36:37], v[32:33]
	v_lshlrev_b32_e32 v36, 16, v34
	v_and_b32_e32 v31, 0xffff0000, v41
	v_and_b32_e32 v37, 0xffff0000, v34
	v_mul_f32_e32 v0, 0xbfb8aa3b, v36
	v_pk_mul_f32 v[30:31], v[32:33], v[30:31]
	v_exp_f32_e32 v0, v0
	v_mul_f32_e32 v33, 0xbfb8aa3b, v37
	v_exp_f32_e32 v34, v33
	v_lshlrev_b32_e32 v32, 16, v42
	v_add_f32_e32 v0, 1.0, v0
	v_rcp_f32_e32 v38, v0
	v_add_f32_e32 v0, 1.0, v34
	v_lshlrev_b32_e32 v34, 16, v35
	v_rcp_f32_e32 v39, v0
	v_and_b32_e32 v35, 0xffff0000, v35
	v_mul_f32_e32 v0, 0xbfb8aa3b, v34
	v_exp_f32_e32 v0, v0
	v_mul_f32_e32 v40, 0xbfb8aa3b, v35
	v_exp_f32_e32 v40, v40
	v_pk_mul_f32 v[36:37], v[38:39], v[36:37]
	v_add_f32_e32 v0, 1.0, v0
	v_rcp_f32_e32 v38, v0
	v_add_f32_e32 v0, 1.0, v40
	v_rcp_f32_e32 v39, v0
	v_and_b32_e32 v33, 0xffff0000, v42
	v_pk_mul_f32 v[36:37], v[36:37], v[32:33]
	v_lshlrev_b32_e32 v32, 16, v43
	v_and_b32_e32 v33, 0xffff0000, v43
	v_pk_mul_f32 v[34:35], v[38:39], v[34:35]
	v_cvt_pk_bf16_f32 v28, v28, v29
	v_pk_mul_f32 v[38:39], v[34:35], v[32:33]
	v_cvt_pk_bf16_f32 v29, v30, v31
	v_cvt_pk_bf16_f32 v31, v38, v39
	s_waitcnt vmcnt(6)
; #define LAS __attribute__((address_space(3)))
; __device__ __forceinline__ void unpack8(u32x4 w, float* f) { f[0] = lo16(w.x); f[1] = hi16(w.x); f[2] = lo16(w.y); f[3] = hi16(w.y); f[4] = lo16(w.z); f[5] = hi16(w.z); f[6] = lo16(w.w); f[7] = hi16(w.w); }
; __device__ __forceinline__ u32x4 pack8(const float* f) { u32x4 w; w.x = pk2(f[0], f[1]); w.y = pk2(f[2], f[3]); w.z = pk2(f[4], f[5]); w.w = pk2(f[6], f[7]); return w; }
; __device__ __forceinline__ float sigmoidf_(float x) { return __builtin_amdgcn_rcpf(1.0f + __expf(-x)); }
;     ...
;           for (int q = 0; q < 8; ++q) { const int c = cgp + 4 * q; float v[8], gr[8]; unpack8(*(const LAS u32x4*)(ost + r * 272 + 8 * c), v); unpack8(gv[q], gr);
; #pragma unroll
;               for (int e = 0; e < 8; ++e) v[e] *= gr[e] * sigmoidf_(gr[e]);
;               *(u32x4*)(drow + 8 * c) = pack8(v); } }
	v_lshlrev_b32_e32 v38, 16, v22
	v_and_b32_e32 v39, 0xffff0000, v22
	v_mul_f32_e32 v0, 0xbfb8aa3b, v38
	v_exp_f32_e32 v0, v0
	v_mul_f32_e32 v22, 0xbfb8aa3b, v39
	v_exp_f32_e32 v22, v22
	ds_read_b128 v[32:35], v198 offset:128
	v_add_f32_e32 v0, 1.0, v0
	v_rcp_f32_e32 v40, v0
	v_add_f32_e32 v0, 1.0, v22
	v_lshlrev_b32_e32 v22, 16, v23
	v_cvt_pk_bf16_f32 v30, v36, v37
	v_rcp_f32_e32 v41, v0
	v_and_b32_e32 v23, 0xffff0000, v23
	v_mul_f32_e32 v0, 0xbfb8aa3b, v22
	global_store_dwordx4 v[26:27], v[28:31], off offset:64
	ds_read_b128 v[28:31], v198 offset:192
	s_waitcnt lgkmcnt(1)
	v_lshlrev_b32_e32 v36, 16, v32
	v_and_b32_e32 v37, 0xffff0000, v32
	v_exp_f32_e32 v0, v0
	v_mul_f32_e32 v32, 0xbfb8aa3b, v23
	v_exp_f32_e32 v32, v32
	v_pk_mul_f32 v[38:39], v[40:41], v[38:39]
	v_add_f32_e32 v0, 1.0, v0
	v_rcp_f32_e32 v40, v0
	v_add_f32_e32 v0, 1.0, v32
	v_rcp_f32_e32 v41, v0
	v_pk_mul_f32 v[36:37], v[38:39], v[36:37]
	v_lshlrev_b32_e32 v38, 16, v24
	v_lshlrev_b32_e32 v32, 16, v33
	v_and_b32_e32 v33, 0xffff0000, v33
	v_pk_mul_f32 v[22:23], v[40:41], v[22:23]
	v_and_b32_e32 v39, 0xffff0000, v24
	v_mul_f32_e32 v0, 0xbfb8aa3b, v38
	v_pk_mul_f32 v[32:33], v[22:23], v[32:33]
	v_exp_f32_e32 v0, v0
	v_mul_f32_e32 v23, 0xbfb8aa3b, v39
	v_exp_f32_e32 v24, v23
	v_lshlrev_b32_e32 v22, 16, v34
	v_add_f32_e32 v0, 1.0, v0
	v_rcp_f32_e32 v40, v0
	v_add_f32_e32 v0, 1.0, v24
	v_lshlrev_b32_e32 v24, 16, v25
	v_rcp_f32_e32 v41, v0
	v_and_b32_e32 v25, 0xffff0000, v25
	v_mul_f32_e32 v0, 0xbfb8aa3b, v24
	v_and_b32_e32 v23, 0xffff0000, v34
	v_exp_f32_e32 v0, v0
	v_mul_f32_e32 v34, 0xbfb8aa3b, v25
	v_exp_f32_e32 v34, v34
	v_pk_mul_f32 v[38:39], v[40:41], v[38:39]
	v_add_f32_e32 v0, 1.0, v0
	v_rcp_f32_e32 v40, v0
	v_add_f32_e32 v0, 1.0, v34
	v_rcp_f32_e32 v41, v0
	v_pk_mul_f32 v[38:39], v[38:39], v[22:23]
	v_lshlrev_b32_e32 v22, 16, v35
	v_and_b32_e32 v23, 0xffff0000, v35
	v_pk_mul_f32 v[24:25], v[40:41], v[24:25]
	s_nop 0
	v_pk_mul_f32 v[34:35], v[24:25], v[22:23]
	v_cvt_pk_bf16_f32 v22, v36, v37
	v_cvt_pk_bf16_f32 v23, v32, v33
	v_cvt_pk_bf16_f32 v24, v38, v39
	v_cvt_pk_bf16_f32 v25, v34, v35
	global_store_dwordx4 v[26:27], v[22:25], off offset:128
	s_waitcnt vmcnt(7)
	s_nop 0
	v_lshlrev_b32_e32 v24, 16, v18
	v_and_b32_e32 v25, 0xffff0000, v18
	v_mul_f32_e32 v0, 0xbfb8aa3b, v24
	v_exp_f32_e32 v0, v0
	v_mul_f32_e32 v18, 0xbfb8aa3b, v25
	v_exp_f32_e32 v18, v18
	s_waitcnt lgkmcnt(0)
	v_lshlrev_b32_e32 v22, 16, v28
	v_add_f32_e32 v0, 1.0, v0
	v_rcp_f32_e32 v32, v0
	v_add_f32_e32 v0, 1.0, v18
	v_lshlrev_b32_e32 v18, 16, v19
	v_rcp_f32_e32 v33, v0
	v_and_b32_e32 v19, 0xffff0000, v19
	v_mul_f32_e32 v0, 0xbfb8aa3b, v18
	v_and_b32_e32 v23, 0xffff0000, v28
	v_exp_f32_e32 v0, v0
	v_mul_f32_e32 v28, 0xbfb8aa3b, v19
	v_exp_f32_e32 v28, v28
	v_pk_mul_f32 v[24:25], v[32:33], v[24:25]
	v_add_f32_e32 v0, 1.0, v0
	v_rcp_f32_e32 v32, v0
	v_add_f32_e32 v0, 1.0, v28
	v_rcp_f32_e32 v33, v0
	v_lshlrev_b32_e32 v28, 16, v20
	v_pk_mul_f32 v[22:23], v[24:25], v[22:23]
	v_lshlrev_b32_e32 v24, 16, v29
	v_and_b32_e32 v25, 0xffff0000, v29
	v_pk_mul_f32 v[18:19], v[32:33], v[18:19]
	v_and_b32_e32 v29, 0xffff0000, v20
	v_mul_f32_e32 v0, 0xbfb8aa3b, v28
	v_pk_mul_f32 v[24:25], v[18:19], v[24:25]
	v_exp_f32_e32 v0, v0
	v_mul_f32_e32 v19, 0xbfb8aa3b, v29
	v_exp_f32_e32 v20, v19
	v_lshlrev_b32_e32 v18, 16, v30
	v_add_f32_e32 v0, 1.0, v0
	v_rcp_f32_e32 v32, v0
	v_add_f32_e32 v0, 1.0, v20
	v_lshlrev_b32_e32 v20, 16, v21
	v_rcp_f32_e32 v33, v0
	v_and_b32_e32 v21, 0xffff0000, v21
	v_mul_f32_e32 v0, 0xbfb8aa3b, v20
	v_and_b32_e32 v19, 0xffff0000, v30
	v_exp_f32_e32 v0, v0
	v_mul_f32_e32 v30, 0xbfb8aa3b, v21
	v_exp_f32_e32 v30, v30
	v_pk_mul_f32 v[28:29], v[32:33], v[28:29]
	v_add_f32_e32 v0, 1.0, v0
	v_rcp_f32_e32 v32, v0
	v_add_f32_e32 v0, 1.0, v30
	v_rcp_f32_e32 v33, v0
	v_pk_mul_f32 v[28:29], v[28:29], v[18:19]
	v_lshlrev_b32_e32 v18, 16, v31
	v_and_b32_e32 v19, 0xffff0000, v31
	v_pk_mul_f32 v[20:21], v[32:33], v[20:21]
	s_nop 0
	v_pk_mul_f32 v[30:31], v[20:21], v[18:19]
	v_cvt_pk_bf16_f32 v18, v22, v23
	v_cvt_pk_bf16_f32 v21, v30, v31
	s_waitcnt vmcnt(6)
	v_lshlrev_b32_e32 v30, 16, v14
	v_and_b32_e32 v31, 0xffff0000, v14
	v_mul_f32_e32 v0, 0xbfb8aa3b, v30
	v_exp_f32_e32 v0, v0
	v_mul_f32_e32 v14, 0xbfb8aa3b, v31
	v_exp_f32_e32 v14, v14
	v_cvt_pk_bf16_f32 v19, v24, v25
	ds_read_b128 v[22:25], v198 offset:256
	v_add_f32_e32 v0, 1.0, v0
	v_rcp_f32_e32 v32, v0
	v_add_f32_e32 v0, 1.0, v14
	v_lshlrev_b32_e32 v14, 16, v15
	v_cvt_pk_bf16_f32 v20, v28, v29
	v_rcp_f32_e32 v33, v0
	v_and_b32_e32 v15, 0xffff0000, v15
	v_mul_f32_e32 v0, 0xbfb8aa3b, v14
	global_store_dwordx4 v[26:27], v[18:21], off offset:192
	ds_read_b128 v[18:21], v198 offset:320
	s_waitcnt lgkmcnt(1)
	v_lshlrev_b32_e32 v28, 16, v22
	v_and_b32_e32 v29, 0xffff0000, v22
	v_exp_f32_e32 v0, v0
	v_mul_f32_e32 v22, 0xbfb8aa3b, v15
	v_exp_f32_e32 v22, v22
	v_pk_mul_f32 v[30:31], v[32:33], v[30:31]
	v_add_f32_e32 v0, 1.0, v0
	v_rcp_f32_e32 v32, v0
	v_add_f32_e32 v0, 1.0, v22
	v_rcp_f32_e32 v33, v0
	v_pk_mul_f32 v[28:29], v[30:31], v[28:29]
	v_lshlrev_b32_e32 v30, 16, v16
	v_lshlrev_b32_e32 v22, 16, v23
	v_and_b32_e32 v23, 0xffff0000, v23
	v_pk_mul_f32 v[14:15], v[32:33], v[14:15]
	v_and_b32_e32 v31, 0xffff0000, v16
	v_mul_f32_e32 v0, 0xbfb8aa3b, v30
	v_pk_mul_f32 v[22:23], v[14:15], v[22:23]
	v_exp_f32_e32 v0, v0
	v_mul_f32_e32 v15, 0xbfb8aa3b, v31
	v_exp_f32_e32 v16, v15
	v_lshlrev_b32_e32 v14, 16, v24
	v_add_f32_e32 v0, 1.0, v0
	v_rcp_f32_e32 v32, v0
	v_add_f32_e32 v0, 1.0, v16
	v_lshlrev_b32_e32 v16, 16, v17
	v_rcp_f32_e32 v33, v0
	v_and_b32_e32 v17, 0xffff0000, v17
	v_mul_f32_e32 v0, 0xbfb8aa3b, v16
	v_and_b32_e32 v15, 0xffff0000, v24
	v_exp_f32_e32 v0, v0
	v_mul_f32_e32 v24, 0xbfb8aa3b, v17
	v_exp_f32_e32 v24, v24
	v_pk_mul_f32 v[30:31], v[32:33], v[30:31]
	v_add_f32_e32 v0, 1.0, v0
	v_rcp_f32_e32 v32, v0
	v_add_f32_e32 v0, 1.0, v24
	v_rcp_f32_e32 v33, v0
	v_pk_mul_f32 v[30:31], v[30:31], v[14:15]
	v_lshlrev_b32_e32 v14, 16, v25
	v_and_b32_e32 v15, 0xffff0000, v25
	v_pk_mul_f32 v[16:17], v[32:33], v[16:17]
	s_nop 0
	v_pk_mul_f32 v[24:25], v[16:17], v[14:15]
	v_cvt_pk_bf16_f32 v14, v28, v29
	v_cvt_pk_bf16_f32 v15, v22, v23
	v_cvt_pk_bf16_f32 v16, v30, v31
	v_cvt_pk_bf16_f32 v17, v24, v25
	global_store_dwordx4 v[26:27], v[14:17], off offset:256
	s_waitcnt vmcnt(7)
; #define LAS __attribute__((address_space(3)))
; __device__ __forceinline__ void unpack8(u32x4 w, float* f) { f[0] = lo16(w.x); f[1] = hi16(w.x); f[2] = lo16(w.y); f[3] = hi16(w.y); f[4] = lo16(w.z); f[5] = hi16(w.z); f[6] = lo16(w.w); f[7] = hi16(w.w); }
; __device__ __forceinline__ u32x4 pack8(const float* f) { u32x4 w; w.x = pk2(f[0], f[1]); w.y = pk2(f[2], f[3]); w.z = pk2(f[4], f[5]); w.w = pk2(f[6], f[7]); return w; }
; __device__ __forceinline__ float sigmoidf_(float x) { return __builtin_amdgcn_rcpf(1.0f + __expf(-x)); }
;     ...
;     for (int unit = blockIdx.x; unit < 512; unit += gridDim.x) {
;     ...
;           for (int q = 0; q < 8; ++q) { const int c = cgp + 4 * q; float v[8], gr[8]; unpack8(*(const LAS u32x4*)(ost + r * 272 + 8 * c), v); unpack8(gv[q], gr);
; #pragma unroll
;               for (int e = 0; e < 8; ++e) v[e] *= gr[e] * sigmoidf_(gr[e]);
;               *(u32x4*)(drow + 8 * c) = pack8(v); } }
	s_nop 0
	v_lshlrev_b32_e32 v16, 16, v10
	v_and_b32_e32 v17, 0xffff0000, v10
	v_mul_f32_e32 v0, 0xbfb8aa3b, v16
	v_exp_f32_e32 v0, v0
	v_mul_f32_e32 v10, 0xbfb8aa3b, v17
	v_exp_f32_e32 v10, v10
	s_waitcnt lgkmcnt(0)
	v_lshlrev_b32_e32 v14, 16, v18
	v_add_f32_e32 v0, 1.0, v0
	v_rcp_f32_e32 v22, v0
	v_add_f32_e32 v0, 1.0, v10
	v_lshlrev_b32_e32 v10, 16, v11
	v_rcp_f32_e32 v23, v0
	v_and_b32_e32 v11, 0xffff0000, v11
	v_mul_f32_e32 v0, 0xbfb8aa3b, v10
	v_and_b32_e32 v15, 0xffff0000, v18
	v_exp_f32_e32 v0, v0
	v_mul_f32_e32 v18, 0xbfb8aa3b, v11
	v_exp_f32_e32 v18, v18
	v_pk_mul_f32 v[16:17], v[22:23], v[16:17]
	v_add_f32_e32 v0, 1.0, v0
	v_rcp_f32_e32 v22, v0
	v_add_f32_e32 v0, 1.0, v18
	v_rcp_f32_e32 v23, v0
	v_lshlrev_b32_e32 v18, 16, v12
	v_pk_mul_f32 v[14:15], v[16:17], v[14:15]
	v_lshlrev_b32_e32 v16, 16, v19
	v_and_b32_e32 v17, 0xffff0000, v19
	v_pk_mul_f32 v[10:11], v[22:23], v[10:11]
	v_and_b32_e32 v19, 0xffff0000, v12
	v_mul_f32_e32 v0, 0xbfb8aa3b, v18
	v_pk_mul_f32 v[16:17], v[10:11], v[16:17]
	v_exp_f32_e32 v0, v0
	v_mul_f32_e32 v11, 0xbfb8aa3b, v19
	v_exp_f32_e32 v12, v11
	v_lshlrev_b32_e32 v10, 16, v20
	v_add_f32_e32 v0, 1.0, v0
	v_rcp_f32_e32 v22, v0
	v_add_f32_e32 v0, 1.0, v12
	v_lshlrev_b32_e32 v12, 16, v13
	v_rcp_f32_e32 v23, v0
	v_and_b32_e32 v13, 0xffff0000, v13
	v_mul_f32_e32 v0, 0xbfb8aa3b, v12
	v_and_b32_e32 v11, 0xffff0000, v20
	v_exp_f32_e32 v0, v0
	v_mul_f32_e32 v20, 0xbfb8aa3b, v13
	v_exp_f32_e32 v20, v20
	v_pk_mul_f32 v[18:19], v[22:23], v[18:19]
	v_add_f32_e32 v0, 1.0, v0
	v_rcp_f32_e32 v22, v0
	v_add_f32_e32 v0, 1.0, v20
	v_rcp_f32_e32 v23, v0
	v_pk_mul_f32 v[18:19], v[18:19], v[10:11]
	v_lshlrev_b32_e32 v10, 16, v21
	v_and_b32_e32 v11, 0xffff0000, v21
	v_pk_mul_f32 v[12:13], v[22:23], v[12:13]
	s_nop 0
	v_pk_mul_f32 v[20:21], v[12:13], v[10:11]
	v_cvt_pk_bf16_f32 v10, v14, v15
	v_cvt_pk_bf16_f32 v13, v20, v21
	s_waitcnt vmcnt(6)
	v_lshlrev_b32_e32 v20, 16, v6
	v_and_b32_e32 v21, 0xffff0000, v6
	v_mul_f32_e32 v0, 0xbfb8aa3b, v20
	v_exp_f32_e32 v0, v0
	v_mul_f32_e32 v6, 0xbfb8aa3b, v21
	v_exp_f32_e32 v6, v6
	v_cvt_pk_bf16_f32 v11, v16, v17
	ds_read_b128 v[14:17], v198 offset:384
	v_add_f32_e32 v0, 1.0, v0
	v_rcp_f32_e32 v22, v0
	v_add_f32_e32 v0, 1.0, v6
	v_lshlrev_b32_e32 v6, 16, v7
	v_cvt_pk_bf16_f32 v12, v18, v19
	v_rcp_f32_e32 v23, v0
	v_and_b32_e32 v7, 0xffff0000, v7
	v_mul_f32_e32 v0, 0xbfb8aa3b, v6
	global_store_dwordx4 v[26:27], v[10:13], off offset:320
	ds_read_b128 v[10:13], v198 offset:448
	s_waitcnt lgkmcnt(1)
	v_lshlrev_b32_e32 v18, 16, v14
	v_and_b32_e32 v19, 0xffff0000, v14
	v_exp_f32_e32 v0, v0
	v_mul_f32_e32 v14, 0xbfb8aa3b, v7
	v_exp_f32_e32 v14, v14
	v_pk_mul_f32 v[20:21], v[22:23], v[20:21]
	v_add_f32_e32 v0, 1.0, v0
	v_rcp_f32_e32 v22, v0
	v_add_f32_e32 v0, 1.0, v14
	v_rcp_f32_e32 v23, v0
	v_pk_mul_f32 v[18:19], v[20:21], v[18:19]
	v_lshlrev_b32_e32 v20, 16, v8
	v_lshlrev_b32_e32 v14, 16, v15
	v_and_b32_e32 v15, 0xffff0000, v15
	v_pk_mul_f32 v[6:7], v[22:23], v[6:7]
	v_and_b32_e32 v21, 0xffff0000, v8
	v_mul_f32_e32 v0, 0xbfb8aa3b, v20
	v_pk_mul_f32 v[14:15], v[6:7], v[14:15]
	v_exp_f32_e32 v0, v0
	v_mul_f32_e32 v7, 0xbfb8aa3b, v21
	v_exp_f32_e32 v8, v7
	v_lshlrev_b32_e32 v6, 16, v16
	v_add_f32_e32 v0, 1.0, v0
	v_rcp_f32_e32 v22, v0
	v_add_f32_e32 v0, 1.0, v8
	v_lshlrev_b32_e32 v8, 16, v9
	v_rcp_f32_e32 v23, v0
	v_and_b32_e32 v9, 0xffff0000, v9
	v_mul_f32_e32 v0, 0xbfb8aa3b, v8
	v_and_b32_e32 v7, 0xffff0000, v16
	v_exp_f32_e32 v0, v0
	v_mul_f32_e32 v16, 0xbfb8aa3b, v9
	v_exp_f32_e32 v16, v16
	v_pk_mul_f32 v[20:21], v[22:23], v[20:21]
	v_add_f32_e32 v0, 1.0, v0
	v_rcp_f32_e32 v22, v0
	v_add_f32_e32 v0, 1.0, v16
	v_rcp_f32_e32 v23, v0
	v_pk_mul_f32 v[20:21], v[20:21], v[6:7]
	v_lshlrev_b32_e32 v6, 16, v17
	v_and_b32_e32 v7, 0xffff0000, v17
	v_pk_mul_f32 v[8:9], v[22:23], v[8:9]
	s_nop 0
	v_pk_mul_f32 v[16:17], v[8:9], v[6:7]
	v_cvt_pk_bf16_f32 v6, v18, v19
	v_cvt_pk_bf16_f32 v7, v14, v15
	v_cvt_pk_bf16_f32 v8, v20, v21
	v_cvt_pk_bf16_f32 v9, v16, v17
	global_store_dwordx4 v[26:27], v[6:9], off offset:384
	s_waitcnt vmcnt(7)
	s_nop 0
	v_lshlrev_b32_e32 v8, 16, v2
	v_and_b32_e32 v9, 0xffff0000, v2
	v_mul_f32_e32 v0, 0xbfb8aa3b, v8
	v_exp_f32_e32 v0, v0
	v_mul_f32_e32 v2, 0xbfb8aa3b, v9
	v_exp_f32_e32 v2, v2
	s_waitcnt lgkmcnt(0)
	v_lshlrev_b32_e32 v6, 16, v10
	v_add_f32_e32 v0, 1.0, v0
	v_rcp_f32_e32 v14, v0
	v_add_f32_e32 v0, 1.0, v2
	v_lshlrev_b32_e32 v2, 16, v3
	v_rcp_f32_e32 v15, v0
	v_and_b32_e32 v3, 0xffff0000, v3
	v_mul_f32_e32 v0, 0xbfb8aa3b, v2
	v_and_b32_e32 v7, 0xffff0000, v10
	v_exp_f32_e32 v0, v0
	v_mul_f32_e32 v10, 0xbfb8aa3b, v3
	v_exp_f32_e32 v10, v10
	v_pk_mul_f32 v[8:9], v[14:15], v[8:9]
	v_add_f32_e32 v0, 1.0, v0
	v_rcp_f32_e32 v14, v0
	v_add_f32_e32 v0, 1.0, v10
	v_rcp_f32_e32 v15, v0
	v_lshlrev_b32_e32 v10, 16, v4
	v_pk_mul_f32 v[6:7], v[8:9], v[6:7]
	v_lshlrev_b32_e32 v8, 16, v11
	v_and_b32_e32 v9, 0xffff0000, v11
	v_pk_mul_f32 v[2:3], v[14:15], v[2:3]
	v_and_b32_e32 v11, 0xffff0000, v4
	v_mul_f32_e32 v0, 0xbfb8aa3b, v10
	v_pk_mul_f32 v[8:9], v[2:3], v[8:9]
	v_exp_f32_e32 v0, v0
	v_mul_f32_e32 v3, 0xbfb8aa3b, v11
	v_exp_f32_e32 v4, v3
	v_lshlrev_b32_e32 v2, 16, v12
	v_add_f32_e32 v0, 1.0, v0
	v_rcp_f32_e32 v14, v0
	v_add_f32_e32 v0, 1.0, v4
	v_lshlrev_b32_e32 v4, 16, v5
	v_rcp_f32_e32 v15, v0
	v_and_b32_e32 v5, 0xffff0000, v5
	v_mul_f32_e32 v0, 0xbfb8aa3b, v4
	v_and_b32_e32 v3, 0xffff0000, v12
	v_exp_f32_e32 v0, v0
	v_mul_f32_e32 v12, 0xbfb8aa3b, v5
	v_exp_f32_e32 v12, v12
	v_pk_mul_f32 v[10:11], v[14:15], v[10:11]
	v_add_f32_e32 v0, 1.0, v0
	v_rcp_f32_e32 v14, v0
	v_add_f32_e32 v0, 1.0, v12
	v_rcp_f32_e32 v15, v0
	v_pk_mul_f32 v[10:11], v[10:11], v[2:3]
	v_lshlrev_b32_e32 v2, 16, v13
	v_and_b32_e32 v3, 0xffff0000, v13
	v_pk_mul_f32 v[4:5], v[14:15], v[4:5]
	s_nop 0
	v_pk_mul_f32 v[12:13], v[4:5], v[2:3]
	v_cvt_pk_bf16_f32 v2, v6, v7
	v_cvt_pk_bf16_f32 v3, v8, v9
	v_cvt_pk_bf16_f32 v4, v10, v11
	v_cvt_pk_bf16_f32 v5, v12, v13
	global_store_dwordx4 v[26:27], v[2:5], off offset:448
	s_cbranch_scc0 .LBB0_489
; #define LAS __attribute__((address_space(3)))
; #define X make_ctx(lds_raw)
; __device__ __forceinline__ void gla_bcum(KArgs a, int tid, int t0, int h, LAS float* segtot, LAS float* glrs, float (&bc)[32], float& tot) {
;     const int d = tid & 127, seg = __builtin_amdgcn_readfirstlane(tid >> 7), col = h * 128 + d;
;     const float* glr = (const float*)(a->ws + WS_GLR);
;     float w2r[16];
; #pragma unroll
;     for (int j = 0; j < 16; ++j) w2r[j] = a->gate_w2[j * 512 + col];
;     const float bias = a->gate_b[col];
;     *(LAS f32x4*)(glrs + tid * 4) = *(const f32x4*)(glr + (size_t)t0 * 16 + tid * 4);
;     __syncthreads();
;     float run = 0.f;
; #pragma unroll
;     for (int r = 0; r < 32; ++r) { const LAS f32x4* gp = (const LAS f32x4*)(glrs + (seg * 32 + r) * 16);
;         float z = bias;
; #pragma unroll
;         for (int q = 0; q < 4; ++q) { const f32x4 g = gp[q]; z += g[0] * w2r[4 * q] + g[1] * w2r[4 * q + 1] + g[2] * w2r[4 * q + 2] + g[3] * w2r[4 * q + 3]; }
;         const float la = (fminf(z, 0.f) - __logf(1.0f + __expf(-fabsf(z)))) * (1.0f / 16.0f);
;         run += la; bc[r] = run; }
;     ...
;     for (int unit = blockIdx.x; unit < 512; unit += gridDim.x) {
;         const int bh = unit >> 5, n = unit & 31, b = bh >> 2, h = bh & 3, t0 = b * SEQ + n * 128;
;         __syncthreads();
;         { float bc[32], tot; gla_bcum(a, X.tid, t0, h, segtot, (LAS float*)vT, bc, tot);
.LBB0_478:
	s_bfe_u32 s1, s42, 0x20005
	s_lshl_b32 s8, s1, 9
	v_lshl_or_b32 v0, v88, 2, s8
	v_lshl_add_u64 v[16:17], s[16:17], 0, v[0:1]
	v_add_co_u32_e32 v18, vcc, s25, v16
	s_and_b32 s0, s42, 31
	s_nop 0
	v_addc_co_u32_e32 v19, vcc, 0, v17, vcc
	v_add_co_u32_e32 v2, vcc, s26, v16
	s_lshl_b32 s6, s42, 5
	s_nop 0
	v_addc_co_u32_e32 v3, vcc, 0, v17, vcc
	v_add_co_u32_e32 v24, vcc, s27, v16
	s_and_b32 s6, s6, 0xfffff000
	s_lshl_b32 s7, s0, 7
	v_addc_co_u32_e32 v25, vcc, 0, v17, vcc
	s_or_b32 s44, s6, s7
	v_add_co_u32_e32 v4, vcc, s28, v16
	s_ashr_i32 s45, s44, 31
	s_nop 0
	v_addc_co_u32_e32 v5, vcc, 0, v17, vcc
	s_lshl_b64 s[6:7], s[44:45], 6
	v_add_co_u32_e32 v26, vcc, s30, v16
	v_lshl_add_u64 v[6:7], v[90:91], 0, s[6:7]
	s_nop 0
	v_addc_co_u32_e32 v27, vcc, 0, v17, vcc
	s_barrier
	global_load_dwordx4 v[20:23], v[6:7], off
	global_load_dword v12, v0, s[16:17]
	global_load_dword v15, v0, s[16:17] offset:2048
	global_load_dword v14, v[2:3], off offset:-4096
	global_load_dword v11, v[2:3], off
	global_load_dword v13, v[2:3], off offset:2048
	global_load_dword v9, v[4:5], off offset:-4096
	s_nop 0
	global_load_dword v3, v[4:5], off
	global_load_dword v7, v[4:5], off offset:2048
	s_nop 0
	global_load_dword v5, v[26:27], off offset:-4096
	global_load_dword v2, v[26:27], off
	global_load_dword v4, v[26:27], off offset:2048
	v_add_co_u32_e32 v26, vcc, s29, v16
	v_readfirstlane_b32 s36, v84
	s_nop 0
	v_addc_co_u32_e32 v27, vcc, 0, v17, vcc
	v_add_co_u32_e32 v28, vcc, s31, v16
	s_ashr_i32 s9, s36, 7
	s_nop 0
	v_addc_co_u32_e32 v29, vcc, 0, v17, vcc
	global_load_dword v6, v[28:29], off
	global_load_dword v17, v[18:19], off offset:2048
	global_load_dword v16, v[24:25], off offset:2048
	global_load_dword v10, v[26:27], off offset:2048
	global_load_dword v8, v[28:29], off offset:2048
	s_nop 0
	global_load_dword v19, v0, s[18:19]
	s_lshl_b32 s98, s1, 8
	s_mov_b32 s99, 0
	v_lshl_add_u64 v[82:83], v[92:93], 0, s[98:99]
	s_lshl_b32 s6, s9, 11
	s_add_i32 s6, s6, 0
	s_add_i32 s6, s6, 0x11000
	v_mov_b32_e32 v0, s6
	v_mov_b32_e32 v111, v1
	s_waitcnt vmcnt(17)
	ds_write_b128 v117, v[20:23]
	s_waitcnt lgkmcnt(0)
	s_barrier
	ds_read_b128 v[20:23], v0
	ds_read_b128 v[24:27], v0 offset:16
	ds_read_b128 v[28:31], v0 offset:32
	ds_read_b128 v[32:35], v0 offset:48
	ds_read_b128 v[36:39], v0 offset:64
	ds_read_b128 v[40:43], v0 offset:80
	s_waitcnt lgkmcnt(5)
	s_waitcnt vmcnt(15)
	v_mul_f32_e32 v18, v15, v21
	s_waitcnt lgkmcnt(4)
	s_waitcnt vmcnt(12)
	v_mul_f32_e32 v21, v13, v25
	v_fmac_f32_e32 v18, v12, v20
	s_waitcnt lgkmcnt(3)
	s_waitcnt vmcnt(9)
	v_mul_f32_e32 v25, v7, v29
	v_fmac_f32_e32 v21, v11, v24
	v_fmac_f32_e32 v18, v14, v22
	s_waitcnt lgkmcnt(2)
	s_waitcnt vmcnt(6)
	v_mul_f32_e32 v29, v4, v33
	v_fmac_f32_e32 v25, v3, v28
	v_fmac_f32_e32 v21, v9, v26
	v_fmac_f32_e32 v29, v2, v32
	s_waitcnt vmcnt(4)
	v_fmac_f32_e32 v18, v17, v23
	v_fmac_f32_e32 v25, v5, v30
	s_waitcnt vmcnt(3)
	v_fmac_f32_e32 v21, v16, v27
	v_fmac_f32_e32 v29, v6, v34
	s_waitcnt vmcnt(0)
	v_add_f32_e32 v18, v19, v18
	v_fmac_f32_e32 v25, v10, v31
	v_add_f32_e32 v18, v18, v21
	v_fmac_f32_e32 v29, v8, v35
	v_add_f32_e32 v18, v18, v25
	v_add_f32_e32 v18, v18, v29
	v_mul_f32_e64 v20, |v18|, s33
	v_exp_f32_e32 v20, v20
	s_waitcnt lgkmcnt(1)
	v_mul_f32_e32 v33, v15, v37
	s_waitcnt lgkmcnt(0)
	v_mul_f32_e32 v24, v13, v41
	v_fmac_f32_e32 v33, v12, v36
	v_add_f32_e32 v20, 1.0, v20
	v_fmac_f32_e32 v33, v14, v38
	v_fmac_f32_e32 v24, v11, v40
	v_log_f32_e32 v28, v20
	v_fmac_f32_e32 v33, v17, v39
	v_fmac_f32_e32 v24, v9, v42
	v_add_f32_e32 v25, v19, v33
	v_mul_f32_e32 v20, 0x3f317217, v28
	v_fma_f32 v29, v28, s35, -v20
	ds_read_b128 v[20:23], v0 offset:96
	v_fmac_f32_e32 v24, v16, v43
	v_add_f32_e32 v30, v25, v24
	ds_read_b128 v[24:27], v0 offset:112
	v_fmac_f32_e32 v29, 0x3377d1cf, v28
	s_waitcnt lgkmcnt(1)
	v_mul_f32_e32 v21, v7, v21
	v_fmac_f32_e32 v21, v3, v20
	v_fmac_f32_e32 v21, v5, v22
	v_fmac_f32_e32 v21, v10, v23
	v_add_f32_e32 v20, v30, v21
	s_waitcnt lgkmcnt(0)
	v_mul_f32_e32 v21, v4, v25
	v_fmac_f32_e32 v21, v2, v24
	v_fmac_f32_e32 v21, v6, v26
	v_fmac_f32_e32 v21, v8, v27
	v_add_f32_e32 v20, v20, v21
	v_mul_f32_e64 v21, |v20|, s33
	v_exp_f32_e32 v21, v21
	v_fmac_f32_e32 v29, 0x3f317217, v28
	v_add_f32_e32 v21, 1.0, v21
	v_mov_b32_e32 v22, v29
	v_min_f32_e32 v18, 0, v18
	v_log_f32_e32 v28, v21
	v_sub_f32_e32 v18, v18, v22
	v_min_f32_e32 v29, 0, v20
	ds_read_b128 v[20:23], v0 offset:128
	v_mul_f32_e32 v24, 0x3f317217, v28
	v_fma_f32 v30, v28, s35, -v24
	ds_read_b128 v[24:27], v0 offset:144
	v_fmac_f32_e32 v30, 0x3377d1cf, v28
	s_waitcnt lgkmcnt(1)
	v_mul_f32_e32 v21, v15, v21
	v_fmac_f32_e32 v21, v12, v20
	v_fmac_f32_e32 v21, v14, v22
	v_fmac_f32_e32 v21, v17, v23
	v_add_f32_e32 v31, v19, v21
	s_waitcnt lgkmcnt(0)
	v_mul_f32_e32 v25, v13, v25
	ds_read_b128 v[20:23], v0 offset:160
	v_fmac_f32_e32 v25, v11, v24
	v_fmac_f32_e32 v25, v9, v26
	v_fmac_f32_e32 v25, v16, v27
	v_add_f32_e32 v31, v31, v25
	ds_read_b128 v[24:27], v0 offset:176
	s_waitcnt lgkmcnt(1)
	v_mul_f32_e32 v21, v7, v21
	v_fmac_f32_e32 v21, v3, v20
	v_fmac_f32_e32 v21, v5, v22
	v_fmac_f32_e32 v21, v10, v23
	v_add_f32_e32 v20, v31, v21
	s_waitcnt lgkmcnt(0)
	v_mul_f32_e32 v21, v4, v25
	v_fmac_f32_e32 v21, v2, v24
	v_fmac_f32_e32 v21, v6, v26
	v_fmac_f32_e32 v21, v8, v27
	v_add_f32_e32 v21, v20, v21
	v_mul_f32_e64 v20, |v21|, s33
	v_exp_f32_e32 v20, v20
	v_fmac_f32_e32 v30, 0x3f317217, v28
	v_add_f32_e32 v20, 1.0, v20
	v_mov_b32_e32 v22, v30
	v_min_f32_e32 v21, 0, v21
	v_log_f32_e32 v30, v20
	v_sub_f32_e32 v20, v29, v22
	ds_read_b128 v[22:25], v0 offset:192
	v_fma_f32 v18, v18, s47, 0
	v_mul_f32_e32 v26, 0x3f317217, v30
	v_fma_f32 v31, v30, s35, -v26
	ds_read_b128 v[26:29], v0 offset:208
	s_waitcnt lgkmcnt(1)
; #define LAS __attribute__((address_space(3)))
; __device__ __forceinline__ void gla_bcum(KArgs a, int tid, int t0, int h, LAS float* segtot, LAS float* glrs, float (&bc)[32], float& tot) {
;     ...
;     float run = 0.f;
; #pragma unroll
;     for (int r = 0; r < 32; ++r) { const LAS f32x4* gp = (const LAS f32x4*)(glrs + (seg * 32 + r) * 16);
;         float z = bias;
; #pragma unroll
;         for (int q = 0; q < 4; ++q) { const f32x4 g = gp[q]; z += g[0] * w2r[4 * q] + g[1] * w2r[4 * q + 1] + g[2] * w2r[4 * q + 2] + g[3] * w2r[4 * q + 3]; }
;         const float la = (fminf(z, 0.f) - __logf(1.0f + __expf(-fabsf(z)))) * (1.0f / 16.0f);
;         run += la; bc[r] = run; }
	v_mul_f32_e32 v23, v15, v23
	v_fmac_f32_e32 v23, v12, v22
	v_fmac_f32_e32 v23, v14, v24
	v_fmac_f32_e32 v23, v17, v25
	v_add_f32_e32 v32, v19, v23
	s_waitcnt lgkmcnt(0)
	v_mul_f32_e32 v27, v13, v27
	ds_read_b128 v[22:25], v0 offset:224
	v_fmac_f32_e32 v27, v11, v26
	v_fmac_f32_e32 v27, v9, v28
	v_fmac_f32_e32 v27, v16, v29
	v_add_f32_e32 v32, v32, v27
	ds_read_b128 v[26:29], v0 offset:240
	s_waitcnt lgkmcnt(1)
	v_mul_f32_e32 v23, v7, v23
	v_fmac_f32_e32 v23, v3, v22
	v_fmac_f32_e32 v23, v5, v24
	v_fmac_f32_e32 v23, v10, v25
	v_add_f32_e32 v22, v32, v23
	s_waitcnt lgkmcnt(0)
	v_mul_f32_e32 v23, v4, v27
	v_fmac_f32_e32 v23, v2, v26
	v_fmac_f32_e32 v23, v6, v28
	v_fmac_f32_e32 v23, v8, v29
	v_add_f32_e32 v22, v22, v23
	v_mul_f32_e64 v23, |v22|, s33
	v_exp_f32_e32 v23, v23
	v_fmac_f32_e32 v31, 0x3377d1cf, v30
	v_fmac_f32_e32 v31, 0x3f317217, v30
	v_add_f32_e32 v23, 1.0, v23
	v_mov_b32_e32 v24, v31
	v_sub_f32_e32 v21, v21, v24
	v_log_f32_e32 v30, v23
	v_min_f32_e32 v31, 0, v22
	ds_read_b128 v[22:25], v0 offset:256
	v_fmamk_f32 v20, v20, 0x3d800000, v18
	v_mul_f32_e32 v26, 0x3f317217, v30
	v_fma_f32 v32, v30, s35, -v26
	ds_read_b128 v[26:29], v0 offset:272
	s_waitcnt lgkmcnt(1)
	v_mul_f32_e32 v23, v15, v23
	v_fmac_f32_e32 v23, v12, v22
	v_fmac_f32_e32 v23, v14, v24
	v_fmac_f32_e32 v23, v17, v25
	v_add_f32_e32 v33, v19, v23
	s_waitcnt lgkmcnt(0)
	v_mul_f32_e32 v27, v13, v27
	ds_read_b128 v[22:25], v0 offset:288
	v_fmac_f32_e32 v27, v11, v26
	v_fmac_f32_e32 v27, v9, v28
	v_fmac_f32_e32 v27, v16, v29
	v_add_f32_e32 v33, v33, v27
	ds_read_b128 v[26:29], v0 offset:304
	s_waitcnt lgkmcnt(1)
	v_mul_f32_e32 v23, v7, v23
	v_fmac_f32_e32 v23, v3, v22
	v_fmac_f32_e32 v23, v5, v24
	v_fmac_f32_e32 v23, v10, v25
	v_add_f32_e32 v22, v33, v23
	s_waitcnt lgkmcnt(0)
	v_mul_f32_e32 v23, v4, v27
	v_fmac_f32_e32 v23, v2, v26
	v_fmac_f32_e32 v23, v6, v28
	v_fmac_f32_e32 v23, v8, v29
	v_add_f32_e32 v23, v22, v23
	v_mul_f32_e64 v22, |v23|, s33
	v_exp_f32_e32 v22, v22
	v_fmac_f32_e32 v32, 0x3377d1cf, v30
	v_fmac_f32_e32 v32, 0x3f317217, v30
	v_add_f32_e32 v22, 1.0, v22
	v_mov_b32_e32 v24, v32
	v_min_f32_e32 v23, 0, v23
	v_log_f32_e32 v32, v22
	v_sub_f32_e32 v22, v31, v24
	ds_read_b128 v[24:27], v0 offset:320
	v_fmamk_f32 v21, v21, 0x3d800000, v20
	v_mul_f32_e32 v28, 0x3f317217, v32
	v_fma_f32 v33, v32, s35, -v28
	ds_read_b128 v[28:31], v0 offset:336
	s_waitcnt lgkmcnt(1)
	v_mul_f32_e32 v25, v15, v25
	v_fmac_f32_e32 v25, v12, v24
	v_fmac_f32_e32 v25, v14, v26
	v_fmac_f32_e32 v25, v17, v27
	v_add_f32_e32 v34, v19, v25
	s_waitcnt lgkmcnt(0)
	v_mul_f32_e32 v29, v13, v29
	ds_read_b128 v[24:27], v0 offset:352
	v_fmac_f32_e32 v29, v11, v28
	v_fmac_f32_e32 v29, v9, v30
	v_fmac_f32_e32 v29, v16, v31
	v_add_f32_e32 v34, v34, v29
	ds_read_b128 v[28:31], v0 offset:368
	s_waitcnt lgkmcnt(1)
	v_mul_f32_e32 v25, v7, v25
	v_fmac_f32_e32 v25, v3, v24
	v_fmac_f32_e32 v25, v5, v26
	v_fmac_f32_e32 v25, v10, v27
	v_add_f32_e32 v24, v34, v25
	s_waitcnt lgkmcnt(0)
	v_mul_f32_e32 v25, v4, v29
	v_fmac_f32_e32 v25, v2, v28
	v_fmac_f32_e32 v25, v6, v30
	v_fmac_f32_e32 v25, v8, v31
	v_add_f32_e32 v24, v24, v25
	v_mul_f32_e64 v25, |v24|, s33
	v_exp_f32_e32 v25, v25
	v_fmac_f32_e32 v33, 0x3377d1cf, v32
	v_fmac_f32_e32 v33, 0x3f317217, v32
	v_add_f32_e32 v25, 1.0, v25
	v_mov_b32_e32 v26, v33
	v_sub_f32_e32 v23, v23, v26
	v_log_f32_e32 v32, v25
	v_min_f32_e32 v33, 0, v24
	ds_read_b128 v[24:27], v0 offset:384
	v_fmamk_f32 v22, v22, 0x3d800000, v21
	v_mul_f32_e32 v28, 0x3f317217, v32
	v_fma_f32 v34, v32, s35, -v28
	ds_read_b128 v[28:31], v0 offset:400
	s_waitcnt lgkmcnt(1)
	v_mul_f32_e32 v25, v15, v25
	v_fmac_f32_e32 v25, v12, v24
	v_fmac_f32_e32 v25, v14, v26
	v_fmac_f32_e32 v25, v17, v27
	v_add_f32_e32 v35, v19, v25
	s_waitcnt lgkmcnt(0)
	v_mul_f32_e32 v29, v13, v29
	ds_read_b128 v[24:27], v0 offset:416
	v_fmac_f32_e32 v29, v11, v28
	v_fmac_f32_e32 v29, v9, v30
	v_fmac_f32_e32 v29, v16, v31
	v_add_f32_e32 v35, v35, v29
	ds_read_b128 v[28:31], v0 offset:432
	s_waitcnt lgkmcnt(1)
	v_mul_f32_e32 v25, v7, v25
	v_fmac_f32_e32 v25, v3, v24
	v_fmac_f32_e32 v25, v5, v26
	v_fmac_f32_e32 v25, v10, v27
	v_add_f32_e32 v24, v35, v25
	s_waitcnt lgkmcnt(0)
	v_mul_f32_e32 v25, v4, v29
	v_fmac_f32_e32 v25, v2, v28
	v_fmac_f32_e32 v25, v6, v30
	v_fmac_f32_e32 v25, v8, v31
	v_add_f32_e32 v25, v24, v25
	v_mul_f32_e64 v24, |v25|, s33
	v_exp_f32_e32 v24, v24
	v_fmac_f32_e32 v34, 0x3377d1cf, v32
	v_fmac_f32_e32 v34, 0x3f317217, v32
	v_add_f32_e32 v24, 1.0, v24
	v_mov_b32_e32 v26, v34
	v_min_f32_e32 v25, 0, v25
	v_log_f32_e32 v34, v24
	v_sub_f32_e32 v24, v33, v26
	ds_read_b128 v[26:29], v0 offset:448
	v_fmamk_f32 v23, v23, 0x3d800000, v22
	v_mul_f32_e32 v30, 0x3f317217, v34
	v_fma_f32 v35, v34, s35, -v30
	ds_read_b128 v[30:33], v0 offset:464
	s_waitcnt lgkmcnt(1)
	v_mul_f32_e32 v27, v15, v27
	v_fmac_f32_e32 v27, v12, v26
	v_fmac_f32_e32 v27, v14, v28
	v_fmac_f32_e32 v27, v17, v29
	v_add_f32_e32 v36, v19, v27
	s_waitcnt lgkmcnt(0)
	v_mul_f32_e32 v31, v13, v31
	ds_read_b128 v[26:29], v0 offset:480
	v_fmac_f32_e32 v31, v11, v30
	v_fmac_f32_e32 v31, v9, v32
	v_fmac_f32_e32 v31, v16, v33
	v_add_f32_e32 v36, v36, v31
	ds_read_b128 v[30:33], v0 offset:496
	s_waitcnt lgkmcnt(1)
	v_mul_f32_e32 v27, v7, v27
	v_fmac_f32_e32 v27, v3, v26
	v_fmac_f32_e32 v27, v5, v28
	v_fmac_f32_e32 v27, v10, v29
	v_add_f32_e32 v26, v36, v27
	s_waitcnt lgkmcnt(0)
; #define LAS __attribute__((address_space(3)))
; __device__ __forceinline__ void gla_bcum(KArgs a, int tid, int t0, int h, LAS float* segtot, LAS float* glrs, float (&bc)[32], float& tot) {
;     ...
;     float run = 0.f;
; #pragma unroll
;     for (int r = 0; r < 32; ++r) { const LAS f32x4* gp = (const LAS f32x4*)(glrs + (seg * 32 + r) * 16);
;         float z = bias;
; #pragma unroll
;         for (int q = 0; q < 4; ++q) { const f32x4 g = gp[q]; z += g[0] * w2r[4 * q] + g[1] * w2r[4 * q + 1] + g[2] * w2r[4 * q + 2] + g[3] * w2r[4 * q + 3]; }
;         const float la = (fminf(z, 0.f) - __logf(1.0f + __expf(-fabsf(z)))) * (1.0f / 16.0f);
;         run += la; bc[r] = run; }
	v_mul_f32_e32 v27, v4, v31
	v_fmac_f32_e32 v27, v2, v30
	v_fmac_f32_e32 v27, v6, v32
	v_fmac_f32_e32 v27, v8, v33
	v_add_f32_e32 v26, v26, v27
	v_mul_f32_e64 v27, |v26|, s33
	v_exp_f32_e32 v27, v27
	v_fmac_f32_e32 v35, 0x3377d1cf, v34
	v_fmac_f32_e32 v35, 0x3f317217, v34
	v_add_f32_e32 v27, 1.0, v27
	v_mov_b32_e32 v28, v35
	v_sub_f32_e32 v25, v25, v28
	v_log_f32_e32 v34, v27
	v_min_f32_e32 v35, 0, v26
	ds_read_b128 v[26:29], v0 offset:512
	v_fmamk_f32 v24, v24, 0x3d800000, v23
	v_mul_f32_e32 v30, 0x3f317217, v34
	v_fma_f32 v36, v34, s35, -v30
	ds_read_b128 v[30:33], v0 offset:528
	s_waitcnt lgkmcnt(1)
	v_mul_f32_e32 v27, v15, v27
	v_fmac_f32_e32 v27, v12, v26
	v_fmac_f32_e32 v27, v14, v28
	v_fmac_f32_e32 v27, v17, v29
	v_add_f32_e32 v37, v19, v27
	s_waitcnt lgkmcnt(0)
	v_mul_f32_e32 v31, v13, v31
	ds_read_b128 v[26:29], v0 offset:544
	v_fmac_f32_e32 v31, v11, v30
	v_fmac_f32_e32 v31, v9, v32
	v_fmac_f32_e32 v31, v16, v33
	v_add_f32_e32 v37, v37, v31
	ds_read_b128 v[30:33], v0 offset:560
	s_waitcnt lgkmcnt(1)
	v_mul_f32_e32 v27, v7, v27
	v_fmac_f32_e32 v27, v3, v26
	v_fmac_f32_e32 v27, v5, v28
	v_fmac_f32_e32 v27, v10, v29
	v_add_f32_e32 v26, v37, v27
	s_waitcnt lgkmcnt(0)
	v_mul_f32_e32 v27, v4, v31
	v_fmac_f32_e32 v27, v2, v30
	v_fmac_f32_e32 v27, v6, v32
	v_fmac_f32_e32 v27, v8, v33
	v_add_f32_e32 v27, v26, v27
	v_mul_f32_e64 v26, |v27|, s33
	v_exp_f32_e32 v26, v26
	v_fmac_f32_e32 v36, 0x3377d1cf, v34
	v_fmac_f32_e32 v36, 0x3f317217, v34
	v_add_f32_e32 v26, 1.0, v26
	v_mov_b32_e32 v28, v36
	v_min_f32_e32 v27, 0, v27
	v_log_f32_e32 v36, v26
	v_sub_f32_e32 v26, v35, v28
	ds_read_b128 v[28:31], v0 offset:576
	v_fmamk_f32 v25, v25, 0x3d800000, v24
	v_mul_f32_e32 v32, 0x3f317217, v36
	v_fma_f32 v37, v36, s35, -v32
	ds_read_b128 v[32:35], v0 offset:592
	s_waitcnt lgkmcnt(1)
	v_mul_f32_e32 v29, v15, v29
	v_fmac_f32_e32 v29, v12, v28
	v_fmac_f32_e32 v29, v14, v30
	v_fmac_f32_e32 v29, v17, v31
	v_add_f32_e32 v38, v19, v29
	s_waitcnt lgkmcnt(0)
	v_mul_f32_e32 v33, v13, v33
	ds_read_b128 v[28:31], v0 offset:608
	v_fmac_f32_e32 v33, v11, v32
	v_fmac_f32_e32 v33, v9, v34
	v_fmac_f32_e32 v33, v16, v35
	v_add_f32_e32 v38, v38, v33
	ds_read_b128 v[32:35], v0 offset:624
	s_waitcnt lgkmcnt(1)
	v_mul_f32_e32 v29, v7, v29
	v_fmac_f32_e32 v29, v3, v28
	v_fmac_f32_e32 v29, v5, v30
	v_fmac_f32_e32 v29, v10, v31
	v_add_f32_e32 v28, v38, v29
	s_waitcnt lgkmcnt(0)
	v_mul_f32_e32 v29, v4, v33
	v_fmac_f32_e32 v29, v2, v32
	v_fmac_f32_e32 v29, v6, v34
	v_fmac_f32_e32 v29, v8, v35
	v_add_f32_e32 v28, v28, v29
	v_mul_f32_e64 v29, |v28|, s33
	v_exp_f32_e32 v29, v29
	v_fmac_f32_e32 v37, 0x3377d1cf, v36
	v_fmac_f32_e32 v37, 0x3f317217, v36
	v_add_f32_e32 v29, 1.0, v29
	v_mov_b32_e32 v30, v37
	v_sub_f32_e32 v27, v27, v30
	v_log_f32_e32 v36, v29
	v_min_f32_e32 v37, 0, v28
	ds_read_b128 v[28:31], v0 offset:640
	v_fmamk_f32 v26, v26, 0x3d800000, v25
	v_mul_f32_e32 v32, 0x3f317217, v36
	v_fma_f32 v38, v36, s35, -v32
	ds_read_b128 v[32:35], v0 offset:656
	s_waitcnt lgkmcnt(1)
	v_mul_f32_e32 v29, v15, v29
	v_fmac_f32_e32 v29, v12, v28
	v_fmac_f32_e32 v29, v14, v30
	v_fmac_f32_e32 v29, v17, v31
	v_add_f32_e32 v39, v19, v29
	s_waitcnt lgkmcnt(0)
	v_mul_f32_e32 v33, v13, v33
	ds_read_b128 v[28:31], v0 offset:672
	v_fmac_f32_e32 v33, v11, v32
	v_fmac_f32_e32 v33, v9, v34
	v_fmac_f32_e32 v33, v16, v35
	v_add_f32_e32 v39, v39, v33
	ds_read_b128 v[32:35], v0 offset:688
	s_waitcnt lgkmcnt(1)
	v_mul_f32_e32 v29, v7, v29
	v_fmac_f32_e32 v29, v3, v28
	v_fmac_f32_e32 v29, v5, v30
	v_fmac_f32_e32 v29, v10, v31
	v_add_f32_e32 v28, v39, v29
	s_waitcnt lgkmcnt(0)
	v_mul_f32_e32 v29, v4, v33
	v_fmac_f32_e32 v29, v2, v32
	v_fmac_f32_e32 v29, v6, v34
	v_fmac_f32_e32 v29, v8, v35
	v_add_f32_e32 v29, v28, v29
	v_mul_f32_e64 v28, |v29|, s33
	v_exp_f32_e32 v28, v28
	v_fmac_f32_e32 v38, 0x3377d1cf, v36
	v_fmac_f32_e32 v38, 0x3f317217, v36
	v_add_f32_e32 v28, 1.0, v28
	v_mov_b32_e32 v30, v38
	v_min_f32_e32 v29, 0, v29
	v_log_f32_e32 v38, v28
	v_sub_f32_e32 v28, v37, v30
	ds_read_b128 v[30:33], v0 offset:704
	v_fmamk_f32 v27, v27, 0x3d800000, v26
	v_mul_f32_e32 v34, 0x3f317217, v38
	v_fma_f32 v39, v38, s35, -v34
	ds_read_b128 v[34:37], v0 offset:720
	s_waitcnt lgkmcnt(1)
	v_mul_f32_e32 v31, v15, v31
	v_fmac_f32_e32 v31, v12, v30
	v_fmac_f32_e32 v31, v14, v32
	v_fmac_f32_e32 v31, v17, v33
	v_add_f32_e32 v40, v19, v31
	s_waitcnt lgkmcnt(0)
	v_mul_f32_e32 v35, v13, v35
	ds_read_b128 v[30:33], v0 offset:736
	v_fmac_f32_e32 v35, v11, v34
	v_fmac_f32_e32 v35, v9, v36
	v_fmac_f32_e32 v35, v16, v37
	v_add_f32_e32 v40, v40, v35
	ds_read_b128 v[34:37], v0 offset:752
	s_waitcnt lgkmcnt(1)
	v_mul_f32_e32 v31, v7, v31
	v_fmac_f32_e32 v31, v3, v30
	v_fmac_f32_e32 v31, v5, v32
	v_fmac_f32_e32 v31, v10, v33
	v_add_f32_e32 v30, v40, v31
	s_waitcnt lgkmcnt(0)
	v_mul_f32_e32 v31, v4, v35
	v_fmac_f32_e32 v31, v2, v34
	v_fmac_f32_e32 v31, v6, v36
	v_fmac_f32_e32 v31, v8, v37
	v_add_f32_e32 v30, v30, v31
	v_mul_f32_e64 v31, |v30|, s33
	v_exp_f32_e32 v31, v31
	v_fmac_f32_e32 v39, 0x3377d1cf, v38
	v_fmac_f32_e32 v39, 0x3f317217, v38
	v_add_f32_e32 v31, 1.0, v31
	v_mov_b32_e32 v32, v39
	v_sub_f32_e32 v29, v29, v32
	v_log_f32_e32 v38, v31
	v_min_f32_e32 v39, 0, v30
	ds_read_b128 v[30:33], v0 offset:768
	v_fmamk_f32 v28, v28, 0x3d800000, v27
	v_mul_f32_e32 v34, 0x3f317217, v38
	v_fma_f32 v40, v38, s35, -v34
	ds_read_b128 v[34:37], v0 offset:784
	s_waitcnt lgkmcnt(1)
	v_mul_f32_e32 v31, v15, v31
	v_fmac_f32_e32 v31, v12, v30
	v_fmac_f32_e32 v31, v14, v32
	v_fmac_f32_e32 v31, v17, v33
	v_add_f32_e32 v41, v19, v31
	s_waitcnt lgkmcnt(0)
; #define LAS __attribute__((address_space(3)))
; __device__ __forceinline__ void gla_bcum(KArgs a, int tid, int t0, int h, LAS float* segtot, LAS float* glrs, float (&bc)[32], float& tot) {
;     ...
;     float run = 0.f;
; #pragma unroll
;     for (int r = 0; r < 32; ++r) { const LAS f32x4* gp = (const LAS f32x4*)(glrs + (seg * 32 + r) * 16);
;         float z = bias;
; #pragma unroll
;         for (int q = 0; q < 4; ++q) { const f32x4 g = gp[q]; z += g[0] * w2r[4 * q] + g[1] * w2r[4 * q + 1] + g[2] * w2r[4 * q + 2] + g[3] * w2r[4 * q + 3]; }
;         const float la = (fminf(z, 0.f) - __logf(1.0f + __expf(-fabsf(z)))) * (1.0f / 16.0f);
;         run += la; bc[r] = run; }
	v_mul_f32_e32 v35, v13, v35
	ds_read_b128 v[30:33], v0 offset:800
	v_fmac_f32_e32 v35, v11, v34
	v_fmac_f32_e32 v35, v9, v36
	v_fmac_f32_e32 v35, v16, v37
	v_add_f32_e32 v41, v41, v35
	ds_read_b128 v[34:37], v0 offset:816
	s_waitcnt lgkmcnt(1)
	v_mul_f32_e32 v31, v7, v31
	v_fmac_f32_e32 v31, v3, v30
	v_fmac_f32_e32 v31, v5, v32
	v_fmac_f32_e32 v31, v10, v33
	v_add_f32_e32 v30, v41, v31
	s_waitcnt lgkmcnt(0)
	v_mul_f32_e32 v31, v4, v35
	v_fmac_f32_e32 v31, v2, v34
	v_fmac_f32_e32 v31, v6, v36
	v_fmac_f32_e32 v31, v8, v37
	v_add_f32_e32 v31, v30, v31
	v_mul_f32_e64 v30, |v31|, s33
	v_exp_f32_e32 v30, v30
	v_fmac_f32_e32 v40, 0x3377d1cf, v38
	v_fmac_f32_e32 v40, 0x3f317217, v38
	v_add_f32_e32 v30, 1.0, v30
	v_mov_b32_e32 v32, v40
	v_min_f32_e32 v31, 0, v31
	v_log_f32_e32 v40, v30
	v_sub_f32_e32 v30, v39, v32
	ds_read_b128 v[32:35], v0 offset:832
	v_fmamk_f32 v29, v29, 0x3d800000, v28
	v_mul_f32_e32 v36, 0x3f317217, v40
	v_fma_f32 v41, v40, s35, -v36
	ds_read_b128 v[36:39], v0 offset:848
	s_waitcnt lgkmcnt(1)
	v_mul_f32_e32 v33, v15, v33
	v_fmac_f32_e32 v33, v12, v32
	v_fmac_f32_e32 v33, v14, v34
	v_fmac_f32_e32 v33, v17, v35
	v_add_f32_e32 v42, v19, v33
	s_waitcnt lgkmcnt(0)
	v_mul_f32_e32 v37, v13, v37
	ds_read_b128 v[32:35], v0 offset:864
	v_fmac_f32_e32 v37, v11, v36
	v_fmac_f32_e32 v37, v9, v38
	v_fmac_f32_e32 v37, v16, v39
	v_add_f32_e32 v42, v42, v37
	ds_read_b128 v[36:39], v0 offset:880
	s_waitcnt lgkmcnt(1)
	v_mul_f32_e32 v33, v7, v33
	v_fmac_f32_e32 v33, v3, v32
	v_fmac_f32_e32 v33, v5, v34
	v_fmac_f32_e32 v33, v10, v35
	v_add_f32_e32 v32, v42, v33
	s_waitcnt lgkmcnt(0)
	v_mul_f32_e32 v33, v4, v37
	v_fmac_f32_e32 v33, v2, v36
	v_fmac_f32_e32 v33, v6, v38
	v_fmac_f32_e32 v33, v8, v39
	v_add_f32_e32 v32, v32, v33
	v_mul_f32_e64 v33, |v32|, s33
	v_exp_f32_e32 v33, v33
	v_fmac_f32_e32 v41, 0x3377d1cf, v40
	v_fmac_f32_e32 v41, 0x3f317217, v40
	v_add_f32_e32 v33, 1.0, v33
	v_mov_b32_e32 v34, v41
	v_sub_f32_e32 v31, v31, v34
	v_log_f32_e32 v40, v33
	v_min_f32_e32 v41, 0, v32
	ds_read_b128 v[32:35], v0 offset:896
	v_fmamk_f32 v30, v30, 0x3d800000, v29
	v_mul_f32_e32 v36, 0x3f317217, v40
	v_fma_f32 v42, v40, s35, -v36
	ds_read_b128 v[36:39], v0 offset:912
	s_waitcnt lgkmcnt(1)
	v_mul_f32_e32 v33, v15, v33
	v_fmac_f32_e32 v33, v12, v32
	v_fmac_f32_e32 v33, v14, v34
	v_fmac_f32_e32 v33, v17, v35
	v_add_f32_e32 v43, v19, v33
	s_waitcnt lgkmcnt(0)
	v_mul_f32_e32 v37, v13, v37
	ds_read_b128 v[32:35], v0 offset:928
	v_fmac_f32_e32 v37, v11, v36
	v_fmac_f32_e32 v37, v9, v38
	v_fmac_f32_e32 v37, v16, v39
	v_add_f32_e32 v43, v43, v37
	ds_read_b128 v[36:39], v0 offset:944
	s_waitcnt lgkmcnt(1)
	v_mul_f32_e32 v33, v7, v33
	v_fmac_f32_e32 v33, v3, v32
	v_fmac_f32_e32 v33, v5, v34
	v_fmac_f32_e32 v33, v10, v35
	v_add_f32_e32 v32, v43, v33
	s_waitcnt lgkmcnt(0)
	v_mul_f32_e32 v33, v4, v37
	v_fmac_f32_e32 v33, v2, v36
	v_fmac_f32_e32 v33, v6, v38
	v_fmac_f32_e32 v33, v8, v39
	v_add_f32_e32 v33, v32, v33
	v_mul_f32_e64 v32, |v33|, s33
	v_exp_f32_e32 v32, v32
	v_fmac_f32_e32 v42, 0x3377d1cf, v40
	v_fmac_f32_e32 v42, 0x3f317217, v40
	v_add_f32_e32 v32, 1.0, v32
	v_mov_b32_e32 v34, v42
	v_min_f32_e32 v33, 0, v33
	v_log_f32_e32 v42, v32
	v_sub_f32_e32 v32, v41, v34
	ds_read_b128 v[34:37], v0 offset:960
	v_fmamk_f32 v31, v31, 0x3d800000, v30
	v_mul_f32_e32 v38, 0x3f317217, v42
	v_fma_f32 v43, v42, s35, -v38
	ds_read_b128 v[38:41], v0 offset:976
	s_waitcnt lgkmcnt(1)
	v_mul_f32_e32 v35, v15, v35
	v_fmac_f32_e32 v35, v12, v34
	v_fmac_f32_e32 v35, v14, v36
	v_fmac_f32_e32 v35, v17, v37
	v_add_f32_e32 v44, v19, v35
	s_waitcnt lgkmcnt(0)
	v_mul_f32_e32 v39, v13, v39
	ds_read_b128 v[34:37], v0 offset:992
	v_fmac_f32_e32 v39, v11, v38
	v_fmac_f32_e32 v39, v9, v40
	v_fmac_f32_e32 v39, v16, v41
	v_add_f32_e32 v44, v44, v39
	ds_read_b128 v[38:41], v0 offset:1008
	s_waitcnt lgkmcnt(1)
	v_mul_f32_e32 v35, v7, v35
	v_fmac_f32_e32 v35, v3, v34
	v_fmac_f32_e32 v35, v5, v36
	v_fmac_f32_e32 v35, v10, v37
	v_add_f32_e32 v34, v44, v35
	s_waitcnt lgkmcnt(0)
	v_mul_f32_e32 v35, v4, v39
	v_fmac_f32_e32 v35, v2, v38
	v_fmac_f32_e32 v35, v6, v40
	v_fmac_f32_e32 v35, v8, v41
	v_add_f32_e32 v34, v34, v35
	v_mul_f32_e64 v35, |v34|, s33
	v_exp_f32_e32 v35, v35
	v_fmac_f32_e32 v43, 0x3377d1cf, v42
	v_fmac_f32_e32 v43, 0x3f317217, v42
	v_add_f32_e32 v35, 1.0, v35
	v_mov_b32_e32 v36, v43
	v_sub_f32_e32 v33, v33, v36
	v_log_f32_e32 v42, v35
	v_min_f32_e32 v43, 0, v34
	ds_read_b128 v[34:37], v0 offset:1024
	v_fmamk_f32 v32, v32, 0x3d800000, v31
	v_mul_f32_e32 v38, 0x3f317217, v42
	v_fma_f32 v44, v42, s35, -v38
	ds_read_b128 v[38:41], v0 offset:1040
	s_waitcnt lgkmcnt(1)
	v_mul_f32_e32 v35, v15, v35
	v_fmac_f32_e32 v35, v12, v34
	v_fmac_f32_e32 v35, v14, v36
	v_fmac_f32_e32 v35, v17, v37
	v_add_f32_e32 v45, v19, v35
	s_waitcnt lgkmcnt(0)
	v_mul_f32_e32 v39, v13, v39
	ds_read_b128 v[34:37], v0 offset:1056
	v_fmac_f32_e32 v39, v11, v38
	v_fmac_f32_e32 v39, v9, v40
	v_fmac_f32_e32 v39, v16, v41
	v_add_f32_e32 v45, v45, v39
	ds_read_b128 v[38:41], v0 offset:1072
	s_waitcnt lgkmcnt(1)
	v_mul_f32_e32 v35, v7, v35
	v_fmac_f32_e32 v35, v3, v34
	v_fmac_f32_e32 v35, v5, v36
	v_fmac_f32_e32 v35, v10, v37
	v_add_f32_e32 v34, v45, v35
	s_waitcnt lgkmcnt(0)
	v_mul_f32_e32 v35, v4, v39
	v_fmac_f32_e32 v35, v2, v38
	v_fmac_f32_e32 v35, v6, v40
	v_fmac_f32_e32 v35, v8, v41
	v_add_f32_e32 v35, v34, v35
	v_mul_f32_e64 v34, |v35|, s33
	v_exp_f32_e32 v34, v34
	v_fmac_f32_e32 v44, 0x3377d1cf, v42
	v_fmac_f32_e32 v44, 0x3f317217, v42
	v_add_f32_e32 v34, 1.0, v34
	v_mov_b32_e32 v36, v44
	v_min_f32_e32 v35, 0, v35
	v_log_f32_e32 v44, v34
	v_sub_f32_e32 v34, v43, v36
	ds_read_b128 v[36:39], v0 offset:1088
	v_fmamk_f32 v33, v33, 0x3d800000, v32
	v_mul_f32_e32 v40, 0x3f317217, v44
	v_fma_f32 v45, v44, s35, -v40
	ds_read_b128 v[40:43], v0 offset:1104
	s_waitcnt lgkmcnt(1)
; #define LAS __attribute__((address_space(3)))
; __device__ __forceinline__ void gla_bcum(KArgs a, int tid, int t0, int h, LAS float* segtot, LAS float* glrs, float (&bc)[32], float& tot) {
;     ...
;     for (int r = 0; r < 32; ++r) { const LAS f32x4* gp = (const LAS f32x4*)(glrs + (seg * 32 + r) * 16);
;         float z = bias;
; #pragma unroll
;         for (int q = 0; q < 4; ++q) { const f32x4 g = gp[q]; z += g[0] * w2r[4 * q] + g[1] * w2r[4 * q + 1] + g[2] * w2r[4 * q + 2] + g[3] * w2r[4 * q + 3]; }
;         const float la = (fminf(z, 0.f) - __logf(1.0f + __expf(-fabsf(z)))) * (1.0f / 16.0f);
;         run += la; bc[r] = run; }
	v_mul_f32_e32 v37, v15, v37
	v_fmac_f32_e32 v37, v12, v36
	v_fmac_f32_e32 v37, v14, v38
	v_fmac_f32_e32 v37, v17, v39
	v_add_f32_e32 v46, v19, v37
	s_waitcnt lgkmcnt(0)
	v_mul_f32_e32 v41, v13, v41
	ds_read_b128 v[36:39], v0 offset:1120
	v_fmac_f32_e32 v41, v11, v40
	v_fmac_f32_e32 v41, v9, v42
	v_fmac_f32_e32 v41, v16, v43
	v_add_f32_e32 v46, v46, v41
	ds_read_b128 v[40:43], v0 offset:1136
	s_waitcnt lgkmcnt(1)
	v_mul_f32_e32 v37, v7, v37
	v_fmac_f32_e32 v37, v3, v36
	v_fmac_f32_e32 v37, v5, v38
	v_fmac_f32_e32 v37, v10, v39
	v_add_f32_e32 v36, v46, v37
	s_waitcnt lgkmcnt(0)
	v_mul_f32_e32 v37, v4, v41
	v_fmac_f32_e32 v37, v2, v40
	v_fmac_f32_e32 v37, v6, v42
	v_fmac_f32_e32 v37, v8, v43
	v_add_f32_e32 v36, v36, v37
	v_mul_f32_e64 v37, |v36|, s33
	v_exp_f32_e32 v37, v37
	v_fmac_f32_e32 v45, 0x3377d1cf, v44
	v_fmac_f32_e32 v45, 0x3f317217, v44
	v_add_f32_e32 v37, 1.0, v37
	v_mov_b32_e32 v38, v45
	v_sub_f32_e32 v35, v35, v38
	v_log_f32_e32 v44, v37
	v_min_f32_e32 v45, 0, v36
	ds_read_b128 v[36:39], v0 offset:1152
	v_fmamk_f32 v34, v34, 0x3d800000, v33
	v_mul_f32_e32 v40, 0x3f317217, v44
	v_fma_f32 v46, v44, s35, -v40
	ds_read_b128 v[40:43], v0 offset:1168
	s_waitcnt lgkmcnt(1)
	v_mul_f32_e32 v37, v15, v37
	v_fmac_f32_e32 v37, v12, v36
	v_fmac_f32_e32 v37, v14, v38
	v_fmac_f32_e32 v37, v17, v39
	v_add_f32_e32 v47, v19, v37
	s_waitcnt lgkmcnt(0)
	v_mul_f32_e32 v41, v13, v41
	ds_read_b128 v[36:39], v0 offset:1184
	v_fmac_f32_e32 v41, v11, v40
	v_fmac_f32_e32 v41, v9, v42
	v_fmac_f32_e32 v41, v16, v43
	v_add_f32_e32 v47, v47, v41
	ds_read_b128 v[40:43], v0 offset:1200
	s_waitcnt lgkmcnt(1)
	v_mul_f32_e32 v37, v7, v37
	v_fmac_f32_e32 v37, v3, v36
	v_fmac_f32_e32 v37, v5, v38
	v_fmac_f32_e32 v37, v10, v39
	v_add_f32_e32 v36, v47, v37
	s_waitcnt lgkmcnt(0)
	v_mul_f32_e32 v37, v4, v41
	v_fmac_f32_e32 v37, v2, v40
	v_fmac_f32_e32 v37, v6, v42
	v_fmac_f32_e32 v37, v8, v43
	v_add_f32_e32 v37, v36, v37
	v_mul_f32_e64 v36, |v37|, s33
	v_exp_f32_e32 v36, v36
	v_fmac_f32_e32 v46, 0x3377d1cf, v44
	v_fmac_f32_e32 v46, 0x3f317217, v44
	v_add_f32_e32 v36, 1.0, v36
	v_mov_b32_e32 v38, v46
	v_min_f32_e32 v37, 0, v37
	v_log_f32_e32 v46, v36
	v_sub_f32_e32 v36, v45, v38
	ds_read_b128 v[38:41], v0 offset:1216
	v_fmamk_f32 v35, v35, 0x3d800000, v34
	v_mul_f32_e32 v42, 0x3f317217, v46
	v_fma_f32 v47, v46, s35, -v42
	ds_read_b128 v[42:45], v0 offset:1232
	s_waitcnt lgkmcnt(1)
	v_mul_f32_e32 v39, v15, v39
	v_fmac_f32_e32 v39, v12, v38
	v_fmac_f32_e32 v39, v14, v40
	v_fmac_f32_e32 v39, v17, v41
	v_add_f32_e32 v48, v19, v39
	s_waitcnt lgkmcnt(0)
	v_mul_f32_e32 v43, v13, v43
	ds_read_b128 v[38:41], v0 offset:1248
	v_fmac_f32_e32 v43, v11, v42
	v_fmac_f32_e32 v43, v9, v44
	v_fmac_f32_e32 v43, v16, v45
	v_add_f32_e32 v48, v48, v43
	ds_read_b128 v[42:45], v0 offset:1264
	s_waitcnt lgkmcnt(1)
	v_mul_f32_e32 v39, v7, v39
	v_fmac_f32_e32 v39, v3, v38
	v_fmac_f32_e32 v39, v5, v40
	v_fmac_f32_e32 v39, v10, v41
	v_add_f32_e32 v38, v48, v39
	s_waitcnt lgkmcnt(0)
	v_mul_f32_e32 v39, v4, v43
	v_fmac_f32_e32 v39, v2, v42
	v_fmac_f32_e32 v39, v6, v44
	v_fmac_f32_e32 v39, v8, v45
	v_add_f32_e32 v38, v38, v39
	v_mul_f32_e64 v39, |v38|, s33
	v_exp_f32_e32 v39, v39
	v_fmac_f32_e32 v47, 0x3377d1cf, v46
	v_fmac_f32_e32 v47, 0x3f317217, v46
	v_add_f32_e32 v39, 1.0, v39
	v_mov_b32_e32 v40, v47
	v_sub_f32_e32 v37, v37, v40
	v_log_f32_e32 v46, v39
	v_min_f32_e32 v47, 0, v38
	ds_read_b128 v[38:41], v0 offset:1280
	v_fmamk_f32 v36, v36, 0x3d800000, v35
	v_mul_f32_e32 v42, 0x3f317217, v46
	v_fma_f32 v48, v46, s35, -v42
	ds_read_b128 v[42:45], v0 offset:1296
	s_waitcnt lgkmcnt(1)
	v_mul_f32_e32 v39, v15, v39
	v_fmac_f32_e32 v39, v12, v38
	v_fmac_f32_e32 v39, v14, v40
	v_fmac_f32_e32 v39, v17, v41
	v_add_f32_e32 v49, v19, v39
	s_waitcnt lgkmcnt(0)
	v_mul_f32_e32 v43, v13, v43
	ds_read_b128 v[38:41], v0 offset:1312
	v_fmac_f32_e32 v43, v11, v42
	v_fmac_f32_e32 v43, v9, v44
	v_fmac_f32_e32 v43, v16, v45
	v_add_f32_e32 v49, v49, v43
	ds_read_b128 v[42:45], v0 offset:1328
	s_waitcnt lgkmcnt(1)
	v_mul_f32_e32 v39, v7, v39
	v_fmac_f32_e32 v39, v3, v38
	v_fmac_f32_e32 v39, v5, v40
	v_fmac_f32_e32 v39, v10, v41
	v_add_f32_e32 v38, v49, v39
	s_waitcnt lgkmcnt(0)
	v_mul_f32_e32 v39, v4, v43
	v_fmac_f32_e32 v39, v2, v42
	v_fmac_f32_e32 v39, v6, v44
	v_fmac_f32_e32 v39, v8, v45
	v_add_f32_e32 v39, v38, v39
	v_mul_f32_e64 v38, |v39|, s33
	v_exp_f32_e32 v38, v38
	v_fmac_f32_e32 v48, 0x3377d1cf, v46
	v_fmac_f32_e32 v48, 0x3f317217, v46
	v_add_f32_e32 v38, 1.0, v38
	v_mov_b32_e32 v40, v48
	v_min_f32_e32 v39, 0, v39
	v_log_f32_e32 v48, v38
	v_sub_f32_e32 v38, v47, v40
	ds_read_b128 v[40:43], v0 offset:1344
	v_fmamk_f32 v37, v37, 0x3d800000, v36
	v_mul_f32_e32 v44, 0x3f317217, v48
	v_fma_f32 v49, v48, s35, -v44
	ds_read_b128 v[44:47], v0 offset:1360
	s_waitcnt lgkmcnt(1)
	v_mul_f32_e32 v41, v15, v41
	v_fmac_f32_e32 v41, v12, v40
	v_fmac_f32_e32 v41, v14, v42
	v_fmac_f32_e32 v41, v17, v43
	v_add_f32_e32 v50, v19, v41
	s_waitcnt lgkmcnt(0)
	v_mul_f32_e32 v45, v13, v45
	ds_read_b128 v[40:43], v0 offset:1376
	v_fmac_f32_e32 v45, v11, v44
	v_fmac_f32_e32 v45, v9, v46
	v_fmac_f32_e32 v45, v16, v47
	v_add_f32_e32 v50, v50, v45
	ds_read_b128 v[44:47], v0 offset:1392
	s_waitcnt lgkmcnt(1)
	v_mul_f32_e32 v41, v7, v41
	v_fmac_f32_e32 v41, v3, v40
	v_fmac_f32_e32 v41, v5, v42
	v_fmac_f32_e32 v41, v10, v43
	v_add_f32_e32 v40, v50, v41
	s_waitcnt lgkmcnt(0)
; #define LAS __attribute__((address_space(3)))
; __device__ __forceinline__ void gla_bcum(KArgs a, int tid, int t0, int h, LAS float* segtot, LAS float* glrs, float (&bc)[32], float& tot) {
;     ...
;     for (int r = 0; r < 32; ++r) { const LAS f32x4* gp = (const LAS f32x4*)(glrs + (seg * 32 + r) * 16);
;         float z = bias;
; #pragma unroll
;         for (int q = 0; q < 4; ++q) { const f32x4 g = gp[q]; z += g[0] * w2r[4 * q] + g[1] * w2r[4 * q + 1] + g[2] * w2r[4 * q + 2] + g[3] * w2r[4 * q + 3]; }
;         const float la = (fminf(z, 0.f) - __logf(1.0f + __expf(-fabsf(z)))) * (1.0f / 16.0f);
;         run += la; bc[r] = run; }
	v_mul_f32_e32 v41, v4, v45
	v_fmac_f32_e32 v41, v2, v44
	v_fmac_f32_e32 v41, v6, v46
	v_fmac_f32_e32 v41, v8, v47
	v_add_f32_e32 v40, v40, v41
	v_mul_f32_e64 v41, |v40|, s33
	v_exp_f32_e32 v41, v41
	v_fmac_f32_e32 v49, 0x3377d1cf, v48
	v_fmac_f32_e32 v49, 0x3f317217, v48
	v_add_f32_e32 v41, 1.0, v41
	v_mov_b32_e32 v42, v49
	v_sub_f32_e32 v39, v39, v42
	v_log_f32_e32 v48, v41
	v_min_f32_e32 v49, 0, v40
	ds_read_b128 v[40:43], v0 offset:1408
	v_fmamk_f32 v38, v38, 0x3d800000, v37
	v_mul_f32_e32 v44, 0x3f317217, v48
	v_fma_f32 v50, v48, s35, -v44
	ds_read_b128 v[44:47], v0 offset:1424
	s_waitcnt lgkmcnt(1)
	v_mul_f32_e32 v41, v15, v41
	v_fmac_f32_e32 v41, v12, v40
	v_fmac_f32_e32 v41, v14, v42
	v_fmac_f32_e32 v41, v17, v43
	v_add_f32_e32 v51, v19, v41
	s_waitcnt lgkmcnt(0)
	v_mul_f32_e32 v45, v13, v45
	ds_read_b128 v[40:43], v0 offset:1440
	v_fmac_f32_e32 v45, v11, v44
	v_fmac_f32_e32 v45, v9, v46
	v_fmac_f32_e32 v45, v16, v47
	v_add_f32_e32 v51, v51, v45
	ds_read_b128 v[44:47], v0 offset:1456
	s_waitcnt lgkmcnt(1)
	v_mul_f32_e32 v41, v7, v41
	v_fmac_f32_e32 v41, v3, v40
	v_fmac_f32_e32 v41, v5, v42
	v_fmac_f32_e32 v41, v10, v43
	v_add_f32_e32 v40, v51, v41
	s_waitcnt lgkmcnt(0)
	v_mul_f32_e32 v41, v4, v45
	v_fmac_f32_e32 v41, v2, v44
	v_fmac_f32_e32 v41, v6, v46
	v_fmac_f32_e32 v41, v8, v47
	v_add_f32_e32 v41, v40, v41
	v_mul_f32_e64 v40, |v41|, s33
	v_exp_f32_e32 v40, v40
	v_fmac_f32_e32 v50, 0x3377d1cf, v48
	v_fmac_f32_e32 v50, 0x3f317217, v48
	v_add_f32_e32 v40, 1.0, v40
	v_mov_b32_e32 v42, v50
	v_min_f32_e32 v41, 0, v41
	v_log_f32_e32 v50, v40
	v_sub_f32_e32 v40, v49, v42
	ds_read_b128 v[42:45], v0 offset:1472
	v_fmamk_f32 v39, v39, 0x3d800000, v38
	v_mul_f32_e32 v46, 0x3f317217, v50
	v_fma_f32 v51, v50, s35, -v46
	ds_read_b128 v[46:49], v0 offset:1488
	s_waitcnt lgkmcnt(1)
	v_mul_f32_e32 v43, v15, v43
	v_fmac_f32_e32 v43, v12, v42
	v_fmac_f32_e32 v43, v14, v44
	v_fmac_f32_e32 v43, v17, v45
	v_add_f32_e32 v52, v19, v43
	s_waitcnt lgkmcnt(0)
	v_mul_f32_e32 v47, v13, v47
	ds_read_b128 v[42:45], v0 offset:1504
	v_fmac_f32_e32 v47, v11, v46
	v_fmac_f32_e32 v47, v9, v48
	v_fmac_f32_e32 v47, v16, v49
	v_add_f32_e32 v52, v52, v47
	ds_read_b128 v[46:49], v0 offset:1520
	s_waitcnt lgkmcnt(1)
	v_mul_f32_e32 v43, v7, v43
	v_fmac_f32_e32 v43, v3, v42
	v_fmac_f32_e32 v43, v5, v44
	v_fmac_f32_e32 v43, v10, v45
	v_add_f32_e32 v42, v52, v43
	s_waitcnt lgkmcnt(0)
	v_mul_f32_e32 v43, v4, v47
	v_fmac_f32_e32 v43, v2, v46
	v_fmac_f32_e32 v43, v6, v48
	v_fmac_f32_e32 v43, v8, v49
	v_add_f32_e32 v42, v42, v43
	v_mul_f32_e64 v43, |v42|, s33
	v_exp_f32_e32 v43, v43
	v_fmac_f32_e32 v51, 0x3377d1cf, v50
	v_fmac_f32_e32 v51, 0x3f317217, v50
	v_add_f32_e32 v43, 1.0, v43
	v_mov_b32_e32 v44, v51
	v_sub_f32_e32 v41, v41, v44
	v_log_f32_e32 v50, v43
	v_min_f32_e32 v51, 0, v42
	ds_read_b128 v[42:45], v0 offset:1536
	v_fmamk_f32 v40, v40, 0x3d800000, v39
	v_mul_f32_e32 v46, 0x3f317217, v50
	v_fma_f32 v52, v50, s35, -v46
	ds_read_b128 v[46:49], v0 offset:1552
	s_waitcnt lgkmcnt(1)
	v_mul_f32_e32 v43, v15, v43
	v_fmac_f32_e32 v43, v12, v42
	v_fmac_f32_e32 v43, v14, v44
	v_fmac_f32_e32 v43, v17, v45
	v_add_f32_e32 v53, v19, v43
	s_waitcnt lgkmcnt(0)
	v_mul_f32_e32 v47, v13, v47
	ds_read_b128 v[42:45], v0 offset:1568
	v_fmac_f32_e32 v47, v11, v46
	v_fmac_f32_e32 v47, v9, v48
	v_fmac_f32_e32 v47, v16, v49
	v_add_f32_e32 v53, v53, v47
	ds_read_b128 v[46:49], v0 offset:1584
	s_waitcnt lgkmcnt(1)
	v_mul_f32_e32 v43, v7, v43
	v_fmac_f32_e32 v43, v3, v42
	v_fmac_f32_e32 v43, v5, v44
	v_fmac_f32_e32 v43, v10, v45
	v_add_f32_e32 v42, v53, v43
	s_waitcnt lgkmcnt(0)
	v_mul_f32_e32 v43, v4, v47
	v_fmac_f32_e32 v43, v2, v46
	v_fmac_f32_e32 v43, v6, v48
	v_fmac_f32_e32 v43, v8, v49
	v_add_f32_e32 v43, v42, v43
	v_mul_f32_e64 v42, |v43|, s33
	v_exp_f32_e32 v42, v42
	v_fmac_f32_e32 v52, 0x3377d1cf, v50
	v_fmac_f32_e32 v52, 0x3f317217, v50
	v_add_f32_e32 v42, 1.0, v42
	v_mov_b32_e32 v44, v52
	v_min_f32_e32 v43, 0, v43
	v_log_f32_e32 v52, v42
	v_sub_f32_e32 v42, v51, v44
	ds_read_b128 v[44:47], v0 offset:1600
	v_fmamk_f32 v41, v41, 0x3d800000, v40
	v_mul_f32_e32 v48, 0x3f317217, v52
	v_fma_f32 v53, v52, s35, -v48
	ds_read_b128 v[48:51], v0 offset:1616
	s_waitcnt lgkmcnt(1)
	v_mul_f32_e32 v45, v15, v45
	v_fmac_f32_e32 v45, v12, v44
	v_fmac_f32_e32 v45, v14, v46
	v_fmac_f32_e32 v45, v17, v47
	v_add_f32_e32 v54, v19, v45
	s_waitcnt lgkmcnt(0)
	v_mul_f32_e32 v49, v13, v49
	ds_read_b128 v[44:47], v0 offset:1632
	v_fmac_f32_e32 v49, v11, v48
	v_fmac_f32_e32 v49, v9, v50
	v_fmac_f32_e32 v49, v16, v51
	v_add_f32_e32 v54, v54, v49
	ds_read_b128 v[48:51], v0 offset:1648
	s_waitcnt lgkmcnt(1)
	v_mul_f32_e32 v45, v7, v45
	v_fmac_f32_e32 v45, v3, v44
	v_fmac_f32_e32 v45, v5, v46
	v_fmac_f32_e32 v45, v10, v47
	v_add_f32_e32 v44, v54, v45
	s_waitcnt lgkmcnt(0)
	v_mul_f32_e32 v45, v4, v49
	v_fmac_f32_e32 v45, v2, v48
	v_fmac_f32_e32 v45, v6, v50
	v_fmac_f32_e32 v45, v8, v51
	v_add_f32_e32 v44, v44, v45
	v_mul_f32_e64 v45, |v44|, s33
	v_exp_f32_e32 v45, v45
	v_fmac_f32_e32 v53, 0x3377d1cf, v52
	v_fmac_f32_e32 v53, 0x3f317217, v52
	v_add_f32_e32 v45, 1.0, v45
	v_mov_b32_e32 v46, v53
	v_sub_f32_e32 v43, v43, v46
	v_log_f32_e32 v52, v45
	v_min_f32_e32 v53, 0, v44
	ds_read_b128 v[44:47], v0 offset:1664
	v_fmamk_f32 v42, v42, 0x3d800000, v41
	v_mul_f32_e32 v48, 0x3f317217, v52
	v_fma_f32 v54, v52, s35, -v48
	ds_read_b128 v[48:51], v0 offset:1680
	s_waitcnt lgkmcnt(1)
	v_mul_f32_e32 v45, v15, v45
	v_fmac_f32_e32 v45, v12, v44
	v_fmac_f32_e32 v45, v14, v46
	v_fmac_f32_e32 v45, v17, v47
	v_add_f32_e32 v55, v19, v45
	s_waitcnt lgkmcnt(0)
; #define LAS __attribute__((address_space(3)))
; __device__ __forceinline__ void gla_bcum(KArgs a, int tid, int t0, int h, LAS float* segtot, LAS float* glrs, float (&bc)[32], float& tot) {
;     ...
;     for (int r = 0; r < 32; ++r) { const LAS f32x4* gp = (const LAS f32x4*)(glrs + (seg * 32 + r) * 16);
;         float z = bias;
; #pragma unroll
;         for (int q = 0; q < 4; ++q) { const f32x4 g = gp[q]; z += g[0] * w2r[4 * q] + g[1] * w2r[4 * q + 1] + g[2] * w2r[4 * q + 2] + g[3] * w2r[4 * q + 3]; }
;         const float la = (fminf(z, 0.f) - __logf(1.0f + __expf(-fabsf(z)))) * (1.0f / 16.0f);
;         run += la; bc[r] = run; }
	v_mul_f32_e32 v49, v13, v49
	ds_read_b128 v[44:47], v0 offset:1696
	v_fmac_f32_e32 v49, v11, v48
	v_fmac_f32_e32 v49, v9, v50
	v_fmac_f32_e32 v49, v16, v51
	v_add_f32_e32 v55, v55, v49
	ds_read_b128 v[48:51], v0 offset:1712
	s_waitcnt lgkmcnt(1)
	v_mul_f32_e32 v45, v7, v45
	v_fmac_f32_e32 v45, v3, v44
	v_fmac_f32_e32 v45, v5, v46
	v_fmac_f32_e32 v45, v10, v47
	v_add_f32_e32 v44, v55, v45
	s_waitcnt lgkmcnt(0)
	v_mul_f32_e32 v45, v4, v49
	v_fmac_f32_e32 v45, v2, v48
	v_fmac_f32_e32 v45, v6, v50
	v_fmac_f32_e32 v45, v8, v51
	v_add_f32_e32 v45, v44, v45
	v_mul_f32_e64 v44, |v45|, s33
	v_exp_f32_e32 v44, v44
	v_fmac_f32_e32 v54, 0x3377d1cf, v52
	v_fmac_f32_e32 v54, 0x3f317217, v52
	v_add_f32_e32 v44, 1.0, v44
	v_mov_b32_e32 v46, v54
	v_min_f32_e32 v45, 0, v45
	v_log_f32_e32 v54, v44
	v_sub_f32_e32 v44, v53, v46
	ds_read_b128 v[46:49], v0 offset:1728
	v_fmamk_f32 v43, v43, 0x3d800000, v42
	v_mul_f32_e32 v50, 0x3f317217, v54
	v_fma_f32 v55, v54, s35, -v50
	ds_read_b128 v[50:53], v0 offset:1744
	s_waitcnt lgkmcnt(1)
	v_mul_f32_e32 v47, v15, v47
	v_fmac_f32_e32 v47, v12, v46
	v_fmac_f32_e32 v47, v14, v48
	v_fmac_f32_e32 v47, v17, v49
	v_add_f32_e32 v56, v19, v47
	s_waitcnt lgkmcnt(0)
	v_mul_f32_e32 v51, v13, v51
	ds_read_b128 v[46:49], v0 offset:1760
	v_fmac_f32_e32 v51, v11, v50
	v_fmac_f32_e32 v51, v9, v52
	v_fmac_f32_e32 v51, v16, v53
	v_add_f32_e32 v56, v56, v51
	ds_read_b128 v[50:53], v0 offset:1776
	s_waitcnt lgkmcnt(1)
	v_mul_f32_e32 v47, v7, v47
	v_fmac_f32_e32 v47, v3, v46
	v_fmac_f32_e32 v47, v5, v48
	v_fmac_f32_e32 v47, v10, v49
	v_add_f32_e32 v46, v56, v47
	s_waitcnt lgkmcnt(0)
	v_mul_f32_e32 v47, v4, v51
	v_fmac_f32_e32 v47, v2, v50
	v_fmac_f32_e32 v47, v6, v52
	v_fmac_f32_e32 v47, v8, v53
	v_add_f32_e32 v46, v46, v47
	v_mul_f32_e64 v47, |v46|, s33
	v_exp_f32_e32 v47, v47
	v_fmac_f32_e32 v55, 0x3377d1cf, v54
	v_fmac_f32_e32 v55, 0x3f317217, v54
	v_add_f32_e32 v47, 1.0, v47
	v_mov_b32_e32 v48, v55
	v_sub_f32_e32 v45, v45, v48
	v_log_f32_e32 v54, v47
	v_min_f32_e32 v55, 0, v46
	ds_read_b128 v[46:49], v0 offset:1792
	v_fmamk_f32 v44, v44, 0x3d800000, v43
	v_mul_f32_e32 v50, 0x3f317217, v54
	v_fma_f32 v56, v54, s35, -v50
	ds_read_b128 v[50:53], v0 offset:1808
	s_waitcnt lgkmcnt(1)
	v_mul_f32_e32 v47, v15, v47
	v_fmac_f32_e32 v47, v12, v46
	v_fmac_f32_e32 v47, v14, v48
	v_fmac_f32_e32 v47, v17, v49
	v_add_f32_e32 v57, v19, v47
	s_waitcnt lgkmcnt(0)
	v_mul_f32_e32 v51, v13, v51
	ds_read_b128 v[46:49], v0 offset:1824
	v_fmac_f32_e32 v51, v11, v50
	v_fmac_f32_e32 v51, v9, v52
	v_fmac_f32_e32 v51, v16, v53
	v_add_f32_e32 v57, v57, v51
	ds_read_b128 v[50:53], v0 offset:1840
	s_waitcnt lgkmcnt(1)
	v_mul_f32_e32 v47, v7, v47
	v_fmac_f32_e32 v47, v3, v46
	v_fmac_f32_e32 v47, v5, v48
	v_fmac_f32_e32 v47, v10, v49
	v_add_f32_e32 v46, v57, v47
	s_waitcnt lgkmcnt(0)
	v_mul_f32_e32 v47, v4, v51
	v_fmac_f32_e32 v47, v2, v50
	v_fmac_f32_e32 v47, v6, v52
	v_fmac_f32_e32 v47, v8, v53
	v_add_f32_e32 v46, v46, v47
	v_mul_f32_e64 v47, |v46|, s33
	v_exp_f32_e32 v47, v47
	v_fmac_f32_e32 v56, 0x3377d1cf, v54
	v_fmac_f32_e32 v56, 0x3f317217, v54
	v_add_f32_e32 v47, 1.0, v47
	v_mov_b32_e32 v48, v56
	v_fmamk_f32 v45, v45, 0x3d800000, v44
	v_log_f32_e32 v54, v47
	v_sub_f32_e32 v47, v55, v48
	v_fmamk_f32 v55, v47, 0x3d800000, v45
	v_min_f32_e32 v56, 0, v46
	ds_read_b128 v[46:49], v0 offset:1856
	v_mul_f32_e32 v50, 0x3f317217, v54
	v_fma_f32 v57, v54, s35, -v50
	ds_read_b128 v[50:53], v0 offset:1872
	v_fmac_f32_e32 v57, 0x3377d1cf, v54
	s_waitcnt lgkmcnt(1)
	v_mul_f32_e32 v47, v15, v47
	v_fmac_f32_e32 v47, v12, v46
	v_fmac_f32_e32 v47, v14, v48
	v_fmac_f32_e32 v47, v17, v49
	v_add_f32_e32 v58, v19, v47
	s_waitcnt lgkmcnt(0)
	v_mul_f32_e32 v51, v13, v51
	ds_read_b128 v[46:49], v0 offset:1888
	v_fmac_f32_e32 v51, v11, v50
	v_fmac_f32_e32 v51, v9, v52
	v_fmac_f32_e32 v51, v16, v53
	v_add_f32_e32 v58, v58, v51
	ds_read_b128 v[50:53], v0 offset:1904
	s_waitcnt lgkmcnt(1)
	v_mul_f32_e32 v47, v7, v47
	v_fmac_f32_e32 v47, v3, v46
	v_fmac_f32_e32 v47, v5, v48
	v_fmac_f32_e32 v47, v10, v49
	v_add_f32_e32 v46, v58, v47
	s_waitcnt lgkmcnt(0)
	v_mul_f32_e32 v47, v4, v51
	v_fmac_f32_e32 v47, v2, v50
	v_fmac_f32_e32 v47, v6, v52
	v_fmac_f32_e32 v47, v8, v53
	v_add_f32_e32 v46, v46, v47
	v_mul_f32_e64 v47, |v46|, s33
	v_exp_f32_e32 v47, v47
	v_fmac_f32_e32 v57, 0x3f317217, v54
	v_add_f32_e32 v47, 1.0, v47
	v_mov_b32_e32 v48, v57
	v_min_f32_e32 v57, 0, v46
	v_log_f32_e32 v54, v47
	v_sub_f32_e32 v47, v56, v48
	v_fmamk_f32 v56, v47, 0x3d800000, v55
	ds_read_b128 v[46:49], v0 offset:1920
	v_mul_f32_e32 v50, 0x3f317217, v54
	v_fma_f32 v58, v54, s35, -v50
	ds_read_b128 v[50:53], v0 offset:1936
	v_fmac_f32_e32 v58, 0x3377d1cf, v54
	s_waitcnt lgkmcnt(1)
	v_mul_f32_e32 v47, v15, v47
	v_fmac_f32_e32 v47, v12, v46
	v_fmac_f32_e32 v47, v14, v48
	v_fmac_f32_e32 v47, v17, v49
	v_add_f32_e32 v59, v19, v47
	s_waitcnt lgkmcnt(0)
	v_mul_f32_e32 v51, v13, v51
	ds_read_b128 v[46:49], v0 offset:1952
	v_fmac_f32_e32 v51, v11, v50
	v_fmac_f32_e32 v51, v9, v52
	v_fmac_f32_e32 v51, v16, v53
	v_add_f32_e32 v59, v59, v51
	ds_read_b128 v[50:53], v0 offset:1968
	s_waitcnt lgkmcnt(1)
	v_mul_f32_e32 v47, v7, v47
	v_fmac_f32_e32 v47, v3, v46
	v_fmac_f32_e32 v47, v5, v48
	v_fmac_f32_e32 v47, v10, v49
	v_add_f32_e32 v46, v59, v47
	s_waitcnt lgkmcnt(0)
	v_mul_f32_e32 v47, v4, v51
	v_fmac_f32_e32 v47, v2, v50
	v_fmac_f32_e32 v47, v6, v52
	v_fmac_f32_e32 v47, v8, v53
	v_add_f32_e32 v46, v46, v47
	v_mul_f32_e64 v47, |v46|, s33
	v_exp_f32_e32 v47, v47
	v_fmac_f32_e32 v58, 0x3f317217, v54
	v_add_f32_e32 v47, 1.0, v47
	v_mov_b32_e32 v48, v58
	v_min_f32_e32 v58, 0, v46
	v_log_f32_e32 v54, v47
	v_sub_f32_e32 v47, v57, v48
	v_fmamk_f32 v57, v47, 0x3d800000, v56
	ds_read_b128 v[46:49], v0 offset:1984
	v_mul_f32_e32 v50, 0x3f317217, v54
	v_fma_f32 v59, v54, s35, -v50
	ds_read_b128 v[50:53], v0 offset:2000
	v_fmac_f32_e32 v59, 0x3377d1cf, v54
	s_waitcnt lgkmcnt(1)
; #define LAS __attribute__((address_space(3)))
; __device__ __forceinline__ float bf2f(bf16_t v) { return __uint_as_float((unsigned)v << 16); }
; __device__ __forceinline__ unsigned f2bf(float f) { return (unsigned)__builtin_bit_cast(unsigned short, (__bf16)f); }
; __device__ __forceinline__ void gla_bcum(KArgs a, int tid, int t0, int h, LAS float* segtot, LAS float* glrs, float (&bc)[32], float& tot) {
;     ...
;     for (int r = 0; r < 32; ++r) { const LAS f32x4* gp = (const LAS f32x4*)(glrs + (seg * 32 + r) * 16);
;         float z = bias;
; #pragma unroll
;         for (int q = 0; q < 4; ++q) { const f32x4 g = gp[q]; z += g[0] * w2r[4 * q] + g[1] * w2r[4 * q + 1] + g[2] * w2r[4 * q + 2] + g[3] * w2r[4 * q + 3]; }
;         const float la = (fminf(z, 0.f) - __logf(1.0f + __expf(-fabsf(z)))) * (1.0f / 16.0f);
;         run += la; bc[r] = run; }
;     segtot[seg * 128 + d] = run;
;     __syncthreads();
;     float off = 0.f; tot = 0.f;
; #pragma unroll
;     for (int s2 = 0; s2 < 4; ++s2) { const float v = segtot[s2 * 128 + d]; tot += v; if (s2 < seg) off += v; }
; #pragma unroll
;     for (int r = 0; r < 32; ++r) bc[r] += off;
;     ...
;           for (int r = 0; r < 32; ++r) { const int i = seg * 32 + r; const bf16_t* row = proj + (size_t)(t0 + i) * NMAIN + h * 128 + d;
;               const float qv = bf2f(row[C_GQ]), kv = bf2f(row[C_GK]);
;               qgs[i * GP + d] = (bf16_t)f2bf(qv * 0.08838834764831845f * __expf(bc[r])); kgs[i * GP + d] = (bf16_t)f2bf(kv * __expf(-bc[r])); } }
	v_mul_f32_e32 v15, v15, v47
	v_fmac_f32_e32 v15, v12, v46
	v_fmac_f32_e32 v15, v14, v48
	v_fmac_f32_e32 v15, v17, v49
	v_add_f32_e32 v17, v19, v15
	s_waitcnt lgkmcnt(0)
	v_mul_f32_e32 v19, v13, v51
	ds_read_b128 v[12:15], v0 offset:2016
	ds_read_b128 v[46:49], v0 offset:2032
	v_fmac_f32_e32 v19, v11, v50
	v_fmac_f32_e32 v19, v9, v52
	v_fmac_f32_e32 v19, v16, v53
	s_waitcnt lgkmcnt(1)
	v_mul_f32_e32 v0, v7, v13
	v_fmac_f32_e32 v0, v3, v12
	s_waitcnt lgkmcnt(0)
	v_mul_f32_e32 v3, v4, v47
	v_fmac_f32_e32 v0, v5, v14
	v_fmac_f32_e32 v3, v2, v46
	v_add_f32_e32 v9, v17, v19
	v_fmac_f32_e32 v0, v10, v15
	v_fmac_f32_e32 v3, v6, v48
	v_add_f32_e32 v0, v9, v0
	v_fmac_f32_e32 v3, v8, v49
	v_add_f32_e32 v0, v0, v3
	v_mul_f32_e64 v2, |v0|, s33
	v_exp_f32_e32 v2, v2
	v_fmac_f32_e32 v59, 0x3f317217, v54
	v_add_f32_e32 v2, 1.0, v2
	v_mov_b32_e32 v3, v59
	v_sub_f32_e32 v3, v58, v3
	v_log_f32_e32 v2, v2
	v_fmamk_f32 v19, v3, 0x3d800000, v57
	v_min_f32_e32 v0, 0, v0
	v_mul_f32_e32 v3, 0x3f317217, v2
	v_fma_f32 v3, v2, s35, -v3
	v_fmac_f32_e32 v3, 0x3377d1cf, v2
	v_fmac_f32_e32 v3, 0x3f317217, v2
	s_nop 1
	v_mov_b32_e32 v2, v3
	v_sub_f32_e32 v0, v0, v2
	s_and_b32 s6, s36, 0x3fffff80
	v_fmamk_f32 v0, v0, 0x3d800000, v19
	v_lshl_add_u32 v2, s6, 2, v118
	ds_write_b32 v2, v0
	s_waitcnt lgkmcnt(0)
	s_barrier
	v_add_u32_e32 v81, s44, v120
	v_mad_i64_i32 v[188:189], s[100:101], v81, s48, v[82:83]
	global_load_ushort v210, v[188:189], off
	global_load_ushort v211, v[188:189], off offset:1024
	v_add_u32_e32 v81, s44, v122
	v_mad_i64_i32 v[188:189], s[100:101], v81, s48, v[82:83]
	global_load_ushort v212, v[188:189], off
	global_load_ushort v213, v[188:189], off offset:1024
	v_add_u32_e32 v81, s44, v124
	v_mad_i64_i32 v[188:189], s[100:101], v81, s48, v[82:83]
	global_load_ushort v214, v[188:189], off
	global_load_ushort v215, v[188:189], off offset:1024
	v_add_u32_e32 v81, s44, v126
	v_mad_i64_i32 v[188:189], s[100:101], v81, s48, v[82:83]
	global_load_ushort v216, v[188:189], off
	global_load_ushort v217, v[188:189], off offset:1024
	v_add_u32_e32 v81, s44, v128
	v_mad_i64_i32 v[188:189], s[100:101], v81, s48, v[82:83]
	global_load_ushort v218, v[188:189], off
	global_load_ushort v219, v[188:189], off offset:1024
	v_add_u32_e32 v81, s44, v130
	v_mad_i64_i32 v[188:189], s[100:101], v81, s48, v[82:83]
	global_load_ushort v220, v[188:189], off
	global_load_ushort v221, v[188:189], off offset:1024
	v_add_u32_e32 v81, s44, v132
	v_mad_i64_i32 v[188:189], s[100:101], v81, s48, v[82:83]
	global_load_ushort v222, v[188:189], off
	global_load_ushort v223, v[188:189], off offset:1024
	v_add_u32_e32 v81, s44, v134
	v_mad_i64_i32 v[188:189], s[100:101], v81, s48, v[82:83]
	global_load_ushort v224, v[188:189], off
	global_load_ushort v225, v[188:189], off offset:1024
	v_add_u32_e32 v81, s44, v136
	v_mad_i64_i32 v[188:189], s[100:101], v81, s48, v[82:83]
	global_load_ushort v226, v[188:189], off
	global_load_ushort v227, v[188:189], off offset:1024
	v_add_u32_e32 v81, s44, v138
	v_mad_i64_i32 v[188:189], s[100:101], v81, s48, v[82:83]
	global_load_ushort v228, v[188:189], off
	global_load_ushort v229, v[188:189], off offset:1024
	v_add_u32_e32 v81, s44, v140
	v_mad_i64_i32 v[188:189], s[100:101], v81, s48, v[82:83]
	global_load_ushort v230, v[188:189], off
	global_load_ushort v231, v[188:189], off offset:1024
	v_add_u32_e32 v81, s44, v142
	v_mad_i64_i32 v[188:189], s[100:101], v81, s48, v[82:83]
	global_load_ushort v232, v[188:189], off
	global_load_ushort v233, v[188:189], off offset:1024
	v_add_u32_e32 v81, s44, v144
	v_mad_i64_i32 v[188:189], s[100:101], v81, s48, v[82:83]
	global_load_ushort v234, v[188:189], off
	global_load_ushort v235, v[188:189], off offset:1024
	v_add_u32_e32 v81, s44, v146
	v_mad_i64_i32 v[188:189], s[100:101], v81, s48, v[82:83]
	global_load_ushort v236, v[188:189], off
	global_load_ushort v237, v[188:189], off offset:1024
	v_add_u32_e32 v81, s44, v148
	v_mad_i64_i32 v[188:189], s[100:101], v81, s48, v[82:83]
	global_load_ushort v238, v[188:189], off
	global_load_ushort v239, v[188:189], off offset:1024
	v_add_u32_e32 v81, s44, v150
	v_mad_i64_i32 v[188:189], s[100:101], v81, s48, v[82:83]
	global_load_ushort v240, v[188:189], off
	global_load_ushort v241, v[188:189], off offset:1024
	ds_read2st64_b32 v[2:3], v118 offset1:2
	s_cmp_gt_i32 s9, 0
	ds_read2st64_b32 v[4:5], v118 offset0:4 offset1:6
	s_cselect_b64 vcc, -1, 0
	s_cmp_gt_i32 s9, 1
	s_waitcnt lgkmcnt(1)
	v_add_f32_e32 v2, 0, v2
	v_cndmask_b32_e32 v2, 0, v2, vcc
	v_add_f32_e32 v3, v3, v2
	s_cselect_b64 vcc, -1, 0
	v_cndmask_b32_e32 v2, v2, v3, vcc
	s_cmp_gt_i32 s9, 2
	s_waitcnt lgkmcnt(0)
	v_add_f32_e32 v3, v4, v2
	s_cselect_b64 vcc, -1, 0
	s_cmp_gt_i32 s9, 3
	v_cndmask_b32_e32 v6, v2, v3, vcc
	s_cselect_b64 vcc, -1, 0
	s_lshl_b32 s36, s1, 8
	v_lshl_add_u64 v[2:3], v[92:93], 0, s[36:37]
	v_add_f32_e32 v7, v5, v6
	v_cndmask_b32_e32 v50, v6, v7, vcc
	v_add_f32_e32 v53, v18, v50
	v_add_f32_e32 v18, v35, v50
	v_add_f32_e32 v17, v36, v50
	v_add_f32_e32 v54, v20, v50
	v_mul_f32_e32 v20, 0x3fb8aa3b, v53
	v_add_f32_e32 v15, v38, v50
	v_exp_f32_e32 v38, v20
	v_mul_f32_e32 v20, 0xbfb8aa3b, v53
	v_add_f32_e32 v14, v39, v50
	v_exp_f32_e32 v39, v20
	v_add_f32_e32 v58, v21, v50
	v_add_f32_e32 v13, v40, v50
	v_add_f32_e32 v12, v41, v50
	v_add_f32_e32 v4, v19, v50
	v_add_f32_e32 v16, v37, v50
	v_mul_f32_e32 v20, 0x3fb8aa3b, v54
	v_add_f32_e32 v11, v42, v50
	v_add_f32_e32 v10, v43, v50
	v_add_f32_e32 v9, v44, v50
	v_add_f32_e32 v8, v45, v50
	v_add_f32_e32 v22, v22, v50
	v_add_f32_e32 v23, v23, v50
	v_add_f32_e32 v24, v24, v50
	v_add_f32_e32 v25, v25, v50
	v_add_f32_e32 v26, v26, v50
	v_add_f32_e32 v27, v27, v50
	v_add_f32_e32 v28, v28, v50
	v_add_f32_e32 v29, v29, v50
	v_add_f32_e32 v30, v30, v50
	v_add_f32_e32 v31, v31, v50
	v_add_f32_e32 v32, v32, v50
	v_add_f32_e32 v33, v33, v50
	v_add_f32_e32 v34, v34, v50
	s_mov_b32 s9, s37
	v_add_f32_e32 v7, v55, v50
	v_add_f32_e32 v6, v56, v50
	v_add_f32_e32 v5, v57, v50
	v_add_f32_e32 v0, v50, v0
	s_andn2_b64 vcc, exec, s[38:39]
	s_waitcnt vmcnt(31)
; __device__ __forceinline__ float bf2f(bf16_t v) { return __uint_as_float((unsigned)v << 16); }
; __device__ __forceinline__ unsigned f2bf(float f) { return (unsigned)__builtin_bit_cast(unsigned short, (__bf16)f); }
;     ...
;           for (int r = 0; r < 32; ++r) { const int i = seg * 32 + r; const bf16_t* row = proj + (size_t)(t0 + i) * NMAIN + h * 128 + d;
;               const float qv = bf2f(row[C_GQ]), kv = bf2f(row[C_GK]);
;               qgs[i * GP + d] = (bf16_t)f2bf(qv * 0.08838834764831845f * __expf(bc[r])); kgs[i * GP + d] = (bf16_t)f2bf(kv * __expf(-bc[r])); } }
	v_lshlrev_b32_e32 v19, 16, v210
	v_mul_f32_e32 v19, 0x3db504f3, v19
	v_mul_f32_e32 v19, v19, v38
	s_waitcnt vmcnt(30)
	v_lshlrev_b32_e32 v37, 16, v211
	v_cvt_pk_bf16_f32 v19, v19, s0
	ds_write_b16 v121, v19
	v_mul_f32_e32 v19, v39, v37
	v_exp_f32_e32 v38, v20
	v_mul_f32_e32 v20, 0xbfb8aa3b, v54
	v_cvt_pk_bf16_f32 v19, v19, s0
	v_exp_f32_e32 v39, v20
	ds_write_b16 v121, v19 offset:34816
	s_waitcnt vmcnt(29)
	v_lshlrev_b32_e32 v19, 16, v212
	v_mul_f32_e32 v19, 0x3db504f3, v19
	v_mul_f32_e32 v19, v38, v19
	s_waitcnt vmcnt(28)
	v_lshlrev_b32_e32 v37, 16, v213
	v_cvt_pk_bf16_f32 v19, v19, s0
	v_mul_f32_e32 v20, 0x3fb8aa3b, v58
	ds_write_b16 v123, v19
	v_mul_f32_e32 v19, v39, v37
	v_exp_f32_e32 v38, v20
	v_mul_f32_e32 v20, 0xbfb8aa3b, v58
	v_cvt_pk_bf16_f32 v19, v19, s0
	v_exp_f32_e32 v39, v20
	ds_write_b16 v123, v19 offset:34816
	s_waitcnt vmcnt(27)
	v_lshlrev_b32_e32 v19, 16, v214
	v_mul_f32_e32 v19, 0x3db504f3, v19
	v_mul_f32_e32 v19, v38, v19
	s_waitcnt vmcnt(26)
	v_lshlrev_b32_e32 v37, 16, v215
	v_cvt_pk_bf16_f32 v19, v19, s0
	v_mul_f32_e32 v20, 0x3fb8aa3b, v22
	ds_write_b16 v125, v19
	v_mul_f32_e32 v19, v39, v37
	v_exp_f32_e32 v38, v20
	v_mul_f32_e32 v20, 0xbfb8aa3b, v22
	v_cvt_pk_bf16_f32 v19, v19, s0
	v_exp_f32_e32 v22, v20
	ds_write_b16 v125, v19 offset:34816
	s_waitcnt vmcnt(25)
	v_lshlrev_b32_e32 v19, 16, v216
	v_mul_f32_e32 v19, 0x3db504f3, v19
	v_mul_f32_e32 v19, v38, v19
	s_waitcnt vmcnt(24)
	v_lshlrev_b32_e32 v37, 16, v217
	v_cvt_pk_bf16_f32 v19, v19, s0
	ds_write_b16 v127, v19
	v_mul_f32_e32 v19, v22, v37
	v_cvt_pk_bf16_f32 v19, v19, s0
	v_mul_f32_e32 v20, 0x3fb8aa3b, v23
	ds_write_b16 v127, v19 offset:34816
	s_waitcnt vmcnt(23)
	v_lshlrev_b32_e32 v19, 16, v218
	v_exp_f32_e32 v35, v20
	v_mul_f32_e32 v20, 0xbfb8aa3b, v23
	v_exp_f32_e32 v23, v20
	s_waitcnt vmcnt(22)
	v_lshlrev_b32_e32 v22, 16, v219
	v_mul_f32_e32 v19, 0x3db504f3, v19
	v_mul_f32_e32 v19, v35, v19
	v_cvt_pk_bf16_f32 v19, v19, s0
	v_mul_f32_e32 v20, 0x3fb8aa3b, v24
	ds_write_b16 v129, v19
	v_mul_f32_e32 v19, v23, v22
	v_exp_f32_e32 v23, v20
	v_mul_f32_e32 v20, 0xbfb8aa3b, v24
	v_cvt_pk_bf16_f32 v19, v19, s0
	v_exp_f32_e32 v24, v20
	ds_write_b16 v129, v19 offset:34816
	s_waitcnt vmcnt(21)
	v_lshlrev_b32_e32 v19, 16, v220
	v_mul_f32_e32 v19, 0x3db504f3, v19
	v_mul_f32_e32 v19, v23, v19
	s_waitcnt vmcnt(20)
	v_lshlrev_b32_e32 v22, 16, v221
	v_cvt_pk_bf16_f32 v19, v19, s0
	v_mul_f32_e32 v20, 0x3fb8aa3b, v25
	ds_write_b16 v131, v19
	v_mul_f32_e32 v19, v24, v22
	v_exp_f32_e32 v23, v20
	v_mul_f32_e32 v20, 0xbfb8aa3b, v25
	v_cvt_pk_bf16_f32 v19, v19, s0
	v_exp_f32_e32 v24, v20
	ds_write_b16 v131, v19 offset:34816
	s_waitcnt vmcnt(19)
	v_lshlrev_b32_e32 v19, 16, v222
	v_mul_f32_e32 v19, 0x3db504f3, v19
	v_mul_f32_e32 v19, v23, v19
	s_waitcnt vmcnt(18)
	v_lshlrev_b32_e32 v22, 16, v223
	v_cvt_pk_bf16_f32 v19, v19, s0
	v_mul_f32_e32 v20, 0x3fb8aa3b, v26
	ds_write_b16 v133, v19
	v_mul_f32_e32 v19, v24, v22
	v_exp_f32_e32 v23, v20
	v_mul_f32_e32 v20, 0xbfb8aa3b, v26
	v_cvt_pk_bf16_f32 v19, v19, s0
	v_exp_f32_e32 v24, v20
	ds_write_b16 v133, v19 offset:34816
	s_waitcnt vmcnt(17)
	v_lshlrev_b32_e32 v19, 16, v224
	v_mul_f32_e32 v19, 0x3db504f3, v19
	v_mul_f32_e32 v19, v23, v19
	s_waitcnt vmcnt(16)
	v_lshlrev_b32_e32 v22, 16, v225
	v_cvt_pk_bf16_f32 v19, v19, s0
	v_mul_f32_e32 v20, 0x3fb8aa3b, v27
	ds_write_b16 v135, v19
	v_mul_f32_e32 v19, v24, v22
	v_exp_f32_e32 v23, v20
	v_mul_f32_e32 v20, 0xbfb8aa3b, v27
	v_cvt_pk_bf16_f32 v19, v19, s0
	v_exp_f32_e32 v24, v20
	ds_write_b16 v135, v19 offset:34816
	s_waitcnt vmcnt(15)
	v_lshlrev_b32_e32 v19, 16, v226
	v_mul_f32_e32 v19, 0x3db504f3, v19
	v_mul_f32_e32 v19, v23, v19
	s_waitcnt vmcnt(14)
	v_lshlrev_b32_e32 v22, 16, v227
	v_cvt_pk_bf16_f32 v19, v19, s0
	v_mul_f32_e32 v20, 0x3fb8aa3b, v28
	ds_write_b16 v137, v19
	v_mul_f32_e32 v19, v24, v22
	v_exp_f32_e32 v23, v20
	v_mul_f32_e32 v20, 0xbfb8aa3b, v28
	v_cvt_pk_bf16_f32 v19, v19, s0
	v_exp_f32_e32 v24, v20
	ds_write_b16 v137, v19 offset:34816
	s_waitcnt vmcnt(13)
	v_lshlrev_b32_e32 v19, 16, v228
	v_mul_f32_e32 v19, 0x3db504f3, v19
	v_mul_f32_e32 v19, v23, v19
	s_waitcnt vmcnt(12)
	v_lshlrev_b32_e32 v22, 16, v229
	v_cvt_pk_bf16_f32 v19, v19, s0
	v_mul_f32_e32 v20, 0x3fb8aa3b, v29
	ds_write_b16 v139, v19
	v_mul_f32_e32 v19, v24, v22
	v_exp_f32_e32 v23, v20
	v_mul_f32_e32 v20, 0xbfb8aa3b, v29
	v_cvt_pk_bf16_f32 v19, v19, s0
	v_exp_f32_e32 v24, v20
	ds_write_b16 v139, v19 offset:34816
	s_waitcnt vmcnt(11)
	v_lshlrev_b32_e32 v19, 16, v230
	v_mul_f32_e32 v19, 0x3db504f3, v19
	v_mul_f32_e32 v19, v23, v19
	s_waitcnt vmcnt(10)
	v_lshlrev_b32_e32 v22, 16, v231
	v_cvt_pk_bf16_f32 v19, v19, s0
	v_mul_f32_e32 v20, 0x3fb8aa3b, v30
	ds_write_b16 v141, v19
	v_mul_f32_e32 v19, v24, v22
	v_exp_f32_e32 v23, v20
	v_mul_f32_e32 v20, 0xbfb8aa3b, v30
	v_cvt_pk_bf16_f32 v19, v19, s0
	v_exp_f32_e32 v24, v20
	v_add_u32_e32 v20, s44, v152
	ds_write_b16 v141, v19 offset:34816
	v_mad_i64_i32 v[20:21], s[6:7], v20, s48, v[2:3]
	s_waitcnt vmcnt(9)
	v_lshlrev_b32_e32 v19, 16, v232
	global_load_ushort v25, v[20:21], off
	global_load_ushort v30, v[20:21], off offset:1024
	v_mul_f32_e32 v19, 0x3db504f3, v19
	v_mul_f32_e32 v19, v23, v19
	s_waitcnt vmcnt(10)
	v_lshlrev_b32_e32 v22, 16, v233
	v_cvt_pk_bf16_f32 v19, v19, s0
	v_mul_f32_e32 v20, 0x3fb8aa3b, v31
	ds_write_b16 v143, v19
	v_mul_f32_e32 v19, v24, v22
	v_exp_f32_e32 v23, v20
	v_mul_f32_e32 v20, 0xbfb8aa3b, v31
	v_cvt_pk_bf16_f32 v19, v19, s0
	v_exp_f32_e32 v24, v20
	v_add_u32_e32 v20, s44, v154
	ds_write_b16 v143, v19 offset:34816
	v_mad_i64_i32 v[20:21], s[6:7], v20, s48, v[2:3]
	s_waitcnt vmcnt(9)
; __device__ __forceinline__ float bf2f(bf16_t v) { return __uint_as_float((unsigned)v << 16); }
; __device__ __forceinline__ unsigned f2bf(float f) { return (unsigned)__builtin_bit_cast(unsigned short, (__bf16)f); }
;     ...
;           for (int r = 0; r < 32; ++r) { const int i = seg * 32 + r; const bf16_t* row = proj + (size_t)(t0 + i) * NMAIN + h * 128 + d;
;               const float qv = bf2f(row[C_GQ]), kv = bf2f(row[C_GK]);
;               qgs[i * GP + d] = (bf16_t)f2bf(qv * 0.08838834764831845f * __expf(bc[r])); kgs[i * GP + d] = (bf16_t)f2bf(kv * __expf(-bc[r])); } }
	v_lshlrev_b32_e32 v19, 16, v234
	global_load_ushort v26, v[20:21], off
	global_load_ushort v31, v[20:21], off offset:1024
	v_mul_f32_e32 v19, 0x3db504f3, v19
	v_mul_f32_e32 v19, v23, v19
	s_waitcnt vmcnt(10)
	v_lshlrev_b32_e32 v22, 16, v235
	v_cvt_pk_bf16_f32 v19, v19, s0
	v_mul_f32_e32 v20, 0x3fb8aa3b, v32
	ds_write_b16 v145, v19
	v_mul_f32_e32 v19, v24, v22
	v_exp_f32_e32 v23, v20
	v_mul_f32_e32 v20, 0xbfb8aa3b, v32
	v_cvt_pk_bf16_f32 v19, v19, s0
	v_exp_f32_e32 v24, v20
	v_add_u32_e32 v20, s44, v156
	ds_write_b16 v145, v19 offset:34816
	v_mad_i64_i32 v[20:21], s[6:7], v20, s48, v[2:3]
	s_waitcnt vmcnt(9)
	v_lshlrev_b32_e32 v19, 16, v236
	global_load_ushort v27, v[20:21], off
	global_load_ushort v32, v[20:21], off offset:1024
	v_mul_f32_e32 v19, 0x3db504f3, v19
	v_mul_f32_e32 v19, v23, v19
	s_waitcnt vmcnt(10)
	v_lshlrev_b32_e32 v22, 16, v237
	v_cvt_pk_bf16_f32 v19, v19, s0
	v_mul_f32_e32 v20, 0x3fb8aa3b, v33
	ds_write_b16 v147, v19
	v_mul_f32_e32 v19, v24, v22
	v_exp_f32_e32 v23, v20
	v_cvt_pk_bf16_f32 v19, v19, s0
	v_mul_f32_e32 v20, 0xbfb8aa3b, v33
	ds_write_b16 v147, v19 offset:34816
	s_waitcnt vmcnt(9)
	v_lshlrev_b32_e32 v19, 16, v238
	v_exp_f32_e32 v24, v20
	v_mul_f32_e32 v19, 0x3db504f3, v19
	v_add_u32_e32 v20, s44, v158
	v_mad_i64_i32 v[20:21], s[6:7], v20, s48, v[2:3]
	v_mul_f32_e32 v19, v23, v19
	s_waitcnt vmcnt(8)
	v_lshlrev_b32_e32 v22, 16, v239
	global_load_ushort v28, v[20:21], off
	global_load_ushort v33, v[20:21], off offset:1024
	v_cvt_pk_bf16_f32 v19, v19, s0
	v_mul_f32_e32 v20, 0x3fb8aa3b, v34
	ds_write_b16 v149, v19
	v_mul_f32_e32 v19, v24, v22
	v_exp_f32_e32 v23, v20
	v_mul_f32_e32 v20, 0xbfb8aa3b, v34
	v_cvt_pk_bf16_f32 v19, v19, s0
	v_exp_f32_e32 v24, v20
	v_add_u32_e32 v20, s44, v160
	ds_write_b16 v149, v19 offset:34816
	v_mad_i64_i32 v[20:21], s[6:7], v20, s48, v[2:3]
	s_waitcnt vmcnt(9)
	v_lshlrev_b32_e32 v19, 16, v240
	global_load_ushort v29, v[20:21], off
	s_nop 0
	global_load_ushort v20, v[20:21], off offset:1024
	v_mul_f32_e32 v19, 0x3db504f3, v19
	v_mul_f32_e32 v19, v23, v19
	s_waitcnt vmcnt(10)
	v_lshlrev_b32_e32 v22, 16, v241
	v_cvt_pk_bf16_f32 v19, v19, s0
	ds_write_b16 v151, v19
	v_mul_f32_e32 v19, v24, v22
	v_cvt_pk_bf16_f32 v19, v19, s0
	ds_write_b16 v151, v19 offset:34816
	s_waitcnt vmcnt(9)
	v_lshlrev_b32_e32 v19, 16, v25
	v_mul_f32_e32 v22, 0x3db504f3, v19
	v_mul_f32_e32 v19, 0x3fb8aa3b, v18
	v_mul_f32_e32 v18, 0xbfb8aa3b, v18
	v_exp_f32_e32 v24, v18
	v_add_u32_e32 v18, s44, v162
	v_exp_f32_e32 v23, v19
	v_mad_i64_i32 v[18:19], s[6:7], v18, s48, v[2:3]
	s_waitcnt vmcnt(8)
	v_lshlrev_b32_e32 v21, 16, v30
	global_load_ushort v25, v[18:19], off
	global_load_ushort v30, v[18:19], off offset:1024
	v_mul_f32_e32 v18, v23, v22
	v_cvt_pk_bf16_f32 v18, v18, s0
	ds_write_b16 v153, v18
	v_mul_f32_e32 v18, v24, v21
	v_cvt_pk_bf16_f32 v18, v18, s0
	ds_write_b16 v153, v18 offset:34816
	s_waitcnt vmcnt(9)
	v_lshlrev_b32_e32 v18, 16, v26
	v_mul_f32_e32 v22, 0x3db504f3, v18
	v_mul_f32_e32 v18, 0x3fb8aa3b, v17
	v_exp_f32_e32 v23, v18
	v_mul_f32_e32 v17, 0xbfb8aa3b, v17
	v_exp_f32_e32 v17, v17
	v_add_u32_e32 v18, s44, v164
	v_mad_i64_i32 v[18:19], s[6:7], v18, s48, v[2:3]
	s_waitcnt vmcnt(8)
	v_lshlrev_b32_e32 v21, 16, v31
	global_load_ushort v24, v[18:19], off
	global_load_ushort v26, v[18:19], off offset:1024
	v_mul_f32_e32 v18, v23, v22
	v_cvt_pk_bf16_f32 v18, v18, s0
	v_mul_f32_e32 v17, v17, v21
	ds_write_b16 v155, v18
	v_cvt_pk_bf16_f32 v17, v17, s0
	v_add_u32_e32 v18, s44, v166
	ds_write_b16 v155, v17 offset:34816
	v_mad_i64_i32 v[18:19], s[6:7], v18, s48, v[2:3]
	global_load_ushort v22, v[18:19], off
	s_nop 0
	global_load_ushort v18, v[18:19], off offset:1024
	v_mul_f32_e32 v19, 0x3fb8aa3b, v16
	v_mul_f32_e32 v16, 0xbfb8aa3b, v16
	v_exp_f32_e32 v16, v16
	v_exp_f32_e32 v19, v19
	s_waitcnt vmcnt(11)
	v_lshlrev_b32_e32 v17, 16, v27
	s_waitcnt vmcnt(10)
	v_lshlrev_b32_e32 v21, 16, v32
	v_mul_f32_e32 v17, 0x3db504f3, v17
	v_mul_f32_e32 v16, v16, v21
	v_mul_f32_e32 v17, v19, v17
	v_cvt_pk_bf16_f32 v16, v16, s0
	v_cvt_pk_bf16_f32 v17, v17, s0
	ds_write_b16 v157, v16 offset:34816
	v_add_u32_e32 v16, s44, v168
	ds_write_b16 v157, v17
	v_mad_i64_i32 v[16:17], s[6:7], v16, s48, v[2:3]
	global_load_ushort v23, v[16:17], off
	s_nop 0
	global_load_ushort v16, v[16:17], off offset:1024
	v_mul_f32_e32 v17, 0x3fb8aa3b, v15
	v_mul_f32_e32 v15, 0xbfb8aa3b, v15
	v_exp_f32_e32 v15, v15
	s_waitcnt vmcnt(10)
	v_lshlrev_b32_e32 v21, 16, v33
	v_exp_f32_e32 v17, v17
	v_lshlrev_b32_e32 v19, 16, v28
	v_mul_f32_e32 v15, v15, v21
	v_cvt_pk_bf16_f32 v15, v15, s0
	v_mul_f32_e32 v19, 0x3db504f3, v19
	ds_write_b16 v159, v15 offset:34816
	v_mul_f32_e32 v17, v17, v19
	v_cvt_pk_bf16_f32 v17, v17, s0
	ds_write_b16 v159, v17
	s_waitcnt vmcnt(9)
	v_lshlrev_b32_e32 v15, 16, v29
	v_mul_f32_e32 v19, 0x3db504f3, v15
	v_mul_f32_e32 v15, 0x3fb8aa3b, v14
	v_mul_f32_e32 v14, 0xbfb8aa3b, v14
	v_exp_f32_e32 v21, v14
	v_add_u32_e32 v14, s44, v170
	s_waitcnt vmcnt(8)
	v_lshlrev_b32_e32 v17, 16, v20
	v_exp_f32_e32 v20, v15
	v_mad_i64_i32 v[14:15], s[6:7], v14, s48, v[2:3]
	global_load_ushort v27, v[14:15], off
	global_load_ushort v28, v[14:15], off offset:1024
	v_mul_f32_e32 v14, v20, v19
	v_cvt_pk_bf16_f32 v14, v14, s0
	ds_write_b16 v161, v14
	v_mul_f32_e32 v14, v21, v17
	v_cvt_pk_bf16_f32 v14, v14, s0
	ds_write_b16 v161, v14 offset:34816
	s_waitcnt vmcnt(9)
	v_lshlrev_b32_e32 v14, 16, v25
	v_mul_f32_e32 v19, 0x3db504f3, v14
	v_mul_f32_e32 v14, 0x3fb8aa3b, v13
	v_exp_f32_e32 v20, v14
	v_add_u32_e32 v14, s44, v172
	v_mad_i64_i32 v[14:15], s[6:7], v14, s48, v[2:3]
	global_load_ushort v21, v[14:15], off
	s_nop 0
	global_load_ushort v14, v[14:15], off offset:1024
	v_mul_f32_e32 v13, 0xbfb8aa3b, v13
	v_exp_f32_e32 v13, v13
	s_waitcnt vmcnt(10)
; #define LAS __attribute__((address_space(3)))
; __device__ __forceinline__ float bf2f(bf16_t v) { return __uint_as_float((unsigned)v << 16); }
; __device__ __forceinline__ unsigned f2bf(float f) { return (unsigned)__builtin_bit_cast(unsigned short, (__bf16)f); }
; __device__ __forceinline__ void gla_stage_vT(const bf16_t* proj, int tid, int t0, int h, LAS bf16_t* vT) {
; #pragma unroll
;     for (int q = 0; q < 8; ++q) { const int i = tid >> 2, c = (tid & 3) + 4 * q;
;         const u32x4 wv = *(const u32x4*)(proj + (size_t)(t0 + i) * NMAIN + C_GV + h * 256 + 8 * c);
;         LAS bf16_t* vp = vT + (8 * c) * GP + i;
;         vp[0 * GP] = (bf16_t)(wv.x & 0xffff); vp[1 * GP] = (bf16_t)(wv.x >> 16); vp[2 * GP] = (bf16_t)(wv.y & 0xffff); vp[3 * GP] = (bf16_t)(wv.y >> 16);
;         vp[4 * GP] = (bf16_t)(wv.z & 0xffff); vp[5 * GP] = (bf16_t)(wv.z >> 16); vp[6 * GP] = (bf16_t)(wv.w & 0xffff); vp[7 * GP] = (bf16_t)(wv.w >> 16); }
;     ...
;           for (int r = 0; r < 32; ++r) { const int i = seg * 32 + r; const bf16_t* row = proj + (size_t)(t0 + i) * NMAIN + h * 128 + d;
;               const float qv = bf2f(row[C_GQ]), kv = bf2f(row[C_GK]);
;               qgs[i * GP + d] = (bf16_t)f2bf(qv * 0.08838834764831845f * __expf(bc[r])); kgs[i * GP + d] = (bf16_t)f2bf(kv * __expf(-bc[r])); } }
	v_lshlrev_b32_e32 v17, 16, v30
	v_mul_f32_e32 v15, v20, v19
	v_cvt_pk_bf16_f32 v15, v15, s0
	v_mul_f32_e32 v13, v13, v17
	v_mul_f32_e32 v17, 0x3fb8aa3b, v12
	v_mul_f32_e32 v12, 0xbfb8aa3b, v12
	v_exp_f32_e32 v12, v12
	v_exp_f32_e32 v17, v17
	ds_write_b16 v163, v15
	v_cvt_pk_bf16_f32 v13, v13, s0
	s_waitcnt vmcnt(8)
	v_lshlrev_b32_e32 v15, 16, v26
	ds_write_b16 v163, v13 offset:34816
	v_lshlrev_b32_e32 v13, 16, v24
	v_mul_f32_e32 v12, v12, v15
	v_mul_f32_e32 v13, 0x3db504f3, v13
	v_cvt_pk_bf16_f32 v12, v12, s0
	v_mul_f32_e32 v13, v17, v13
	ds_write_b16 v165, v12 offset:34816
	v_mul_f32_e32 v12, 0x3fb8aa3b, v11
	v_cvt_pk_bf16_f32 v13, v13, s0
	s_waitcnt vmcnt(6)
	v_lshlrev_b32_e32 v17, 16, v18
	v_exp_f32_e32 v18, v12
	v_add_u32_e32 v12, s44, v174
	ds_write_b16 v165, v13
	v_mad_i64_i32 v[12:13], s[6:7], v12, s48, v[2:3]
	global_load_ushort v19, v[12:13], off
	global_load_ushort v20, v[12:13], off offset:1024
	v_mul_f32_e32 v11, 0xbfb8aa3b, v11
	v_exp_f32_e32 v11, v11
	v_lshlrev_b32_e32 v15, 16, v22
	v_mul_f32_e32 v12, 0x3db504f3, v15
	v_mul_f32_e32 v12, v18, v12
	v_cvt_pk_bf16_f32 v12, v12, s0
	v_mul_f32_e32 v11, v11, v17
	ds_write_b16 v167, v12
	v_cvt_pk_bf16_f32 v11, v11, s0
	v_add_u32_e32 v12, s44, v176
	ds_write_b16 v167, v11 offset:34816
	v_mad_i64_i32 v[12:13], s[6:7], v12, s48, v[2:3]
	global_load_ushort v24, v[12:13], off
	global_load_ushort v25, v[12:13], off offset:1024
	s_waitcnt vmcnt(8)
	v_lshlrev_b32_e32 v15, 16, v16
	v_mul_f32_e32 v16, 0x3fb8aa3b, v10
	v_mul_f32_e32 v10, 0xbfb8aa3b, v10
	v_exp_f32_e32 v10, v10
	v_exp_f32_e32 v12, v16
	v_lshlrev_b32_e32 v11, 16, v23
	v_mul_f32_e32 v11, 0x3db504f3, v11
	v_mul_f32_e32 v10, v10, v15
	v_mul_f32_e32 v11, v12, v11
	v_cvt_pk_bf16_f32 v10, v10, s0
	v_cvt_pk_bf16_f32 v11, v11, s0
	ds_write_b16 v169, v10 offset:34816
	v_add_u32_e32 v10, s44, v178
	ds_write_b16 v169, v11
	v_mad_i64_i32 v[10:11], s[6:7], v10, s48, v[2:3]
	global_load_ushort v32, v[10:11], off
	global_load_ushort v33, v[10:11], off offset:1024
	s_waitcnt vmcnt(9)
	v_lshlrev_b32_e32 v10, 16, v27
	v_mul_f32_e32 v13, 0x3db504f3, v10
	v_mul_f32_e32 v10, 0x3fb8aa3b, v9
	v_exp_f32_e32 v15, v10
	v_add_u32_e32 v10, s44, v180
	v_mad_i64_i32 v[10:11], s[6:7], v10, s48, v[2:3]
	global_load_ushort v36, v[10:11], off
	global_load_ushort v37, v[10:11], off offset:1024
	v_mul_f32_e32 v9, 0xbfb8aa3b, v9
	v_exp_f32_e32 v9, v9
	s_waitcnt vmcnt(10)
	v_lshlrev_b32_e32 v12, 16, v28
	v_mul_f32_e32 v10, v15, v13
	v_cvt_pk_bf16_f32 v10, v10, s0
	v_mul_f32_e32 v9, v9, v12
	v_cvt_pk_bf16_f32 v9, v9, s0
	ds_write_b16 v171, v9 offset:34816
	ds_write_b16 v171, v10
	v_mul_f32_e32 v15, 0xbfb8aa3b, v8
	s_waitcnt vmcnt(9)
	v_lshlrev_b32_e32 v9, 16, v21
	v_mul_f32_e32 v13, 0x3db504f3, v9
	v_add_u32_e32 v9, s44, v182
	v_mad_i64_i32 v[2:3], s[6:7], v9, s48, v[2:3]
	global_load_ushort v40, v[2:3], off
	global_load_ushort v41, v[2:3], off offset:1024
	v_mul_f32_e32 v2, 0x3fb8aa3b, v8
	s_waitcnt vmcnt(10)
	v_lshlrev_b32_e32 v12, 16, v14
	v_exp_f32_e32 v14, v2
	v_add_u32_e32 v8, s44, v119
	v_mov_b64_e32 v[2:3], s[22:23]
	v_mad_i64_i32 v[2:3], s[6:7], v8, s48, v[2:3]
	v_lshl_add_u64 v[2:3], v[2:3], 0, s[8:9]
	v_lshl_add_u64 v[2:3], v[2:3], 0, v[110:111]
	global_load_dwordx4 v[8:11], v[2:3], off offset:2048
	v_exp_f32_e32 v15, v15
	v_mul_f32_e32 v13, v14, v13
	v_cvt_pk_bf16_f32 v13, v13, s0
	ds_write_b16 v173, v13
	v_mul_f32_e32 v12, v15, v12
	v_cvt_pk_bf16_f32 v12, v12, s0
	ds_write_b16 v173, v12 offset:34816
	global_load_dwordx4 v[12:15], v[2:3], off offset:2112
	s_waitcnt vmcnt(11)
	v_lshlrev_b32_e32 v16, 16, v19
	v_mul_f32_e32 v21, 0x3db504f3, v16
	v_mul_f32_e32 v16, 0x3fb8aa3b, v7
	v_exp_f32_e32 v22, v16
	global_load_dwordx4 v[16:19], v[2:3], off offset:2176
	v_mul_f32_e32 v7, 0xbfb8aa3b, v7
	v_exp_f32_e32 v7, v7
	v_mul_f32_e32 v21, v22, v21
	s_waitcnt vmcnt(11)
	v_lshlrev_b32_e32 v20, 16, v20
	v_cvt_pk_bf16_f32 v21, v21, s0
	ds_write_b16 v175, v21
	v_mul_f32_e32 v7, v7, v20
	global_load_dwordx4 v[20:23], v[2:3], off offset:2240
	v_cvt_pk_bf16_f32 v7, v7, s0
	ds_write_b16 v175, v7 offset:34816
	v_mul_f32_e32 v7, 0x3fb8aa3b, v6
	v_exp_f32_e32 v7, v7
	s_waitcnt vmcnt(11)
	v_lshlrev_b32_e32 v24, 16, v24
	v_mul_f32_e32 v24, 0x3db504f3, v24
	s_waitcnt vmcnt(10)
	v_lshlrev_b32_e32 v28, 16, v25
	v_mul_f32_e32 v7, v7, v24
	global_load_dwordx4 v[24:27], v[2:3], off offset:2304
	v_mul_f32_e32 v6, 0xbfb8aa3b, v6
	v_exp_f32_e32 v6, v6
	v_cvt_pk_bf16_f32 v7, v7, s0
	ds_write_b16 v177, v7
	v_mul_f32_e32 v6, v6, v28
	global_load_dwordx4 v[28:31], v[2:3], off offset:2368
	v_cvt_pk_bf16_f32 v6, v6, s0
	ds_write_b16 v177, v6 offset:34816
	s_waitcnt vmcnt(11)
	v_lshlrev_b32_e32 v7, 16, v32
	s_waitcnt vmcnt(10)
	v_lshlrev_b32_e32 v38, 16, v33
	global_load_dwordx4 v[32:35], v[2:3], off offset:2432
	v_mul_f32_e32 v6, 0x3fb8aa3b, v5
	v_mul_f32_e32 v5, 0xbfb8aa3b, v5
	v_exp_f32_e32 v6, v6
	v_exp_f32_e32 v5, v5
	v_mul_f32_e32 v7, 0x3db504f3, v7
	v_mul_f32_e32 v6, v6, v7
	v_mul_f32_e32 v5, v5, v38
	v_cvt_pk_bf16_f32 v6, v6, s0
	v_cvt_pk_bf16_f32 v5, v5, s0
	ds_write_b16 v179, v6
	ds_write_b16 v179, v5 offset:34816
	s_waitcnt vmcnt(10)
; #define LAS __attribute__((address_space(3)))
; __device__ __forceinline__ unsigned f2bf(float f) { return (unsigned)__builtin_bit_cast(unsigned short, (__bf16)f); }
; #define X make_ctx(lds_raw)
; __device__ __forceinline__ void gla_stage_vT(const bf16_t* proj, int tid, int t0, int h, LAS bf16_t* vT) {
;     ...
;     for (int q = 0; q < 8; ++q) { const int i = tid >> 2, c = (tid & 3) + 4 * q;
;         const u32x4 wv = *(const u32x4*)(proj + (size_t)(t0 + i) * NMAIN + C_GV + h * 256 + 8 * c);
;         LAS bf16_t* vp = vT + (8 * c) * GP + i;
;         vp[0 * GP] = (bf16_t)(wv.x & 0xffff); vp[1 * GP] = (bf16_t)(wv.x >> 16); vp[2 * GP] = (bf16_t)(wv.y & 0xffff); vp[3 * GP] = (bf16_t)(wv.y >> 16);
;         vp[4 * GP] = (bf16_t)(wv.z & 0xffff); vp[5 * GP] = (bf16_t)(wv.z >> 16); vp[6 * GP] = (bf16_t)(wv.w & 0xffff); vp[7 * GP] = (bf16_t)(wv.w >> 16); }
;     ...
;         bf16x8 afr[4];
; #pragma unroll
;         for (int ks = 0; ks < 4; ++ks) afr[ks] = *(const LAS bf16x8*)(qgs + (i0 + fr) * GP + 32 * ks + 8 * fq);
;         f32x4 acc[16];
; #pragma unroll
;         for (int nt = 0; nt < 16; ++nt) acc[nt] = (f32x4){0.f, 0.f, 0.f, 0.f};
;         for (int jt = 0; jt <= (w | 1); ++jt) {
;             f32x4 att = {0.f, 0.f, 0.f, 0.f};
;             if (jt <= w) {
; #pragma unroll
;                 for (int ks = 0; ks < 4; ++ks) { const bf16x8 bf = *(const LAS bf16x8*)(kgs + (16 * jt + fr) * GP + 32 * ks + 8 * fq); att = __builtin_amdgcn_mfma_f32_16x16x32_bf16(afr[ks], bf, att, 0, 0, 0); }
;             }
; #pragma unroll
;             for (int e = 0; e < 4; ++e) { const int i = i0 + 4 * fq + e, j = 16 * jt + fr; qgs[i * GP + j] = (bf16_t)f2bf(j <= i ? att[e] : 0.f); }
;         }
;         asm volatile("s_waitcnt lgkmcnt(0)" ::: "memory");
;         for (int ks = 0; ks <= (w >> 1); ++ks) { const bf16x8 af = *(const LAS bf16x8*)(qgs + (i0 + fr) * GP + 32 * ks + 8 * fq);
; #pragma unroll
;             for (int nt = 0; nt < 16; ++nt) { const bf16x8 bf = *(const LAS bf16x8*)(vT + (16 * nt + fr) * GP + 32 * ks + 8 * fq); acc[nt] = __builtin_amdgcn_mfma_f32_16x16x32_bf16(af, bf, acc[nt], 0, 0, 0); } }
;         if (n > 0) {
;             __syncthreads();
;             const bf16_t* sb = (const bf16_t*)kvt + (size_t)unit * 32768;
; #pragma unroll
;             for (int q = 0; q < 8; ++q) { const int sidx = X.tid + 512 * q; const u32x4 wv = *(const u32x4*)(sb + (size_t)sidx * 8);
	v_lshlrev_b32_e32 v5, 16, v36
	s_waitcnt vmcnt(9)
	v_lshlrev_b32_e32 v6, 16, v37
	global_load_dwordx4 v[36:39], v[2:3], off offset:2496
	v_mul_f32_e32 v7, 0x3fb8aa3b, v4
	v_exp_f32_e32 v2, v7
	v_mul_f32_e32 v4, 0xbfb8aa3b, v4
	v_exp_f32_e32 v4, v4
	v_mul_f32_e32 v3, 0x3db504f3, v5
	v_mul_f32_e32 v2, v2, v3
	v_cvt_pk_bf16_f32 v2, v2, s0
	ds_write_b16 v181, v2
	v_mul_f32_e32 v2, v4, v6
	v_mul_f32_e32 v4, 0x3fb8aa3b, v0
	v_mul_f32_e32 v0, 0xbfb8aa3b, v0
	v_exp_f32_e32 v4, v4
	v_exp_f32_e32 v0, v0
	v_cvt_pk_bf16_f32 v2, v2, s0
	ds_write_b16 v181, v2 offset:34816
	s_waitcnt vmcnt(9)
	v_lshlrev_b32_e32 v2, 16, v40
	s_waitcnt vmcnt(8)
	v_lshlrev_b32_e32 v3, 16, v41
	v_mul_f32_e32 v2, 0x3db504f3, v2
	v_mul_f32_e32 v2, v4, v2
	v_mul_f32_e32 v0, v0, v3
	v_cvt_pk_bf16_f32 v2, v2, s0
	v_cvt_pk_bf16_f32 v0, v0, s0
	ds_write_b16 v183, v2
	ds_write_b16 v183, v0 offset:34816
	s_waitcnt vmcnt(7)
	ds_write_b16 v203, v8
	ds_write_b16_d16_hi v203, v8 offset:272
	ds_write_b16 v203, v9 offset:544
	ds_write_b16_d16_hi v203, v9 offset:816
	ds_write_b16 v203, v10 offset:1088
	ds_write_b16_d16_hi v203, v10 offset:1360
	ds_write_b16 v203, v11 offset:1632
	ds_write_b16_d16_hi v203, v11 offset:1904
	s_waitcnt vmcnt(6)
	ds_write_b16 v203, v12 offset:8704
	ds_write_b16_d16_hi v203, v12 offset:8976
	ds_write_b16 v203, v13 offset:9248
	ds_write_b16_d16_hi v203, v13 offset:9520
	ds_write_b16 v203, v14 offset:9792
	ds_write_b16_d16_hi v203, v14 offset:10064
	ds_write_b16 v203, v15 offset:10336
	ds_write_b16_d16_hi v203, v15 offset:10608
	s_waitcnt vmcnt(5)
	ds_write_b16 v203, v16 offset:17408
	ds_write_b16_d16_hi v203, v16 offset:17680
	ds_write_b16 v203, v17 offset:17952
	ds_write_b16_d16_hi v203, v17 offset:18224
	ds_write_b16 v203, v18 offset:18496
	ds_write_b16_d16_hi v203, v18 offset:18768
	ds_write_b16 v203, v19 offset:19040
	ds_write_b16_d16_hi v203, v19 offset:19312
	s_waitcnt vmcnt(4)
	ds_write_b16 v203, v20 offset:26112
	ds_write_b16_d16_hi v203, v20 offset:26384
	ds_write_b16 v203, v21 offset:26656
	ds_write_b16_d16_hi v203, v21 offset:26928
	ds_write_b16 v203, v22 offset:27200
	ds_write_b16_d16_hi v203, v22 offset:27472
	ds_write_b16 v203, v23 offset:27744
	ds_write_b16_d16_hi v203, v23 offset:28016
	s_waitcnt vmcnt(3)
	ds_write_b16 v203, v24 offset:34816
	ds_write_b16_d16_hi v203, v24 offset:35088
	ds_write_b16 v203, v25 offset:35360
	ds_write_b16_d16_hi v203, v25 offset:35632
	ds_write_b16 v203, v26 offset:35904
	ds_write_b16_d16_hi v203, v26 offset:36176
	ds_write_b16 v203, v27 offset:36448
	ds_write_b16_d16_hi v203, v27 offset:36720
	s_waitcnt vmcnt(2)
	ds_write_b16 v203, v28 offset:43520
	ds_write_b16_d16_hi v203, v28 offset:43792
	ds_write_b16 v203, v29 offset:44064
	ds_write_b16_d16_hi v203, v29 offset:44336
	ds_write_b16 v203, v30 offset:44608
	ds_write_b16_d16_hi v203, v30 offset:44880
	ds_write_b16 v203, v31 offset:45152
	ds_write_b16_d16_hi v203, v31 offset:45424
	s_waitcnt vmcnt(1)
	ds_write_b16 v203, v32 offset:52224
	ds_write_b16_d16_hi v203, v32 offset:52496
	ds_write_b16 v203, v33 offset:52768
	ds_write_b16_d16_hi v203, v33 offset:53040
	ds_write_b16 v203, v34 offset:53312
	ds_write_b16_d16_hi v203, v34 offset:53584
	ds_write_b16 v203, v35 offset:53856
	ds_write_b16_d16_hi v203, v35 offset:54128
	s_waitcnt vmcnt(0)
	ds_write_b16 v203, v36 offset:60928
	ds_write_b16_d16_hi v203, v36 offset:61200
	ds_write_b16 v203, v37 offset:61472
	ds_write_b16_d16_hi v203, v37 offset:61744
	ds_write_b16 v203, v38 offset:62016
	ds_write_b16_d16_hi v203, v38 offset:62288
	ds_write_b16 v203, v39 offset:62560
	ds_write_b16_d16_hi v203, v39 offset:62832
	s_waitcnt lgkmcnt(0)
	s_barrier
	ds_read_b128 v[80:83], v204
	ds_read_b128 v[76:79], v204 offset:64
	ds_read_b128 v[72:75], v204 offset:128
	ds_read_b128 v[68:71], v204 offset:192
	s_and_b32 s100, s42, 31
	s_cmp_eq_u32 s100, 0
	s_cbranch_scc1 .La3st_skip
	s_lshl_b32 s98, s42, 16
	s_add_u32 s98, s12, s98
	s_addc_u32 s99, s13, 0
	v_lshl_add_u64 v[222:223], s[98:99], 0, v[94:95]
	global_load_dwordx4 v[222:225], v[222:223], off
	v_lshl_add_u64 v[226:227], s[98:99], 0, v[96:97]
	global_load_dwordx4 v[226:229], v[226:227], off
	v_lshl_add_u64 v[230:231], s[98:99], 0, v[98:99]
	global_load_dwordx4 v[230:233], v[230:231], off
	v_lshl_add_u64 v[234:235], s[98:99], 0, v[100:101]
	global_load_dwordx4 v[234:237], v[234:235], off
	v_lshl_add_u64 v[238:239], s[98:99], 0, v[102:103]
	global_load_dwordx4 v[238:241], v[238:239], off
	v_lshl_add_u64 v[242:243], s[98:99], 0, v[104:105]
	global_load_dwordx4 v[242:245], v[242:243], off
	v_lshl_add_u64 v[246:247], s[98:99], 0, v[106:107]
	global_load_dwordx4 v[246:249], v[246:247], off
	v_lshl_add_u64 v[250:251], s[98:99], 0, v[108:109]
	global_load_dwordx4 v[250:253], v[250:251], off
.La3st_skip:
	s_cbranch_vccnz .LBB0_483
	s_mov_b32 s1, 0
	v_mov_b32_e32 v0, v200
	v_mov_b32_e32 v6, v199
	v_mov_b32_e32 v7, v86
	s_branch .LBB0_481

; #define LAS __attribute__((address_space(3)))
; #define X make_ctx(lds_raw)
;     ...
;         if (n > 0) {
;             __syncthreads();
;             const bf16_t* sb = (const bf16_t*)kvt + (size_t)unit * 32768;
; #pragma unroll
;             for (int q = 0; q < 8; ++q) { const int sidx = X.tid + 512 * q; const u32x4 wv = *(const u32x4*)(sb + (size_t)sidx * 8);
;                 *(LAS u32x4*)(vT + (sidx >> 4) * GP + (sidx & 15) * 8) = wv; }
;             __syncthreads();
; #pragma unroll
;             for (int ks = 0; ks < 4; ++ks)
; #pragma unroll
;                 for (int nt = 0; nt < 16; ++nt) { const bf16x8 bf = *(const LAS bf16x8*)(vT + (16 * nt + fr) * GP + 32 * ks + 8 * fq); acc[nt] = __builtin_amdgcn_mfma_f32_16x16x32_bf16(afr[ks], bf, acc[nt], 0, 0, 0); }
.LBB0_488:
	s_waitcnt lgkmcnt(0)
	s_barrier
	v_add_u32_e32 v0, v112, v116
	s_waitcnt vmcnt(7)
	ds_write_b128 v85, v[222:225]
	s_waitcnt vmcnt(6)
	ds_write_b128 v184, v[226:229]
	s_waitcnt vmcnt(5)
	ds_write_b128 v185, v[230:233]
	s_waitcnt vmcnt(4)
	ds_write_b128 v191, v[234:237]
	s_waitcnt vmcnt(3)
	ds_write_b128 v192, v[238:241]
	s_waitcnt vmcnt(2)
	ds_write_b128 v193, v[242:245]
	s_waitcnt vmcnt(1)
	ds_write_b128 v194, v[246:249]
	s_waitcnt vmcnt(0)
	ds_write_b128 v195, v[250:253]
	s_waitcnt lgkmcnt(0)
	s_barrier
	ds_read_b128 v[210:213], v0
	s_waitcnt lgkmcnt(0)
	v_mfma_f32_16x16x32_bf16 v[64:67], v[80:83], v[210:213], v[64:67]
	ds_read_b128 v[210:213], v0 offset:4352
	s_waitcnt lgkmcnt(0)
	v_mfma_f32_16x16x32_bf16 v[60:63], v[80:83], v[210:213], v[60:63]
	ds_read_b128 v[210:213], v0 offset:8704
	s_waitcnt lgkmcnt(0)
	v_mfma_f32_16x16x32_bf16 v[52:55], v[80:83], v[210:213], v[52:55]
	ds_read_b128 v[210:213], v0 offset:13056
	s_waitcnt lgkmcnt(0)
	v_mfma_f32_16x16x32_bf16 v[48:51], v[80:83], v[210:213], v[48:51]
	ds_read_b128 v[210:213], v0 offset:17408
	s_waitcnt lgkmcnt(0)
	v_mfma_f32_16x16x32_bf16 v[44:47], v[80:83], v[210:213], v[44:47]
	ds_read_b128 v[210:213], v0 offset:21760
	s_waitcnt lgkmcnt(0)
	v_mfma_f32_16x16x32_bf16 v[40:43], v[80:83], v[210:213], v[40:43]
	ds_read_b128 v[210:213], v205 offset:4352
	s_waitcnt lgkmcnt(0)
	v_mfma_f32_16x16x32_bf16 v[36:39], v[80:83], v[210:213], v[36:39]
	ds_read_b128 v[210:213], v205 offset:8704
	s_waitcnt lgkmcnt(0)
	v_mfma_f32_16x16x32_bf16 v[24:27], v[80:83], v[210:213], v[24:27]
	ds_read_b128 v[210:213], v205 offset:13056
	s_waitcnt lgkmcnt(0)
	v_mfma_f32_16x16x32_bf16 v[20:23], v[80:83], v[210:213], v[20:23]
	ds_read_b128 v[210:213], v205 offset:17408
	s_waitcnt lgkmcnt(0)
	v_mfma_f32_16x16x32_bf16 v[16:19], v[80:83], v[210:213], v[16:19]
	ds_read_b128 v[210:213], v205 offset:21760
	s_waitcnt lgkmcnt(0)
	v_mfma_f32_16x16x32_bf16 v[12:15], v[80:83], v[210:213], v[12:15]
	ds_read_b128 v[210:213], v205 offset:26112
	s_waitcnt lgkmcnt(0)
	v_mfma_f32_16x16x32_bf16 v[8:11], v[80:83], v[210:213], v[8:11]
	ds_read_b128 v[210:213], v205 offset:30464
	s_waitcnt lgkmcnt(0)
	v_mfma_f32_16x16x32_bf16 v[2:5], v[80:83], v[210:213], v[4:7]
	ds_read_b128 v[210:213], v205 offset:34816
	s_waitcnt lgkmcnt(0)
	v_mfma_f32_16x16x32_bf16 v[32:35], v[80:83], v[210:213], v[32:35]
	ds_read_b128 v[210:213], v205 offset:39168
	s_waitcnt lgkmcnt(0)
	v_mfma_f32_16x16x32_bf16 v[28:31], v[80:83], v[210:213], v[28:31]
	ds_read_b128 v[210:213], v205 offset:43520
	s_waitcnt lgkmcnt(0)
	v_mfma_f32_16x16x32_bf16 v[56:59], v[80:83], v[210:213], v[56:59]
	ds_read_b128 v[80:83], v0 offset:64
	s_waitcnt lgkmcnt(0)
	v_mfma_f32_16x16x32_bf16 v[64:67], v[76:79], v[80:83], v[64:67]
	ds_read_b128 v[80:83], v0 offset:4416
	s_waitcnt lgkmcnt(0)
	v_mfma_f32_16x16x32_bf16 v[60:63], v[76:79], v[80:83], v[60:63]
	ds_read_b128 v[80:83], v0 offset:8768
	s_waitcnt lgkmcnt(0)
	v_mfma_f32_16x16x32_bf16 v[52:55], v[76:79], v[80:83], v[52:55]
	ds_read_b128 v[80:83], v0 offset:13120
	s_waitcnt lgkmcnt(0)
	v_mfma_f32_16x16x32_bf16 v[48:51], v[76:79], v[80:83], v[48:51]
	ds_read_b128 v[80:83], v0 offset:17472
	s_waitcnt lgkmcnt(0)
	v_mfma_f32_16x16x32_bf16 v[44:47], v[76:79], v[80:83], v[44:47]
	ds_read_b128 v[80:83], v205 offset:64
	s_waitcnt lgkmcnt(0)
	v_mfma_f32_16x16x32_bf16 v[40:43], v[76:79], v[80:83], v[40:43]
	ds_read_b128 v[80:83], v205 offset:4416
	s_waitcnt lgkmcnt(0)
	v_mfma_f32_16x16x32_bf16 v[36:39], v[76:79], v[80:83], v[36:39]
	ds_read_b128 v[80:83], v205 offset:8768
	s_waitcnt lgkmcnt(0)
	v_mfma_f32_16x16x32_bf16 v[24:27], v[76:79], v[80:83], v[24:27]
	ds_read_b128 v[80:83], v205 offset:13120
	s_waitcnt lgkmcnt(0)
	v_mfma_f32_16x16x32_bf16 v[20:23], v[76:79], v[80:83], v[20:23]
	ds_read_b128 v[80:83], v205 offset:17472
	s_waitcnt lgkmcnt(0)
	v_mfma_f32_16x16x32_bf16 v[16:19], v[76:79], v[80:83], v[16:19]
	ds_read_b128 v[80:83], v205 offset:21824
	s_waitcnt lgkmcnt(0)
	v_mfma_f32_16x16x32_bf16 v[12:15], v[76:79], v[80:83], v[12:15]
	ds_read_b128 v[80:83], v205 offset:26176
	s_waitcnt lgkmcnt(0)
	v_mfma_f32_16x16x32_bf16 v[6:9], v[76:79], v[80:83], v[8:11]
	ds_read_b128 v[80:83], v205 offset:30528
	s_waitcnt lgkmcnt(0)
	v_mfma_f32_16x16x32_bf16 v[2:5], v[76:79], v[80:83], v[2:5]
	ds_read_b128 v[80:83], v205 offset:34880
	s_waitcnt lgkmcnt(0)
; #define LAS __attribute__((address_space(3)))
;     ...
;             for (int ks = 0; ks < 4; ++ks)
; #pragma unroll
;                 for (int nt = 0; nt < 16; ++nt) { const bf16x8 bf = *(const LAS bf16x8*)(vT + (16 * nt + fr) * GP + 32 * ks + 8 * fq); acc[nt] = __builtin_amdgcn_mfma_f32_16x16x32_bf16(afr[ks], bf, acc[nt], 0, 0, 0); }
	v_mfma_f32_16x16x32_bf16 v[32:35], v[76:79], v[80:83], v[32:35]
	ds_read_b128 v[80:83], v205 offset:39232
	s_waitcnt lgkmcnt(0)
	v_mfma_f32_16x16x32_bf16 v[28:31], v[76:79], v[80:83], v[28:31]
	ds_read_b128 v[80:83], v205 offset:43584
	s_waitcnt lgkmcnt(0)
	v_mfma_f32_16x16x32_bf16 v[56:59], v[76:79], v[80:83], v[56:59]
	ds_read_b128 v[76:79], v0 offset:128
	s_waitcnt lgkmcnt(0)
	v_mfma_f32_16x16x32_bf16 v[64:67], v[72:75], v[76:79], v[64:67]
	ds_read_b128 v[76:79], v0 offset:4480
	s_waitcnt lgkmcnt(0)
	v_mfma_f32_16x16x32_bf16 v[60:63], v[72:75], v[76:79], v[60:63]
	ds_read_b128 v[76:79], v0 offset:8832
	s_waitcnt lgkmcnt(0)
	v_mfma_f32_16x16x32_bf16 v[52:55], v[72:75], v[76:79], v[52:55]
	ds_read_b128 v[76:79], v0 offset:13184
	s_waitcnt lgkmcnt(0)
	v_mfma_f32_16x16x32_bf16 v[48:51], v[72:75], v[76:79], v[48:51]
	ds_read_b128 v[76:79], v0 offset:17536
	s_waitcnt lgkmcnt(0)
	v_mfma_f32_16x16x32_bf16 v[44:47], v[72:75], v[76:79], v[44:47]
	ds_read_b128 v[76:79], v205 offset:128
	s_waitcnt lgkmcnt(0)
	v_mfma_f32_16x16x32_bf16 v[40:43], v[72:75], v[76:79], v[40:43]
	ds_read_b128 v[76:79], v205 offset:4480
	s_waitcnt lgkmcnt(0)
	v_mfma_f32_16x16x32_bf16 v[36:39], v[72:75], v[76:79], v[36:39]
	ds_read_b128 v[76:79], v205 offset:8832
	s_waitcnt lgkmcnt(0)
	v_mfma_f32_16x16x32_bf16 v[24:27], v[72:75], v[76:79], v[24:27]
	ds_read_b128 v[76:79], v205 offset:13184
	s_waitcnt lgkmcnt(0)
	v_mfma_f32_16x16x32_bf16 v[20:23], v[72:75], v[76:79], v[20:23]
	ds_read_b128 v[76:79], v205 offset:17536
	s_waitcnt lgkmcnt(0)
	v_mfma_f32_16x16x32_bf16 v[16:19], v[72:75], v[76:79], v[16:19]
	ds_read_b128 v[76:79], v205 offset:21888
	s_waitcnt lgkmcnt(0)
	v_mfma_f32_16x16x32_bf16 v[10:13], v[72:75], v[76:79], v[12:15]
	ds_read_b128 v[76:79], v205 offset:26240
	s_waitcnt lgkmcnt(0)
	v_mfma_f32_16x16x32_bf16 v[6:9], v[72:75], v[76:79], v[6:9]
	ds_read_b128 v[76:79], v205 offset:30592
	s_waitcnt lgkmcnt(0)
	v_mfma_f32_16x16x32_bf16 v[2:5], v[72:75], v[76:79], v[2:5]
	ds_read_b128 v[76:79], v205 offset:34944
	s_waitcnt lgkmcnt(0)
	v_mfma_f32_16x16x32_bf16 v[32:35], v[72:75], v[76:79], v[32:35]
	ds_read_b128 v[76:79], v205 offset:39296
	s_waitcnt lgkmcnt(0)
	v_mfma_f32_16x16x32_bf16 v[28:31], v[72:75], v[76:79], v[28:31]
	ds_read_b128 v[76:79], v205 offset:43648
	s_waitcnt lgkmcnt(0)
	v_mfma_f32_16x16x32_bf16 v[56:59], v[72:75], v[76:79], v[56:59]
	ds_read_b128 v[72:75], v0 offset:192
	s_waitcnt lgkmcnt(0)
	v_mfma_f32_16x16x32_bf16 v[64:67], v[68:71], v[72:75], v[64:67]
	ds_read_b128 v[72:75], v0 offset:4544
	s_waitcnt lgkmcnt(0)
	v_mfma_f32_16x16x32_bf16 v[60:63], v[68:71], v[72:75], v[60:63]
	ds_read_b128 v[72:75], v0 offset:8896
	s_waitcnt lgkmcnt(0)
	v_mfma_f32_16x16x32_bf16 v[52:55], v[68:71], v[72:75], v[52:55]
	ds_read_b128 v[72:75], v0 offset:13248
	s_waitcnt lgkmcnt(0)
	v_mfma_f32_16x16x32_bf16 v[48:51], v[68:71], v[72:75], v[48:51]
	ds_read_b128 v[72:75], v0 offset:17600
	s_waitcnt lgkmcnt(0)
	v_mfma_f32_16x16x32_bf16 v[44:47], v[68:71], v[72:75], v[44:47]
	ds_read_b128 v[72:75], v205 offset:192
	s_waitcnt lgkmcnt(0)
	v_mfma_f32_16x16x32_bf16 v[40:43], v[68:71], v[72:75], v[40:43]
	ds_read_b128 v[72:75], v205 offset:4544
	s_waitcnt lgkmcnt(0)
	v_mfma_f32_16x16x32_bf16 v[36:39], v[68:71], v[72:75], v[36:39]
	ds_read_b128 v[72:75], v205 offset:8896
	s_waitcnt lgkmcnt(0)
	v_mfma_f32_16x16x32_bf16 v[24:27], v[68:71], v[72:75], v[24:27]
	ds_read_b128 v[72:75], v205 offset:13248
	s_waitcnt lgkmcnt(0)
	v_mfma_f32_16x16x32_bf16 v[20:23], v[68:71], v[72:75], v[20:23]
	ds_read_b128 v[72:75], v205 offset:17600
	s_waitcnt lgkmcnt(0)
	v_mfma_f32_16x16x32_bf16 v[16:19], v[68:71], v[72:75], v[16:19]
	ds_read_b128 v[72:75], v205 offset:21952
	s_waitcnt lgkmcnt(0)
	v_mfma_f32_16x16x32_bf16 v[12:15], v[68:71], v[72:75], v[10:13]
	ds_read_b128 v[72:75], v205 offset:26304
	s_waitcnt lgkmcnt(0)
	v_mfma_f32_16x16x32_bf16 v[8:11], v[68:71], v[72:75], v[6:9]
	ds_read_b128 v[72:75], v205 offset:30656
	s_waitcnt lgkmcnt(0)
	v_mfma_f32_16x16x32_bf16 v[4:7], v[68:71], v[72:75], v[2:5]
	ds_read_b128 v[72:75], v205 offset:35008
	s_waitcnt lgkmcnt(0)
	v_mfma_f32_16x16x32_bf16 v[32:35], v[68:71], v[72:75], v[32:35]
	ds_read_b128 v[72:75], v205 offset:39360
	s_waitcnt lgkmcnt(0)
	v_mfma_f32_16x16x32_bf16 v[28:31], v[68:71], v[72:75], v[28:31]
	ds_read_b128 v[72:75], v205 offset:43712
	s_waitcnt lgkmcnt(0)
	v_mfma_f32_16x16x32_bf16 v[56:59], v[68:71], v[72:75], v[56:59]
	s_branch .LBB0_477
